# plus: fused residual+norm GEMM epilogues (4 phases) steps 1 and 5 hand-written with batched loads; modulation vectors loaded once per unit
# speedup vs baseline: 1.0605x; 1.0157x over previous
.LBB0_1860:
	s_lshl_b32 s14, s8, 8
	s_load_dwordx2 s[36:37], s[78:79], 0x0
	s_load_dwordx2 s[38:39], s[78:79], 0x1d0
	s_load_dwordx2 s[40:41], s[78:79], 0x1f8
	v_and_b32_e32 v130, 15, v248
	v_bfe_u32 v131, v248, 8, 1
	v_bfe_u32 v132, v248, 6, 2
	v_bfe_u32 v133, v248, 4, 2
	v_lshl_add_u32 v134, v131, 6, v130
	v_lshlrev_b32_e32 v135, 5, v132
	v_lshl_or_b32 v135, v133, 2, v135
	s_lshl_b32 s0, s12, 8
	v_add_u32_e32 v135, s0, v135
	s_lshl_b32 s0, s8, 8
	v_add_u32_e32 v136, s0, v134
	v_mul_u32_u24_e32 v137, 0x1000, v136
	v_lshl_add_u32 v137, v135, 2, v137
	v_lshlrev_b32_e32 v138, 11, v136
	v_lshl_add_u32 v138, v135, 1, v138
	v_lshlrev_b32_e32 v139, 2, v134
	v_add_lshl_u32 v139, v139, v132, 2
	v_xor_b32_e32 v213, 16, v227
	v_lshlrev_b32_e32 v213, 2, v213
	v_xor_b32_e32 v214, 32, v227
	v_lshlrev_b32_e32 v214, 2, v214
	v_lshlrev_b32_e32 v215, 2, v135
	s_lshr_b32 s0, s8, 3
	s_mul_i32 s0, s0, 0xe000
	s_add_u32 s0, s0, 0x2000
	v_add_u32_e32 v215, s0, v215
	s_waitcnt lgkmcnt(0)
	global_load_dwordx4 v[140:143], v215, s[38:39] offset:0
	global_load_dwordx4 v[144:147], v215, s[38:39] offset:64
	global_load_dwordx4 v[148:151], v215, s[38:39] offset:512
	global_load_dwordx4 v[152:155], v215, s[38:39] offset:576
	v_add_u32_e32 v218, 0x0, v137
	global_load_dwordx4 v[156:159], v218, s[36:37]
	v_add_u32_e32 v219, 0x40, v137
	global_load_dwordx4 v[160:163], v219, s[36:37]
	v_add_u32_e32 v220, 0x200, v137
	global_load_dwordx4 v[164:167], v220, s[36:37]
	v_add_u32_e32 v221, 0x240, v137
	global_load_dwordx4 v[168:171], v221, s[36:37]
	v_add_u32_e32 v218, 0x10000, v137
	global_load_dwordx4 v[172:175], v218, s[36:37]
	v_add_u32_e32 v219, 0x10040, v137
	global_load_dwordx4 v[182:185], v219, s[36:37]
	v_add_u32_e32 v220, 0x10200, v137
	global_load_dwordx4 v[186:189], v220, s[36:37]
	v_add_u32_e32 v221, 0x10240, v137
	global_load_dwordx4 v[190:193], v221, s[36:37]
	v_add_u32_e32 v218, 0x20000, v137
	global_load_dwordx4 v[194:197], v218, s[36:37]
	v_add_u32_e32 v219, 0x20040, v137
	global_load_dwordx4 v[198:201], v219, s[36:37]
	v_add_u32_e32 v220, 0x20200, v137
	global_load_dwordx4 v[202:205], v220, s[36:37]
	v_add_u32_e32 v221, 0x20240, v137
	global_load_dwordx4 v[206:209], v221, s[36:37]
	s_waitcnt vmcnt(12)
	s_waitcnt vmcnt(8)
	v_pk_fma_f32 v[126:127], v[126:127], v[140:141], v[156:157]
	v_pk_fma_f32 v[128:129], v[128:129], v[142:143], v[158:159]
	v_pk_fma_f32 v[122:123], v[122:123], v[144:145], v[160:161]
	v_pk_fma_f32 v[124:125], v[124:125], v[146:147], v[162:163]
	v_pk_fma_f32 v[118:119], v[118:119], v[148:149], v[164:165]
	v_pk_fma_f32 v[120:121], v[120:121], v[150:151], v[166:167]
	v_pk_fma_f32 v[114:115], v[114:115], v[152:153], v[168:169]
	v_pk_fma_f32 v[116:117], v[116:117], v[154:155], v[170:171]
	v_cvt_pk_bf16_f32 v156, v126, v127
	v_cvt_pk_bf16_f32 v157, v128, v129
	v_mul_f32_e32 v158, v127, v127
	v_mul_f32_e32 v159, v129, v129
	v_fmac_f32_e32 v158, v126, v126
	v_fmac_f32_e32 v159, v128, v128
	v_add_f32_e32 v158, v158, v159
	v_add_f32_e32 v222, 0, v158
	v_add_u32_e32 v218, 0x0, v138
	global_store_dwordx2 v218, v[156:157], s[40:41]
	v_cvt_pk_bf16_f32 v160, v122, v123
	v_cvt_pk_bf16_f32 v161, v124, v125
	v_mul_f32_e32 v162, v123, v123
	v_mul_f32_e32 v163, v125, v125
	v_fmac_f32_e32 v162, v122, v122
	v_fmac_f32_e32 v163, v124, v124
	v_add_f32_e32 v162, v162, v163
	v_add_f32_e32 v222, v222, v162
	v_add_u32_e32 v219, 0x20, v138
	global_store_dwordx2 v219, v[160:161], s[40:41]
	v_cvt_pk_bf16_f32 v164, v118, v119
	v_cvt_pk_bf16_f32 v165, v120, v121
	v_mul_f32_e32 v166, v119, v119
	v_mul_f32_e32 v167, v121, v121
	v_fmac_f32_e32 v166, v118, v118
	v_fmac_f32_e32 v167, v120, v120
	v_add_f32_e32 v166, v166, v167
	v_add_f32_e32 v222, v222, v166
	v_add_u32_e32 v220, 0x100, v138
	global_store_dwordx2 v220, v[164:165], s[40:41]
	v_cvt_pk_bf16_f32 v168, v114, v115
	v_cvt_pk_bf16_f32 v169, v116, v117
	v_mul_f32_e32 v170, v115, v115
	v_mul_f32_e32 v171, v117, v117
	v_fmac_f32_e32 v170, v114, v114
	v_fmac_f32_e32 v171, v116, v116
	v_add_f32_e32 v170, v170, v171
	v_add_f32_e32 v222, v222, v170
	v_add_u32_e32 v221, 0x120, v138
	global_store_dwordx2 v221, v[168:169], s[40:41]
	v_add_u32_e32 v218, 0x30000, v137
	global_load_dwordx4 v[156:159], v218, s[36:37]
	v_add_u32_e32 v219, 0x30040, v137
	global_load_dwordx4 v[160:163], v219, s[36:37]
	v_add_u32_e32 v220, 0x30200, v137
	global_load_dwordx4 v[164:167], v220, s[36:37]
	v_add_u32_e32 v221, 0x30240, v137
	global_load_dwordx4 v[168:171], v221, s[36:37]
	s_waitcnt vmcnt(12)
	v_pk_fma_f32 v[110:111], v[110:111], v[140:141], v[172:173]
	v_pk_fma_f32 v[112:113], v[112:113], v[142:143], v[174:175]
	v_pk_fma_f32 v[106:107], v[106:107], v[144:145], v[182:183]
	v_pk_fma_f32 v[108:109], v[108:109], v[146:147], v[184:185]
	v_pk_fma_f32 v[102:103], v[102:103], v[148:149], v[186:187]
	v_pk_fma_f32 v[104:105], v[104:105], v[150:151], v[188:189]
	v_pk_fma_f32 v[98:99], v[98:99], v[152:153], v[190:191]
	v_pk_fma_f32 v[100:101], v[100:101], v[154:155], v[192:193]
	v_cvt_pk_bf16_f32 v172, v110, v111
	v_cvt_pk_bf16_f32 v173, v112, v113
	v_mul_f32_e32 v174, v111, v111
	v_mul_f32_e32 v175, v113, v113
	v_fmac_f32_e32 v174, v110, v110
	v_fmac_f32_e32 v175, v112, v112
	v_add_f32_e32 v174, v174, v175
	v_add_f32_e32 v223, 0, v174
	v_add_u32_e32 v218, 0x8000, v138
	global_store_dwordx2 v218, v[172:173], s[40:41]
	v_cvt_pk_bf16_f32 v182, v106, v107
	v_cvt_pk_bf16_f32 v183, v108, v109
	v_mul_f32_e32 v184, v107, v107
	v_mul_f32_e32 v185, v109, v109
	v_fmac_f32_e32 v184, v106, v106
	v_fmac_f32_e32 v185, v108, v108
	v_add_f32_e32 v184, v184, v185
	v_add_f32_e32 v223, v223, v184
	v_add_u32_e32 v219, 0x8020, v138
	global_store_dwordx2 v219, v[182:183], s[40:41]
	v_cvt_pk_bf16_f32 v186, v102, v103
	v_cvt_pk_bf16_f32 v187, v104, v105
	v_mul_f32_e32 v188, v103, v103
	v_mul_f32_e32 v189, v105, v105
	v_fmac_f32_e32 v188, v102, v102
	v_fmac_f32_e32 v189, v104, v104
	v_add_f32_e32 v188, v188, v189
	v_add_f32_e32 v223, v223, v188
	v_add_u32_e32 v220, 0x8100, v138
	global_store_dwordx2 v220, v[186:187], s[40:41]
	v_cvt_pk_bf16_f32 v190, v98, v99
	v_cvt_pk_bf16_f32 v191, v100, v101
	v_mul_f32_e32 v192, v99, v99
	v_mul_f32_e32 v193, v101, v101
	v_fmac_f32_e32 v192, v98, v98
	v_fmac_f32_e32 v193, v100, v100
	v_add_f32_e32 v192, v192, v193
	v_add_f32_e32 v223, v223, v192
	v_add_u32_e32 v221, 0x8120, v138
	global_store_dwordx2 v221, v[190:191], s[40:41]
	v_add_u32_e32 v218, 0x80000, v137
	global_load_dwordx4 v[172:175], v218, s[36:37]
	v_add_u32_e32 v219, 0x80040, v137
	global_load_dwordx4 v[182:185], v219, s[36:37]
	v_add_u32_e32 v220, 0x80200, v137
	global_load_dwordx4 v[186:189], v220, s[36:37]
	v_add_u32_e32 v221, 0x80240, v137
	global_load_dwordx4 v[190:193], v221, s[36:37]
	s_waitcnt vmcnt(16)
	v_pk_fma_f32 v[94:95], v[94:95], v[140:141], v[194:195]
	v_pk_fma_f32 v[96:97], v[96:97], v[142:143], v[196:197]
	v_pk_fma_f32 v[90:91], v[90:91], v[144:145], v[198:199]
	v_pk_fma_f32 v[92:93], v[92:93], v[146:147], v[200:201]
	v_pk_fma_f32 v[86:87], v[86:87], v[148:149], v[202:203]
	v_pk_fma_f32 v[88:89], v[88:89], v[150:151], v[204:205]
	v_pk_fma_f32 v[82:83], v[82:83], v[152:153], v[206:207]
	v_pk_fma_f32 v[84:85], v[84:85], v[154:155], v[208:209]
	v_cvt_pk_bf16_f32 v194, v94, v95
	v_cvt_pk_bf16_f32 v195, v96, v97
	v_mul_f32_e32 v196, v95, v95
	v_mul_f32_e32 v197, v97, v97
	v_fmac_f32_e32 v196, v94, v94
	v_fmac_f32_e32 v197, v96, v96
	v_add_f32_e32 v196, v196, v197
	v_add_f32_e32 v224, 0, v196
	v_add_u32_e32 v218, 0x10000, v138
	global_store_dwordx2 v218, v[194:195], s[40:41]
	v_cvt_pk_bf16_f32 v198, v90, v91
	v_cvt_pk_bf16_f32 v199, v92, v93
	v_mul_f32_e32 v200, v91, v91
	v_mul_f32_e32 v201, v93, v93
	v_fmac_f32_e32 v200, v90, v90
	v_fmac_f32_e32 v201, v92, v92
	v_add_f32_e32 v200, v200, v201
	v_add_f32_e32 v224, v224, v200
	v_add_u32_e32 v219, 0x10020, v138
	global_store_dwordx2 v219, v[198:199], s[40:41]
	v_cvt_pk_bf16_f32 v202, v86, v87
	v_cvt_pk_bf16_f32 v203, v88, v89
	v_mul_f32_e32 v204, v87, v87
	v_mul_f32_e32 v205, v89, v89
	v_fmac_f32_e32 v204, v86, v86
	v_fmac_f32_e32 v205, v88, v88
	v_add_f32_e32 v204, v204, v205
	v_add_f32_e32 v224, v224, v204
	v_add_u32_e32 v220, 0x10100, v138
	global_store_dwordx2 v220, v[202:203], s[40:41]
	v_cvt_pk_bf16_f32 v206, v82, v83
	v_cvt_pk_bf16_f32 v207, v84, v85
	v_mul_f32_e32 v208, v83, v83
	v_mul_f32_e32 v209, v85, v85
	v_fmac_f32_e32 v208, v82, v82
	v_fmac_f32_e32 v209, v84, v84
	v_add_f32_e32 v208, v208, v209
	v_add_f32_e32 v224, v224, v208
	v_add_u32_e32 v221, 0x10120, v138
	global_store_dwordx2 v221, v[206:207], s[40:41]
	v_add_u32_e32 v218, 0x90000, v137
	global_load_dwordx4 v[194:197], v218, s[36:37]
	v_add_u32_e32 v219, 0x90040, v137
	global_load_dwordx4 v[198:201], v219, s[36:37]
	v_add_u32_e32 v220, 0x90200, v137
	global_load_dwordx4 v[202:205], v220, s[36:37]
	v_add_u32_e32 v221, 0x90240, v137
	global_load_dwordx4 v[206:209], v221, s[36:37]
	s_waitcnt vmcnt(16)
	v_pk_fma_f32 v[78:79], v[78:79], v[140:141], v[156:157]
	v_pk_fma_f32 v[80:81], v[80:81], v[142:143], v[158:159]
	v_pk_fma_f32 v[74:75], v[74:75], v[144:145], v[160:161]
	v_pk_fma_f32 v[76:77], v[76:77], v[146:147], v[162:163]
	v_pk_fma_f32 v[70:71], v[70:71], v[148:149], v[164:165]
	v_pk_fma_f32 v[72:73], v[72:73], v[150:151], v[166:167]
	v_pk_fma_f32 v[66:67], v[66:67], v[152:153], v[168:169]
	v_pk_fma_f32 v[68:69], v[68:69], v[154:155], v[170:171]
	v_cvt_pk_bf16_f32 v156, v78, v79
	v_cvt_pk_bf16_f32 v157, v80, v81
	v_mul_f32_e32 v158, v79, v79
	v_mul_f32_e32 v159, v81, v81
	v_fmac_f32_e32 v158, v78, v78
	v_fmac_f32_e32 v159, v80, v80
	v_add_f32_e32 v158, v158, v159
	v_add_f32_e32 v225, 0, v158
	v_add_u32_e32 v218, 0x18000, v138
	global_store_dwordx2 v218, v[156:157], s[40:41]
	v_cvt_pk_bf16_f32 v160, v74, v75
	v_cvt_pk_bf16_f32 v161, v76, v77
	v_mul_f32_e32 v162, v75, v75
	v_mul_f32_e32 v163, v77, v77
	v_fmac_f32_e32 v162, v74, v74
	v_fmac_f32_e32 v163, v76, v76
	v_add_f32_e32 v162, v162, v163
	v_add_f32_e32 v225, v225, v162
	v_add_u32_e32 v219, 0x18020, v138
	global_store_dwordx2 v219, v[160:161], s[40:41]
	v_cvt_pk_bf16_f32 v164, v70, v71
	v_cvt_pk_bf16_f32 v165, v72, v73
	v_mul_f32_e32 v166, v71, v71
	v_mul_f32_e32 v167, v73, v73
	v_fmac_f32_e32 v166, v70, v70
	v_fmac_f32_e32 v167, v72, v72
	v_add_f32_e32 v166, v166, v167
	v_add_f32_e32 v225, v225, v166
	v_add_u32_e32 v220, 0x18100, v138
	global_store_dwordx2 v220, v[164:165], s[40:41]
	v_cvt_pk_bf16_f32 v168, v66, v67
	v_cvt_pk_bf16_f32 v169, v68, v69
	v_mul_f32_e32 v170, v67, v67
	v_mul_f32_e32 v171, v69, v69
	v_fmac_f32_e32 v170, v66, v66
	v_fmac_f32_e32 v171, v68, v68
	v_add_f32_e32 v170, v170, v171
	v_add_f32_e32 v225, v225, v170
	v_add_u32_e32 v221, 0x18120, v138
	global_store_dwordx2 v221, v[168:169], s[40:41]
	v_add_u32_e32 v218, 0xa0000, v137
	global_load_dwordx4 v[156:159], v218, s[36:37]
	v_add_u32_e32 v219, 0xa0040, v137
	global_load_dwordx4 v[160:163], v219, s[36:37]
	v_add_u32_e32 v220, 0xa0200, v137
	global_load_dwordx4 v[164:167], v220, s[36:37]
	v_add_u32_e32 v221, 0xa0240, v137
	global_load_dwordx4 v[168:171], v221, s[36:37]
	s_waitcnt vmcnt(16)
	v_pk_fma_f32 v[62:63], v[62:63], v[140:141], v[172:173]
	v_pk_fma_f32 v[64:65], v[64:65], v[142:143], v[174:175]
	v_pk_fma_f32 v[58:59], v[58:59], v[144:145], v[182:183]
	v_pk_fma_f32 v[60:61], v[60:61], v[146:147], v[184:185]
	v_pk_fma_f32 v[54:55], v[54:55], v[148:149], v[186:187]
	v_pk_fma_f32 v[56:57], v[56:57], v[150:151], v[188:189]
	v_pk_fma_f32 v[50:51], v[50:51], v[152:153], v[190:191]
	v_pk_fma_f32 v[52:53], v[52:53], v[154:155], v[192:193]
	v_cvt_pk_bf16_f32 v172, v62, v63
	v_cvt_pk_bf16_f32 v173, v64, v65
	v_mul_f32_e32 v174, v63, v63
	v_mul_f32_e32 v175, v65, v65
	v_fmac_f32_e32 v174, v62, v62
	v_fmac_f32_e32 v175, v64, v64
	v_add_f32_e32 v174, v174, v175
	v_add_f32_e32 v226, 0, v174
	v_add_u32_e32 v218, 0x40000, v138
	global_store_dwordx2 v218, v[172:173], s[40:41]
	v_cvt_pk_bf16_f32 v182, v58, v59
	v_cvt_pk_bf16_f32 v183, v60, v61
	v_mul_f32_e32 v184, v59, v59
	v_mul_f32_e32 v185, v61, v61
	v_fmac_f32_e32 v184, v58, v58
	v_fmac_f32_e32 v185, v60, v60
	v_add_f32_e32 v184, v184, v185
	v_add_f32_e32 v226, v226, v184
	v_add_u32_e32 v219, 0x40020, v138
	global_store_dwordx2 v219, v[182:183], s[40:41]
	v_cvt_pk_bf16_f32 v186, v54, v55
	v_cvt_pk_bf16_f32 v187, v56, v57
	v_mul_f32_e32 v188, v55, v55
	v_mul_f32_e32 v189, v57, v57
	v_fmac_f32_e32 v188, v54, v54
	v_fmac_f32_e32 v189, v56, v56
	v_add_f32_e32 v188, v188, v189
	v_add_f32_e32 v226, v226, v188
	v_add_u32_e32 v220, 0x40100, v138
	global_store_dwordx2 v220, v[186:187], s[40:41]
	v_cvt_pk_bf16_f32 v190, v50, v51
	v_cvt_pk_bf16_f32 v191, v52, v53
	v_mul_f32_e32 v192, v51, v51
	v_mul_f32_e32 v193, v53, v53
	v_fmac_f32_e32 v192, v50, v50
	v_fmac_f32_e32 v193, v52, v52
	v_add_f32_e32 v192, v192, v193
	v_add_f32_e32 v226, v226, v192
	v_add_u32_e32 v221, 0x40120, v138
	global_store_dwordx2 v221, v[190:191], s[40:41]
	v_add_u32_e32 v218, 0xb0000, v137
	global_load_dwordx4 v[172:175], v218, s[36:37]
	v_add_u32_e32 v219, 0xb0040, v137
	global_load_dwordx4 v[182:185], v219, s[36:37]
	v_add_u32_e32 v220, 0xb0200, v137
	global_load_dwordx4 v[186:189], v220, s[36:37]
	v_add_u32_e32 v221, 0xb0240, v137
	global_load_dwordx4 v[190:193], v221, s[36:37]
	s_waitcnt vmcnt(16)
	v_pk_fma_f32 v[46:47], v[46:47], v[140:141], v[194:195]
	v_pk_fma_f32 v[48:49], v[48:49], v[142:143], v[196:197]
	v_pk_fma_f32 v[42:43], v[42:43], v[144:145], v[198:199]
	v_pk_fma_f32 v[44:45], v[44:45], v[146:147], v[200:201]
	v_pk_fma_f32 v[38:39], v[38:39], v[148:149], v[202:203]
	v_pk_fma_f32 v[40:41], v[40:41], v[150:151], v[204:205]
	v_pk_fma_f32 v[34:35], v[34:35], v[152:153], v[206:207]
	v_pk_fma_f32 v[36:37], v[36:37], v[154:155], v[208:209]
	v_cvt_pk_bf16_f32 v194, v46, v47
	v_cvt_pk_bf16_f32 v195, v48, v49
	v_mul_f32_e32 v196, v47, v47
	v_mul_f32_e32 v197, v49, v49
	v_fmac_f32_e32 v196, v46, v46
	v_fmac_f32_e32 v197, v48, v48
	v_add_f32_e32 v196, v196, v197
	v_add_f32_e32 v216, 0, v196
	v_add_u32_e32 v218, 0x48000, v138
	global_store_dwordx2 v218, v[194:195], s[40:41]
	v_cvt_pk_bf16_f32 v198, v42, v43
	v_cvt_pk_bf16_f32 v199, v44, v45
	v_mul_f32_e32 v200, v43, v43
	v_mul_f32_e32 v201, v45, v45
	v_fmac_f32_e32 v200, v42, v42
	v_fmac_f32_e32 v201, v44, v44
	v_add_f32_e32 v200, v200, v201
	v_add_f32_e32 v216, v216, v200
	v_add_u32_e32 v219, 0x48020, v138
	global_store_dwordx2 v219, v[198:199], s[40:41]
	v_cvt_pk_bf16_f32 v202, v38, v39
	v_cvt_pk_bf16_f32 v203, v40, v41
	v_mul_f32_e32 v204, v39, v39
	v_mul_f32_e32 v205, v41, v41
	v_fmac_f32_e32 v204, v38, v38
	v_fmac_f32_e32 v205, v40, v40
	v_add_f32_e32 v204, v204, v205
	v_add_f32_e32 v216, v216, v204
	v_add_u32_e32 v220, 0x48100, v138
	global_store_dwordx2 v220, v[202:203], s[40:41]
	v_cvt_pk_bf16_f32 v206, v34, v35
	v_cvt_pk_bf16_f32 v207, v36, v37
	v_mul_f32_e32 v208, v35, v35
	v_mul_f32_e32 v209, v37, v37
	v_fmac_f32_e32 v208, v34, v34
	v_fmac_f32_e32 v209, v36, v36
	v_add_f32_e32 v208, v208, v209
	v_add_f32_e32 v216, v216, v208
	v_add_u32_e32 v221, 0x48120, v138
	global_store_dwordx2 v221, v[206:207], s[40:41]
	s_waitcnt vmcnt(12)
	v_pk_fma_f32 v[30:31], v[30:31], v[140:141], v[156:157]
	v_pk_fma_f32 v[32:33], v[32:33], v[142:143], v[158:159]
	v_pk_fma_f32 v[26:27], v[26:27], v[144:145], v[160:161]
	v_pk_fma_f32 v[28:29], v[28:29], v[146:147], v[162:163]
	v_pk_fma_f32 v[22:23], v[22:23], v[148:149], v[164:165]
	v_pk_fma_f32 v[24:25], v[24:25], v[150:151], v[166:167]
	v_pk_fma_f32 v[18:19], v[18:19], v[152:153], v[168:169]
	v_pk_fma_f32 v[20:21], v[20:21], v[154:155], v[170:171]
	v_cvt_pk_bf16_f32 v156, v30, v31
	v_cvt_pk_bf16_f32 v157, v32, v33
	v_mul_f32_e32 v158, v31, v31
	v_mul_f32_e32 v159, v33, v33
	v_fmac_f32_e32 v158, v30, v30
	v_fmac_f32_e32 v159, v32, v32
	v_add_f32_e32 v158, v158, v159
	v_add_f32_e32 v217, 0, v158
	v_add_u32_e32 v218, 0x50000, v138
	global_store_dwordx2 v218, v[156:157], s[40:41]
	v_cvt_pk_bf16_f32 v160, v26, v27
	v_cvt_pk_bf16_f32 v161, v28, v29
	v_mul_f32_e32 v162, v27, v27
	v_mul_f32_e32 v163, v29, v29
	v_fmac_f32_e32 v162, v26, v26
	v_fmac_f32_e32 v163, v28, v28
	v_add_f32_e32 v162, v162, v163
	v_add_f32_e32 v217, v217, v162
	v_add_u32_e32 v219, 0x50020, v138
	global_store_dwordx2 v219, v[160:161], s[40:41]
	v_cvt_pk_bf16_f32 v164, v22, v23
	v_cvt_pk_bf16_f32 v165, v24, v25
	v_mul_f32_e32 v166, v23, v23
	v_mul_f32_e32 v167, v25, v25
	v_fmac_f32_e32 v166, v22, v22
	v_fmac_f32_e32 v167, v24, v24
	v_add_f32_e32 v166, v166, v167
	v_add_f32_e32 v217, v217, v166
	v_add_u32_e32 v220, 0x50100, v138
	global_store_dwordx2 v220, v[164:165], s[40:41]
	v_cvt_pk_bf16_f32 v168, v18, v19
	v_cvt_pk_bf16_f32 v169, v20, v21
	v_mul_f32_e32 v170, v19, v19
	v_mul_f32_e32 v171, v21, v21
	v_fmac_f32_e32 v170, v18, v18
	v_fmac_f32_e32 v171, v20, v20
	v_add_f32_e32 v170, v170, v171
	v_add_f32_e32 v217, v217, v170
	v_add_u32_e32 v221, 0x50120, v138
	global_store_dwordx2 v221, v[168:169], s[40:41]
	s_waitcnt vmcnt(8)
	v_pk_fma_f32 v[14:15], v[14:15], v[140:141], v[172:173]
	v_pk_fma_f32 v[16:17], v[16:17], v[142:143], v[174:175]
	v_pk_fma_f32 v[10:11], v[10:11], v[144:145], v[182:183]
	v_pk_fma_f32 v[12:13], v[12:13], v[146:147], v[184:185]
	v_pk_fma_f32 v[6:7], v[6:7], v[148:149], v[186:187]
	v_pk_fma_f32 v[8:9], v[8:9], v[150:151], v[188:189]
	v_pk_fma_f32 v[2:3], v[2:3], v[152:153], v[190:191]
	v_pk_fma_f32 v[4:5], v[4:5], v[154:155], v[192:193]
	v_cvt_pk_bf16_f32 v172, v14, v15
	v_cvt_pk_bf16_f32 v173, v16, v17
	v_mul_f32_e32 v174, v15, v15
	v_mul_f32_e32 v175, v17, v17
	v_fmac_f32_e32 v174, v14, v14
	v_fmac_f32_e32 v175, v16, v16
	v_add_f32_e32 v174, v174, v175
	v_add_f32_e32 v212, 0, v174
	v_add_u32_e32 v218, 0x58000, v138
	global_store_dwordx2 v218, v[172:173], s[40:41]
	v_cvt_pk_bf16_f32 v182, v10, v11
	v_cvt_pk_bf16_f32 v183, v12, v13
	v_mul_f32_e32 v184, v11, v11
	v_mul_f32_e32 v185, v13, v13
	v_fmac_f32_e32 v184, v10, v10
	v_fmac_f32_e32 v185, v12, v12
	v_add_f32_e32 v184, v184, v185
	v_add_f32_e32 v212, v212, v184
	v_add_u32_e32 v219, 0x58020, v138
	global_store_dwordx2 v219, v[182:183], s[40:41]
	v_cvt_pk_bf16_f32 v186, v6, v7
	v_cvt_pk_bf16_f32 v187, v8, v9
	v_mul_f32_e32 v188, v7, v7
	v_mul_f32_e32 v189, v9, v9
	v_fmac_f32_e32 v188, v6, v6
	v_fmac_f32_e32 v189, v8, v8
	v_add_f32_e32 v188, v188, v189
	v_add_f32_e32 v212, v212, v188
	v_add_u32_e32 v220, 0x58100, v138
	global_store_dwordx2 v220, v[186:187], s[40:41]
	v_cvt_pk_bf16_f32 v190, v2, v3
	v_cvt_pk_bf16_f32 v191, v4, v5
	v_mul_f32_e32 v192, v3, v3
	v_mul_f32_e32 v193, v5, v5
	v_fmac_f32_e32 v192, v2, v2
	v_fmac_f32_e32 v193, v4, v4
	v_add_f32_e32 v192, v192, v193
	v_add_f32_e32 v212, v212, v192
	v_add_u32_e32 v221, 0x58120, v138
	global_store_dwordx2 v221, v[190:191], s[40:41]
	ds_bpermute_b32 v156, v213, v222
	ds_bpermute_b32 v157, v213, v223
	ds_bpermute_b32 v158, v213, v224
	ds_bpermute_b32 v159, v213, v225
	ds_bpermute_b32 v160, v213, v226
	ds_bpermute_b32 v161, v213, v216
	ds_bpermute_b32 v162, v213, v217
	ds_bpermute_b32 v163, v213, v212
	s_waitcnt lgkmcnt(0)
	v_add_f32_e32 v222, v222, v156
	v_add_f32_e32 v223, v223, v157
	v_add_f32_e32 v224, v224, v158
	v_add_f32_e32 v225, v225, v159
	v_add_f32_e32 v226, v226, v160
	v_add_f32_e32 v216, v216, v161
	v_add_f32_e32 v217, v217, v162
	v_add_f32_e32 v212, v212, v163
	ds_bpermute_b32 v156, v214, v222
	ds_bpermute_b32 v157, v214, v223
	ds_bpermute_b32 v158, v214, v224
	ds_bpermute_b32 v159, v214, v225
	ds_bpermute_b32 v160, v214, v226
	ds_bpermute_b32 v161, v214, v216
	ds_bpermute_b32 v162, v214, v217
	ds_bpermute_b32 v163, v214, v212
	s_waitcnt lgkmcnt(0)
	v_add_f32_e32 v222, v222, v156
	v_add_f32_e32 v223, v223, v157
	v_add_f32_e32 v224, v224, v158
	v_add_f32_e32 v225, v225, v159
	v_add_f32_e32 v226, v226, v160
	v_add_f32_e32 v216, v216, v161
	v_add_f32_e32 v217, v217, v162
	v_add_f32_e32 v212, v212, v163
	v_cmp_gt_u32_e32 vcc, 16, v227
	s_nop 3
	s_and_saveexec_b64 s[0:1], vcc
	ds_write_b32 v139, v222 offset:0
	ds_write_b32 v139, v223 offset:256
	ds_write_b32 v139, v224 offset:512
	ds_write_b32 v139, v225 offset:768
	ds_write_b32 v139, v226 offset:2048
	ds_write_b32 v139, v216 offset:2304
	ds_write_b32 v139, v217 offset:2560
	ds_write_b32 v139, v212 offset:2816
	s_or_b64 exec, exec, s[0:1]
	s_load_dwordx2 s[36:37], s[78:79], 0x60
	s_load_dwordx2 s[38:39], s[78:79], 0x1d0
	v_lshlrev_b32_e32 v137, 2, v135
	s_lshr_b32 s0, s8, 3
	s_mul_i32 s0, s0, 0xe000
	v_add_u32_e32 v138, s0, v137
	s_waitcnt lgkmcnt(0)
	v_add_u32_e32 v216, 0x0, v137
	global_load_dwordx4 v[156:159], v216, s[36:37] offset:0
	global_load_dwordx4 v[160:163], v216, s[36:37] offset:64
	global_load_dwordx4 v[164:167], v216, s[36:37] offset:512
	global_load_dwordx4 v[168:171], v216, s[36:37] offset:576
	v_add_u32_e32 v217, 0x3000, v138
	global_load_dwordx4 v[172:175], v217, s[38:39] offset:0
	global_load_dwordx4 v[182:185], v217, s[38:39] offset:64
	global_load_dwordx4 v[186:189], v217, s[38:39] offset:512
	global_load_dwordx4 v[190:193], v217, s[38:39] offset:576
	v_add_u32_e32 v218, 0x4000, v138
	global_load_dwordx4 v[194:197], v218, s[38:39] offset:0
	global_load_dwordx4 v[198:201], v218, s[38:39] offset:64
	global_load_dwordx4 v[202:205], v218, s[38:39] offset:512
	global_load_dwordx4 v[206:209], v218, s[38:39] offset:576
	v_mov_b32_e32 v223, v134
	v_mov_b32_e32 v224, v135
	v_mov_b32_e32 v225, v136
	v_and_b32_e32 v140, 31, v248
	s_waitcnt vmcnt(0) lgkmcnt(0)
	s_barrier
	v_lshl_or_b32 v144, s13, 5, v140
	v_add_u32_e32 v140, s14, v144
	v_cmp_gt_u32_e64 s[0:1], 32, v227
	s_waitcnt lgkmcnt(0)
	v_ashrrev_i32_e32 v141, 31, v140
	s_and_saveexec_b64 s[2:3], s[0:1]
	s_cbranch_execz .LBB0_1910
	v_lshl_add_u32 v142, v144, 4, 0
	ds_read_b128 v[148:151], v142
	s_load_dwordx16 s[36:51], s[78:79], 0x140
	s_ashr_i32 s13, s12, 31
	s_waitcnt lgkmcnt(0)
	v_mov_b32_e32 v152, v149
	v_mov_b32_e32 v153, v150
	v_mov_b32_e32 v149, v151
	v_lshl_add_u64 v[142:143], v[140:141], 4, s[46:47]
	v_pk_add_f32 v[148:149], v[152:153], v[148:149]
	v_lshl_add_u64 v[142:143], s[12:13], 2, v[142:143]
	v_pk_add_f32 v[148:149], v[148:149], v[148:149] op_sel:[0,1] op_sel_hi:[1,0]
	global_store_dword v[142:143], v148, off sc1

.LBB0_1927:
	s_or_b64 exec, exec, s[2:3]
	s_waitcnt vmcnt(0) lgkmcnt(0)
	s_barrier
	v_lshlrev_b32_e32 v226, 2, v223
	ds_read_b32 v210, v226 offset:4096
	ds_read_b32 v211, v226 offset:4160
	ds_read_b32 v212, v226 offset:4224
	ds_read_b32 v213, v226 offset:4288
	ds_read_b32 v214, v226 offset:4608
	ds_read_b32 v215, v226 offset:4672
	ds_read_b32 v216, v226 offset:4736
	ds_read_b32 v217, v226 offset:4800
	s_load_dwordx2 s[36:37], s[78:79], 0x210
	v_lshlrev_b32_e32 v222, 11, v225
	v_lshl_add_u32 v222, v224, 1, v222
	v_add_f32_e32 v194, 1.0, v194
	v_add_f32_e32 v195, 1.0, v195
	v_add_f32_e32 v196, 1.0, v196
	v_add_f32_e32 v197, 1.0, v197
	v_add_f32_e32 v198, 1.0, v198
	v_add_f32_e32 v199, 1.0, v199
	v_add_f32_e32 v200, 1.0, v200
	v_add_f32_e32 v201, 1.0, v201
	v_add_f32_e32 v202, 1.0, v202
	v_add_f32_e32 v203, 1.0, v203
	v_add_f32_e32 v204, 1.0, v204
	v_add_f32_e32 v205, 1.0, v205
	v_add_f32_e32 v206, 1.0, v206
	v_add_f32_e32 v207, 1.0, v207
	v_add_f32_e32 v208, 1.0, v208
	v_add_f32_e32 v209, 1.0, v209
	s_waitcnt lgkmcnt(0)
	v_mul_f32_e32 v140, v126, v210
	v_mul_f32_e32 v141, v127, v210
	v_mul_f32_e32 v142, v128, v210
	v_mul_f32_e32 v143, v129, v210
	v_mul_f32_e32 v140, v140, v156
	v_mul_f32_e32 v141, v141, v157
	v_mul_f32_e32 v142, v142, v158
	v_mul_f32_e32 v143, v143, v159
	v_fma_f32 v140, v140, v194, v172
	v_fma_f32 v141, v141, v195, v173
	v_fma_f32 v142, v142, v196, v174
	v_fma_f32 v143, v143, v197, v175
	v_cvt_pk_bf16_f32 v140, v140, v141
	v_cvt_pk_bf16_f32 v141, v142, v143
	v_add_u32_e32 v148, 0x0, v222
	global_store_dwordx2 v148, v[140:141], s[36:37]
	v_mul_f32_e32 v144, v122, v210
	v_mul_f32_e32 v145, v123, v210
	v_mul_f32_e32 v146, v124, v210
	v_mul_f32_e32 v147, v125, v210
	v_mul_f32_e32 v144, v144, v160
	v_mul_f32_e32 v145, v145, v161
	v_mul_f32_e32 v146, v146, v162
	v_mul_f32_e32 v147, v147, v163
	v_fma_f32 v144, v144, v198, v182
	v_fma_f32 v145, v145, v199, v183
	v_fma_f32 v146, v146, v200, v184
	v_fma_f32 v147, v147, v201, v185
	v_cvt_pk_bf16_f32 v144, v144, v145
	v_cvt_pk_bf16_f32 v145, v146, v147
	v_add_u32_e32 v149, 0x20, v222
	global_store_dwordx2 v149, v[144:145], s[36:37]
	v_mul_f32_e32 v140, v118, v210
	v_mul_f32_e32 v141, v119, v210
	v_mul_f32_e32 v142, v120, v210
	v_mul_f32_e32 v143, v121, v210
	v_mul_f32_e32 v140, v140, v164
	v_mul_f32_e32 v141, v141, v165
	v_mul_f32_e32 v142, v142, v166
	v_mul_f32_e32 v143, v143, v167
	v_fma_f32 v140, v140, v202, v186
	v_fma_f32 v141, v141, v203, v187
	v_fma_f32 v142, v142, v204, v188
	v_fma_f32 v143, v143, v205, v189
	v_cvt_pk_bf16_f32 v140, v140, v141
	v_cvt_pk_bf16_f32 v141, v142, v143
	v_add_u32_e32 v150, 0x100, v222
	global_store_dwordx2 v150, v[140:141], s[36:37]
	v_mul_f32_e32 v144, v114, v210
	v_mul_f32_e32 v145, v115, v210
	v_mul_f32_e32 v146, v116, v210
	v_mul_f32_e32 v147, v117, v210
	v_mul_f32_e32 v144, v144, v168
	v_mul_f32_e32 v145, v145, v169
	v_mul_f32_e32 v146, v146, v170
	v_mul_f32_e32 v147, v147, v171
	v_fma_f32 v144, v144, v206, v190
	v_fma_f32 v145, v145, v207, v191
	v_fma_f32 v146, v146, v208, v192
	v_fma_f32 v147, v147, v209, v193
	v_cvt_pk_bf16_f32 v144, v144, v145
	v_cvt_pk_bf16_f32 v145, v146, v147
	v_add_u32_e32 v151, 0x120, v222
	global_store_dwordx2 v151, v[144:145], s[36:37]
	v_mul_f32_e32 v140, v110, v211
	v_mul_f32_e32 v141, v111, v211
	v_mul_f32_e32 v142, v112, v211
	v_mul_f32_e32 v143, v113, v211
	v_mul_f32_e32 v140, v140, v156
	v_mul_f32_e32 v141, v141, v157
	v_mul_f32_e32 v142, v142, v158
	v_mul_f32_e32 v143, v143, v159
	v_fma_f32 v140, v140, v194, v172
	v_fma_f32 v141, v141, v195, v173
	v_fma_f32 v142, v142, v196, v174
	v_fma_f32 v143, v143, v197, v175
	v_cvt_pk_bf16_f32 v140, v140, v141
	v_cvt_pk_bf16_f32 v141, v142, v143
	v_add_u32_e32 v148, 0x8000, v222
	global_store_dwordx2 v148, v[140:141], s[36:37]
	v_mul_f32_e32 v144, v106, v211
	v_mul_f32_e32 v145, v107, v211
	v_mul_f32_e32 v146, v108, v211
	v_mul_f32_e32 v147, v109, v211
	v_mul_f32_e32 v144, v144, v160
	v_mul_f32_e32 v145, v145, v161
	v_mul_f32_e32 v146, v146, v162
	v_mul_f32_e32 v147, v147, v163
	v_fma_f32 v144, v144, v198, v182
	v_fma_f32 v145, v145, v199, v183
	v_fma_f32 v146, v146, v200, v184
	v_fma_f32 v147, v147, v201, v185
	v_cvt_pk_bf16_f32 v144, v144, v145
	v_cvt_pk_bf16_f32 v145, v146, v147
	v_add_u32_e32 v149, 0x8020, v222
	global_store_dwordx2 v149, v[144:145], s[36:37]
	v_mul_f32_e32 v140, v102, v211
	v_mul_f32_e32 v141, v103, v211
	v_mul_f32_e32 v142, v104, v211
	v_mul_f32_e32 v143, v105, v211
	v_mul_f32_e32 v140, v140, v164
	v_mul_f32_e32 v141, v141, v165
	v_mul_f32_e32 v142, v142, v166
	v_mul_f32_e32 v143, v143, v167
	v_fma_f32 v140, v140, v202, v186
	v_fma_f32 v141, v141, v203, v187
	v_fma_f32 v142, v142, v204, v188
	v_fma_f32 v143, v143, v205, v189
	v_cvt_pk_bf16_f32 v140, v140, v141
	v_cvt_pk_bf16_f32 v141, v142, v143
	v_add_u32_e32 v150, 0x8100, v222
	global_store_dwordx2 v150, v[140:141], s[36:37]
	v_mul_f32_e32 v144, v98, v211
	v_mul_f32_e32 v145, v99, v211
	v_mul_f32_e32 v146, v100, v211
	v_mul_f32_e32 v147, v101, v211
	v_mul_f32_e32 v144, v144, v168
	v_mul_f32_e32 v145, v145, v169
	v_mul_f32_e32 v146, v146, v170
	v_mul_f32_e32 v147, v147, v171
	v_fma_f32 v144, v144, v206, v190
	v_fma_f32 v145, v145, v207, v191
	v_fma_f32 v146, v146, v208, v192
	v_fma_f32 v147, v147, v209, v193
	v_cvt_pk_bf16_f32 v144, v144, v145
	v_cvt_pk_bf16_f32 v145, v146, v147
	v_add_u32_e32 v151, 0x8120, v222
	global_store_dwordx2 v151, v[144:145], s[36:37]
	v_mul_f32_e32 v140, v94, v212
	v_mul_f32_e32 v141, v95, v212
	v_mul_f32_e32 v142, v96, v212
	v_mul_f32_e32 v143, v97, v212
	v_mul_f32_e32 v140, v140, v156
	v_mul_f32_e32 v141, v141, v157
	v_mul_f32_e32 v142, v142, v158
	v_mul_f32_e32 v143, v143, v159
	v_fma_f32 v140, v140, v194, v172
	v_fma_f32 v141, v141, v195, v173
	v_fma_f32 v142, v142, v196, v174
	v_fma_f32 v143, v143, v197, v175
	v_cvt_pk_bf16_f32 v140, v140, v141
	v_cvt_pk_bf16_f32 v141, v142, v143
	v_add_u32_e32 v148, 0x10000, v222
	global_store_dwordx2 v148, v[140:141], s[36:37]
	v_mul_f32_e32 v144, v90, v212
	v_mul_f32_e32 v145, v91, v212
	v_mul_f32_e32 v146, v92, v212
	v_mul_f32_e32 v147, v93, v212
	v_mul_f32_e32 v144, v144, v160
	v_mul_f32_e32 v145, v145, v161
	v_mul_f32_e32 v146, v146, v162
	v_mul_f32_e32 v147, v147, v163
	v_fma_f32 v144, v144, v198, v182
	v_fma_f32 v145, v145, v199, v183
	v_fma_f32 v146, v146, v200, v184
	v_fma_f32 v147, v147, v201, v185
	v_cvt_pk_bf16_f32 v144, v144, v145
	v_cvt_pk_bf16_f32 v145, v146, v147
	v_add_u32_e32 v149, 0x10020, v222
	global_store_dwordx2 v149, v[144:145], s[36:37]
	v_mul_f32_e32 v140, v86, v212
	v_mul_f32_e32 v141, v87, v212
	v_mul_f32_e32 v142, v88, v212
	v_mul_f32_e32 v143, v89, v212
	v_mul_f32_e32 v140, v140, v164
	v_mul_f32_e32 v141, v141, v165
	v_mul_f32_e32 v142, v142, v166
	v_mul_f32_e32 v143, v143, v167
	v_fma_f32 v140, v140, v202, v186
	v_fma_f32 v141, v141, v203, v187
	v_fma_f32 v142, v142, v204, v188
	v_fma_f32 v143, v143, v205, v189
	v_cvt_pk_bf16_f32 v140, v140, v141
	v_cvt_pk_bf16_f32 v141, v142, v143
	v_add_u32_e32 v150, 0x10100, v222
	global_store_dwordx2 v150, v[140:141], s[36:37]
	v_mul_f32_e32 v144, v82, v212
	v_mul_f32_e32 v145, v83, v212
	v_mul_f32_e32 v146, v84, v212
	v_mul_f32_e32 v147, v85, v212
	v_mul_f32_e32 v144, v144, v168
	v_mul_f32_e32 v145, v145, v169
	v_mul_f32_e32 v146, v146, v170
	v_mul_f32_e32 v147, v147, v171
	v_fma_f32 v144, v144, v206, v190
	v_fma_f32 v145, v145, v207, v191
	v_fma_f32 v146, v146, v208, v192
	v_fma_f32 v147, v147, v209, v193
	v_cvt_pk_bf16_f32 v144, v144, v145
	v_cvt_pk_bf16_f32 v145, v146, v147
	v_add_u32_e32 v151, 0x10120, v222
	global_store_dwordx2 v151, v[144:145], s[36:37]
	v_mul_f32_e32 v140, v78, v213
	v_mul_f32_e32 v141, v79, v213
	v_mul_f32_e32 v142, v80, v213
	v_mul_f32_e32 v143, v81, v213
	v_mul_f32_e32 v140, v140, v156
	v_mul_f32_e32 v141, v141, v157
	v_mul_f32_e32 v142, v142, v158
	v_mul_f32_e32 v143, v143, v159
	v_fma_f32 v140, v140, v194, v172
	v_fma_f32 v141, v141, v195, v173
	v_fma_f32 v142, v142, v196, v174
	v_fma_f32 v143, v143, v197, v175
	v_cvt_pk_bf16_f32 v140, v140, v141
	v_cvt_pk_bf16_f32 v141, v142, v143
	v_add_u32_e32 v148, 0x18000, v222
	global_store_dwordx2 v148, v[140:141], s[36:37]
	v_mul_f32_e32 v144, v74, v213
	v_mul_f32_e32 v145, v75, v213
	v_mul_f32_e32 v146, v76, v213
	v_mul_f32_e32 v147, v77, v213
	v_mul_f32_e32 v144, v144, v160
	v_mul_f32_e32 v145, v145, v161
	v_mul_f32_e32 v146, v146, v162
	v_mul_f32_e32 v147, v147, v163
	v_fma_f32 v144, v144, v198, v182
	v_fma_f32 v145, v145, v199, v183
	v_fma_f32 v146, v146, v200, v184
	v_fma_f32 v147, v147, v201, v185
	v_cvt_pk_bf16_f32 v144, v144, v145
	v_cvt_pk_bf16_f32 v145, v146, v147
	v_add_u32_e32 v149, 0x18020, v222
	global_store_dwordx2 v149, v[144:145], s[36:37]
	v_mul_f32_e32 v140, v70, v213
	v_mul_f32_e32 v141, v71, v213
	v_mul_f32_e32 v142, v72, v213
	v_mul_f32_e32 v143, v73, v213
	v_mul_f32_e32 v140, v140, v164
	v_mul_f32_e32 v141, v141, v165
	v_mul_f32_e32 v142, v142, v166
	v_mul_f32_e32 v143, v143, v167
	v_fma_f32 v140, v140, v202, v186
	v_fma_f32 v141, v141, v203, v187
	v_fma_f32 v142, v142, v204, v188
	v_fma_f32 v143, v143, v205, v189
	v_cvt_pk_bf16_f32 v140, v140, v141
	v_cvt_pk_bf16_f32 v141, v142, v143
	v_add_u32_e32 v150, 0x18100, v222
	global_store_dwordx2 v150, v[140:141], s[36:37]
	v_mul_f32_e32 v144, v66, v213
	v_mul_f32_e32 v145, v67, v213
	v_mul_f32_e32 v146, v68, v213
	v_mul_f32_e32 v147, v69, v213
	v_mul_f32_e32 v144, v144, v168
	v_mul_f32_e32 v145, v145, v169
	v_mul_f32_e32 v146, v146, v170
	v_mul_f32_e32 v147, v147, v171
	v_fma_f32 v144, v144, v206, v190
	v_fma_f32 v145, v145, v207, v191
	v_fma_f32 v146, v146, v208, v192
	v_fma_f32 v147, v147, v209, v193
	v_cvt_pk_bf16_f32 v144, v144, v145
	v_cvt_pk_bf16_f32 v145, v146, v147
	v_add_u32_e32 v151, 0x18120, v222
	global_store_dwordx2 v151, v[144:145], s[36:37]
	v_mul_f32_e32 v140, v62, v214
	v_mul_f32_e32 v141, v63, v214
	v_mul_f32_e32 v142, v64, v214
	v_mul_f32_e32 v143, v65, v214
	v_mul_f32_e32 v140, v140, v156
	v_mul_f32_e32 v141, v141, v157
	v_mul_f32_e32 v142, v142, v158
	v_mul_f32_e32 v143, v143, v159
	v_fma_f32 v140, v140, v194, v172
	v_fma_f32 v141, v141, v195, v173
	v_fma_f32 v142, v142, v196, v174
	v_fma_f32 v143, v143, v197, v175
	v_cvt_pk_bf16_f32 v140, v140, v141
	v_cvt_pk_bf16_f32 v141, v142, v143
	v_add_u32_e32 v148, 0x40000, v222
	global_store_dwordx2 v148, v[140:141], s[36:37]
	v_mul_f32_e32 v144, v58, v214
	v_mul_f32_e32 v145, v59, v214
	v_mul_f32_e32 v146, v60, v214
	v_mul_f32_e32 v147, v61, v214
	v_mul_f32_e32 v144, v144, v160
	v_mul_f32_e32 v145, v145, v161
	v_mul_f32_e32 v146, v146, v162
	v_mul_f32_e32 v147, v147, v163
	v_fma_f32 v144, v144, v198, v182
	v_fma_f32 v145, v145, v199, v183
	v_fma_f32 v146, v146, v200, v184
	v_fma_f32 v147, v147, v201, v185
	v_cvt_pk_bf16_f32 v144, v144, v145
	v_cvt_pk_bf16_f32 v145, v146, v147
	v_add_u32_e32 v149, 0x40020, v222
	global_store_dwordx2 v149, v[144:145], s[36:37]
	v_mul_f32_e32 v140, v54, v214
	v_mul_f32_e32 v141, v55, v214
	v_mul_f32_e32 v142, v56, v214
	v_mul_f32_e32 v143, v57, v214
	v_mul_f32_e32 v140, v140, v164
	v_mul_f32_e32 v141, v141, v165
	v_mul_f32_e32 v142, v142, v166
	v_mul_f32_e32 v143, v143, v167
	v_fma_f32 v140, v140, v202, v186
	v_fma_f32 v141, v141, v203, v187
	v_fma_f32 v142, v142, v204, v188
	v_fma_f32 v143, v143, v205, v189
	v_cvt_pk_bf16_f32 v140, v140, v141
	v_cvt_pk_bf16_f32 v141, v142, v143
	v_add_u32_e32 v150, 0x40100, v222
	global_store_dwordx2 v150, v[140:141], s[36:37]
	v_mul_f32_e32 v144, v50, v214
	v_mul_f32_e32 v145, v51, v214
	v_mul_f32_e32 v146, v52, v214
	v_mul_f32_e32 v147, v53, v214
	v_mul_f32_e32 v144, v144, v168
	v_mul_f32_e32 v145, v145, v169
	v_mul_f32_e32 v146, v146, v170
	v_mul_f32_e32 v147, v147, v171
	v_fma_f32 v144, v144, v206, v190
	v_fma_f32 v145, v145, v207, v191
	v_fma_f32 v146, v146, v208, v192
	v_fma_f32 v147, v147, v209, v193
	v_cvt_pk_bf16_f32 v144, v144, v145
	v_cvt_pk_bf16_f32 v145, v146, v147
	v_add_u32_e32 v151, 0x40120, v222
	global_store_dwordx2 v151, v[144:145], s[36:37]
	v_mul_f32_e32 v140, v46, v215
	v_mul_f32_e32 v141, v47, v215
	v_mul_f32_e32 v142, v48, v215
	v_mul_f32_e32 v143, v49, v215
	v_mul_f32_e32 v140, v140, v156
	v_mul_f32_e32 v141, v141, v157
	v_mul_f32_e32 v142, v142, v158
	v_mul_f32_e32 v143, v143, v159
	v_fma_f32 v140, v140, v194, v172
	v_fma_f32 v141, v141, v195, v173
	v_fma_f32 v142, v142, v196, v174
	v_fma_f32 v143, v143, v197, v175
	v_cvt_pk_bf16_f32 v140, v140, v141
	v_cvt_pk_bf16_f32 v141, v142, v143
	v_add_u32_e32 v148, 0x48000, v222
	global_store_dwordx2 v148, v[140:141], s[36:37]
	v_mul_f32_e32 v144, v42, v215
	v_mul_f32_e32 v145, v43, v215
	v_mul_f32_e32 v146, v44, v215
	v_mul_f32_e32 v147, v45, v215
	v_mul_f32_e32 v144, v144, v160
	v_mul_f32_e32 v145, v145, v161
	v_mul_f32_e32 v146, v146, v162
	v_mul_f32_e32 v147, v147, v163
	v_fma_f32 v144, v144, v198, v182
	v_fma_f32 v145, v145, v199, v183
	v_fma_f32 v146, v146, v200, v184
	v_fma_f32 v147, v147, v201, v185
	v_cvt_pk_bf16_f32 v144, v144, v145
	v_cvt_pk_bf16_f32 v145, v146, v147
	v_add_u32_e32 v149, 0x48020, v222
	global_store_dwordx2 v149, v[144:145], s[36:37]
	v_mul_f32_e32 v140, v38, v215
	v_mul_f32_e32 v141, v39, v215
	v_mul_f32_e32 v142, v40, v215
	v_mul_f32_e32 v143, v41, v215
	v_mul_f32_e32 v140, v140, v164
	v_mul_f32_e32 v141, v141, v165
	v_mul_f32_e32 v142, v142, v166
	v_mul_f32_e32 v143, v143, v167
	v_fma_f32 v140, v140, v202, v186
	v_fma_f32 v141, v141, v203, v187
	v_fma_f32 v142, v142, v204, v188
	v_fma_f32 v143, v143, v205, v189
	v_cvt_pk_bf16_f32 v140, v140, v141
	v_cvt_pk_bf16_f32 v141, v142, v143
	v_add_u32_e32 v150, 0x48100, v222
	global_store_dwordx2 v150, v[140:141], s[36:37]
	v_mul_f32_e32 v144, v34, v215
	v_mul_f32_e32 v145, v35, v215
	v_mul_f32_e32 v146, v36, v215
	v_mul_f32_e32 v147, v37, v215
	v_mul_f32_e32 v144, v144, v168
	v_mul_f32_e32 v145, v145, v169
	v_mul_f32_e32 v146, v146, v170
	v_mul_f32_e32 v147, v147, v171
	v_fma_f32 v144, v144, v206, v190
	v_fma_f32 v145, v145, v207, v191
	v_fma_f32 v146, v146, v208, v192
	v_fma_f32 v147, v147, v209, v193
	v_cvt_pk_bf16_f32 v144, v144, v145
	v_cvt_pk_bf16_f32 v145, v146, v147
	v_add_u32_e32 v151, 0x48120, v222
	global_store_dwordx2 v151, v[144:145], s[36:37]
	v_mul_f32_e32 v140, v30, v216
	v_mul_f32_e32 v141, v31, v216
	v_mul_f32_e32 v142, v32, v216
	v_mul_f32_e32 v143, v33, v216
	v_mul_f32_e32 v140, v140, v156
	v_mul_f32_e32 v141, v141, v157
	v_mul_f32_e32 v142, v142, v158
	v_mul_f32_e32 v143, v143, v159
	v_fma_f32 v140, v140, v194, v172
	v_fma_f32 v141, v141, v195, v173
	v_fma_f32 v142, v142, v196, v174
	v_fma_f32 v143, v143, v197, v175
	v_cvt_pk_bf16_f32 v140, v140, v141
	v_cvt_pk_bf16_f32 v141, v142, v143
	v_add_u32_e32 v148, 0x50000, v222
	global_store_dwordx2 v148, v[140:141], s[36:37]
	v_mul_f32_e32 v144, v26, v216
	v_mul_f32_e32 v145, v27, v216
	v_mul_f32_e32 v146, v28, v216
	v_mul_f32_e32 v147, v29, v216
	v_mul_f32_e32 v144, v144, v160
	v_mul_f32_e32 v145, v145, v161
	v_mul_f32_e32 v146, v146, v162
	v_mul_f32_e32 v147, v147, v163
	v_fma_f32 v144, v144, v198, v182
	v_fma_f32 v145, v145, v199, v183
	v_fma_f32 v146, v146, v200, v184
	v_fma_f32 v147, v147, v201, v185
	v_cvt_pk_bf16_f32 v144, v144, v145
	v_cvt_pk_bf16_f32 v145, v146, v147
	v_add_u32_e32 v149, 0x50020, v222
	global_store_dwordx2 v149, v[144:145], s[36:37]
	v_mul_f32_e32 v140, v22, v216
	v_mul_f32_e32 v141, v23, v216
	v_mul_f32_e32 v142, v24, v216
	v_mul_f32_e32 v143, v25, v216
	v_mul_f32_e32 v140, v140, v164
	v_mul_f32_e32 v141, v141, v165
	v_mul_f32_e32 v142, v142, v166
	v_mul_f32_e32 v143, v143, v167
	v_fma_f32 v140, v140, v202, v186
	v_fma_f32 v141, v141, v203, v187
	v_fma_f32 v142, v142, v204, v188
	v_fma_f32 v143, v143, v205, v189
	v_cvt_pk_bf16_f32 v140, v140, v141
	v_cvt_pk_bf16_f32 v141, v142, v143
	v_add_u32_e32 v150, 0x50100, v222
	global_store_dwordx2 v150, v[140:141], s[36:37]
	v_mul_f32_e32 v144, v18, v216
	v_mul_f32_e32 v145, v19, v216
	v_mul_f32_e32 v146, v20, v216
	v_mul_f32_e32 v147, v21, v216
	v_mul_f32_e32 v144, v144, v168
	v_mul_f32_e32 v145, v145, v169
	v_mul_f32_e32 v146, v146, v170
	v_mul_f32_e32 v147, v147, v171
	v_fma_f32 v144, v144, v206, v190
	v_fma_f32 v145, v145, v207, v191
	v_fma_f32 v146, v146, v208, v192
	v_fma_f32 v147, v147, v209, v193
	v_cvt_pk_bf16_f32 v144, v144, v145
	v_cvt_pk_bf16_f32 v145, v146, v147
	v_add_u32_e32 v151, 0x50120, v222
	global_store_dwordx2 v151, v[144:145], s[36:37]
	v_mul_f32_e32 v140, v14, v217
	v_mul_f32_e32 v141, v15, v217
	v_mul_f32_e32 v142, v16, v217
	v_mul_f32_e32 v143, v17, v217
	v_mul_f32_e32 v140, v140, v156
	v_mul_f32_e32 v141, v141, v157
	v_mul_f32_e32 v142, v142, v158
	v_mul_f32_e32 v143, v143, v159
	v_fma_f32 v140, v140, v194, v172
	v_fma_f32 v141, v141, v195, v173
	v_fma_f32 v142, v142, v196, v174
	v_fma_f32 v143, v143, v197, v175
	v_cvt_pk_bf16_f32 v140, v140, v141
	v_cvt_pk_bf16_f32 v141, v142, v143
	v_add_u32_e32 v148, 0x58000, v222
	global_store_dwordx2 v148, v[140:141], s[36:37]
	v_mul_f32_e32 v144, v10, v217
	v_mul_f32_e32 v145, v11, v217
	v_mul_f32_e32 v146, v12, v217
	v_mul_f32_e32 v147, v13, v217
	v_mul_f32_e32 v144, v144, v160
	v_mul_f32_e32 v145, v145, v161
	v_mul_f32_e32 v146, v146, v162
	v_mul_f32_e32 v147, v147, v163
	v_fma_f32 v144, v144, v198, v182
	v_fma_f32 v145, v145, v199, v183
	v_fma_f32 v146, v146, v200, v184
	v_fma_f32 v147, v147, v201, v185
	v_cvt_pk_bf16_f32 v144, v144, v145
	v_cvt_pk_bf16_f32 v145, v146, v147
	v_add_u32_e32 v149, 0x58020, v222
	global_store_dwordx2 v149, v[144:145], s[36:37]
	v_mul_f32_e32 v140, v6, v217
	v_mul_f32_e32 v141, v7, v217
	v_mul_f32_e32 v142, v8, v217
	v_mul_f32_e32 v143, v9, v217
	v_mul_f32_e32 v140, v140, v164
	v_mul_f32_e32 v141, v141, v165
	v_mul_f32_e32 v142, v142, v166
	v_mul_f32_e32 v143, v143, v167
	v_fma_f32 v140, v140, v202, v186
	v_fma_f32 v141, v141, v203, v187
	v_fma_f32 v142, v142, v204, v188
	v_fma_f32 v143, v143, v205, v189
	v_cvt_pk_bf16_f32 v140, v140, v141
	v_cvt_pk_bf16_f32 v141, v142, v143
	v_add_u32_e32 v150, 0x58100, v222
	global_store_dwordx2 v150, v[140:141], s[36:37]
	v_mul_f32_e32 v144, v2, v217
	v_mul_f32_e32 v145, v3, v217
	v_mul_f32_e32 v146, v4, v217
	v_mul_f32_e32 v147, v5, v217
	v_mul_f32_e32 v144, v144, v168
	v_mul_f32_e32 v145, v145, v169
	v_mul_f32_e32 v146, v146, v170
	v_mul_f32_e32 v147, v147, v171
	v_fma_f32 v144, v144, v206, v190
	v_fma_f32 v145, v145, v207, v191
	v_fma_f32 v146, v146, v208, v192
	v_fma_f32 v147, v147, v209, v193
	v_cvt_pk_bf16_f32 v144, v144, v145
	v_cvt_pk_bf16_f32 v145, v146, v147
	v_add_u32_e32 v151, 0x58120, v222
	global_store_dwordx2 v151, v[144:145], s[36:37]
	s_branch .LBB0_1928

.LBB0_1932:
	v_lshl_add_u64 v[132:133], v[70:71], 0, s[0:1]
	v_lshl_add_u64 v[136:137], v[86:87], 0, s[0:1]
	v_lshl_add_u64 v[138:139], v[84:85], 0, s[0:1]
	v_lshl_add_u64 v[140:141], v[68:69], 0, s[0:1]
	v_lshl_add_u64 v[130:131], v[66:67], 0, s[0:1]
	v_lshl_add_u64 v[134:135], v[82:83], 0, s[0:1]
	v_lshl_add_u64 v[142:143], v[88:89], 0, s[0:1]
	v_lshl_add_u64 v[144:145], v[72:73], 0, s[0:1]
	global_load_dwordx4 v[110:113], v[132:133], off
	global_load_dwordx4 v[118:121], v[136:137], off
	global_load_dwordx4 v[122:125], v[138:139], off offset:-64
	global_load_dwordx4 v[126:129], v[140:141], off offset:-64
	global_load_dwordx4 v[114:117], v[130:131], off
	global_load_dwordx4 v[146:149], v[134:135], off
	global_load_dwordx4 v[150:153], v[142:143], off
	global_load_dwordx4 v[154:157], v[144:145], off offset:-64
	global_load_dwordx4 v[158:161], v[132:133], off offset:64
	global_load_dwordx4 v[162:165], v[136:137], off offset:64
	global_load_dwordx4 v[166:169], v[138:139], off
	global_load_dwordx4 v[170:173], v[140:141], off
	global_load_dwordx4 v[174:177], v[130:131], off offset:64
	global_load_dwordx4 v[182:185], v[134:135], off offset:64
	global_load_dwordx4 v[186:189], v[142:143], off offset:64
	global_load_dwordx4 v[190:193], v[144:145], off
	s_add_u32 s0, s0, 0x80
	s_addc_u32 s1, s1, 0
	s_cmpk_eq_i32 s0, 0x200
	s_waitcnt vmcnt(8)
	v_mfma_f32_16x16x32_bf16 v[2:5], v[110:113], v[114:117], v[2:5]
	v_mfma_f32_16x16x32_bf16 v[6:9], v[118:121], v[114:117], v[6:9]
	v_mfma_f32_16x16x32_bf16 v[10:13], v[122:125], v[114:117], v[10:13]
	v_mfma_f32_16x16x32_bf16 v[14:17], v[126:129], v[114:117], v[14:17]
	v_mfma_f32_16x16x32_bf16 v[18:21], v[110:113], v[146:149], v[18:21]
	v_mfma_f32_16x16x32_bf16 v[22:25], v[118:121], v[146:149], v[22:25]
	v_mfma_f32_16x16x32_bf16 v[26:29], v[122:125], v[146:149], v[26:29]
	v_mfma_f32_16x16x32_bf16 v[30:33], v[126:129], v[146:149], v[30:33]
	v_mfma_f32_16x16x32_bf16 v[34:37], v[110:113], v[150:153], v[34:37]
	v_mfma_f32_16x16x32_bf16 v[38:41], v[118:121], v[150:153], v[38:41]
	v_mfma_f32_16x16x32_bf16 v[42:45], v[122:125], v[150:153], v[42:45]
	v_mfma_f32_16x16x32_bf16 v[46:49], v[126:129], v[150:153], v[46:49]
	v_mfma_f32_16x16x32_bf16 v[50:53], v[110:113], v[154:157], v[50:53]
	v_mfma_f32_16x16x32_bf16 v[54:57], v[118:121], v[154:157], v[54:57]
	v_mfma_f32_16x16x32_bf16 v[58:61], v[122:125], v[154:157], v[58:61]
	v_mfma_f32_16x16x32_bf16 v[62:65], v[126:129], v[154:157], v[62:65]
	s_waitcnt vmcnt(0)
	v_mfma_f32_16x16x32_bf16 v[2:5], v[158:161], v[174:177], v[2:5]
	v_mfma_f32_16x16x32_bf16 v[6:9], v[162:165], v[174:177], v[6:9]
	v_mfma_f32_16x16x32_bf16 v[10:13], v[166:169], v[174:177], v[10:13]
	v_mfma_f32_16x16x32_bf16 v[14:17], v[170:173], v[174:177], v[14:17]
	v_mfma_f32_16x16x32_bf16 v[18:21], v[158:161], v[182:185], v[18:21]
	v_mfma_f32_16x16x32_bf16 v[22:25], v[162:165], v[182:185], v[22:25]
	v_mfma_f32_16x16x32_bf16 v[26:29], v[166:169], v[182:185], v[26:29]
	v_mfma_f32_16x16x32_bf16 v[30:33], v[170:173], v[182:185], v[30:33]
	v_mfma_f32_16x16x32_bf16 v[34:37], v[158:161], v[186:189], v[34:37]
	v_mfma_f32_16x16x32_bf16 v[38:41], v[162:165], v[186:189], v[38:41]
	v_mfma_f32_16x16x32_bf16 v[42:45], v[166:169], v[186:189], v[42:45]
	v_mfma_f32_16x16x32_bf16 v[46:49], v[170:173], v[186:189], v[46:49]
	v_mfma_f32_16x16x32_bf16 v[50:53], v[158:161], v[190:193], v[50:53]
	v_mfma_f32_16x16x32_bf16 v[54:57], v[162:165], v[190:193], v[54:57]
	v_mfma_f32_16x16x32_bf16 v[58:61], v[166:169], v[190:193], v[58:61]
	v_mfma_f32_16x16x32_bf16 v[62:65], v[170:173], v[190:193], v[62:65]
	s_cbranch_scc0 .LBB0_1932
	v_readlane_b32 s36, v252, 26
	v_readlane_b32 s37, v252, 27
	s_add_i32 s0, s2, 0x4000
	v_readlane_b32 s38, v252, 28
	v_readlane_b32 s39, v252, 29
	s_mov_b64 s[12:13], s[36:37]
	s_lshl_b32 s1, s3, 4
	v_add_u32_e32 v84, s0, v179
	s_movk_i32 s0, 0x4000
	s_mov_b64 s[14:15], s[38:39]
	s_sub_i32 s4, s9, s1
	s_barrier
	ds_write_b128 v106, v[2:5]
	ds_write_b128 v106, v[6:9] offset:64
	ds_write_b128 v106, v[10:13] offset:128
	ds_write_b128 v106, v[14:17] offset:192
	ds_write_b128 v106, v[18:21] offset:4096
	ds_write_b128 v106, v[22:25] offset:4160
	ds_write_b128 v106, v[26:29] offset:4224
	ds_write_b128 v106, v[30:33] offset:4288
	ds_write_b128 v106, v[34:37] offset:8192
	ds_write_b128 v106, v[38:41] offset:8256
	ds_write_b128 v106, v[42:45] offset:8320
	ds_write_b128 v106, v[46:49] offset:8384
	ds_write_b128 v106, v[50:53] offset:12288
	ds_write_b128 v106, v[54:57] offset:12352
	ds_write_b128 v106, v[58:61] offset:12416
	ds_write_b128 v106, v[62:65] offset:12480
	v_add_u32_e32 v82, s2, v179
	v_ashrrev_i32_e32 v85, 31, v84
	v_cmp_gt_i32_e64 s[0:1], s0, v84
	v_mov_b32_e32 v4, s15
	v_mov_b32_e32 v5, s13
	v_cndmask_b32_e64 v3, 0, v85, s[0:1]
	v_cndmask_b32_e64 v2, v82, v84, s[0:1]
	v_cndmask_b32_e64 v5, v4, v5, s[0:1]
	v_mov_b32_e32 v4, s14
	v_mov_b32_e32 v6, s12
	v_lshl_or_b32 v86, s4, 6, v1
	v_cndmask_b32_e64 v4, v4, v6, s[0:1]
	v_lshlrev_b64 v[2:3], 12, v[2:3]
	v_lshl_add_u64 v[2:3], v[4:5], 0, v[2:3]
	v_ashrrev_i32_e32 v87, 31, v86
	v_lshl_add_u64 v[6:7], v[86:87], 2, v[2:3]
	s_waitcnt lgkmcnt(0)
	s_barrier
	global_load_dwordx4 v[2:5], v[6:7], off offset:16
	s_nop 0
	global_load_dwordx4 v[6:9], v[6:7], off
	ds_read_b128 v[70:73], v90
	ds_read_b128 v[66:69], v90 offset:16
	ds_read_b128 v[62:65], v90 offset:16384
	ds_read_b128 v[58:61], v90 offset:16400
	ds_read_b128 v[54:57], v90 offset:32768
	ds_read_b128 v[50:53], v90 offset:32784
	ds_read_b128 v[46:49], v90 offset:49152
	ds_read_b128 v[42:45], v90 offset:49168
	ds_read_b128 v[38:41], v91
	ds_read_b128 v[34:37], v92
	ds_read_b128 v[30:33], v93
	ds_read_b128 v[26:29], v94
	ds_read_b128 v[22:25], v95
	ds_read_b128 v[18:21], v96
	ds_read_b128 v[14:17], v97
	ds_read_b128 v[10:13], v98
	s_movk_i32 s0, 0x3fff
	v_cmp_lt_i32_e64 s[0:1], s0, v84
	v_readlane_b32 s40, v252, 30
	v_readlane_b32 s41, v252, 31
	v_readlane_b32 s42, v252, 32
	v_readlane_b32 s43, v252, 33
	v_readlane_b32 s44, v252, 34
	v_readlane_b32 s45, v252, 35
	v_readlane_b32 s46, v252, 36
	v_readlane_b32 s47, v252, 37
	v_readlane_b32 s48, v252, 38
	v_readlane_b32 s49, v252, 39
	v_readlane_b32 s50, v252, 40
	v_readlane_b32 s51, v252, 41
	s_and_saveexec_b64 s[6:7], s[0:1]
	s_xor_b64 s[0:1], exec, s[6:7]
	v_lshrrev_b32_e32 v83, 3, v82
	v_add_u32_e32 v83, 8, v83
	s_andn2_saveexec_b64 s[0:1], s[0:1]
	v_ashrrev_i32_e32 v83, 31, v84
	v_lshrrev_b32_e32 v83, 21, v83
	v_add_u32_e32 v83, v84, v83
	v_ashrrev_i32_e32 v83, 11, v83
	s_or_b64 exec, exec, s[0:1]
	s_waitcnt lgkmcnt(14)
	v_pk_add_f32 v[66:67], v[66:67], 0 op_sel_hi:[1,0]
	s_load_dwordx2 s[0:1], s[78:79], 0x1d0
	s_waitcnt lgkmcnt(0)
	v_pk_add_f32 v[58:59], v[66:67], v[58:59]
	v_pk_add_f32 v[70:71], v[70:71], 0 op_sel_hi:[1,0]
	v_pk_add_f32 v[50:51], v[58:59], v[50:51]
	v_pk_add_f32 v[62:63], v[70:71], v[62:63]
	v_pk_add_f32 v[42:43], v[50:51], v[42:43]
	v_pk_add_f32 v[54:55], v[62:63], v[54:55]
	v_pk_add_f32 v[34:35], v[42:43], v[34:35]
	v_pk_add_f32 v[72:73], v[72:73], 0 op_sel_hi:[1,0]
	v_pk_add_f32 v[26:27], v[34:35], v[26:27]
	v_pk_add_f32 v[68:69], v[68:69], 0 op_sel_hi:[1,0]
	v_pk_add_f32 v[46:47], v[54:55], v[46:47]
	v_pk_add_f32 v[18:19], v[26:27], v[18:19]
	v_pk_add_f32 v[64:65], v[72:73], v[64:65]
	v_pk_add_f32 v[60:61], v[68:69], v[60:61]
	v_pk_add_f32 v[38:39], v[46:47], v[38:39]
	v_pk_add_f32 v[18:19], v[18:19], v[10:11]
	v_mov_b64_e32 v[10:11], s[0:1]
	s_mov_b32 s0, 0xe000
	v_pk_add_f32 v[56:57], v[64:65], v[56:57]
	v_pk_add_f32 v[52:53], v[60:61], v[52:53]
	v_pk_add_f32 v[30:31], v[38:39], v[30:31]
	v_mad_i64_i32 v[10:11], s[0:1], v83, s0, v[10:11]
	v_pk_add_f32 v[48:49], v[56:57], v[48:49]
	v_pk_add_f32 v[44:45], v[52:53], v[44:45]
	v_pk_add_f32 v[22:23], v[30:31], v[22:23]
	v_lshl_add_u64 v[10:11], v[86:87], 2, v[10:11]
	s_mov_b64 s[0:1], 0x2000
	v_pk_add_f32 v[40:41], v[48:49], v[40:41]
	v_pk_add_f32 v[36:37], v[44:45], v[36:37]
	v_pk_add_f32 v[22:23], v[22:23], v[14:15]
	v_lshl_add_u64 v[14:15], v[10:11], 0, s[0:1]
	s_movk_i32 s0, 0x2000
	v_pk_add_f32 v[32:33], v[40:41], v[32:33]
	v_pk_add_f32 v[28:29], v[36:37], v[28:29]
	v_add_co_u32_e64 v10, s[0:1], s0, v10
	v_pk_add_f32 v[24:25], v[32:33], v[24:25]
	v_pk_add_f32 v[20:21], v[28:29], v[20:21]
	v_addc_co_u32_e64 v11, s[0:1], 0, v11, s[0:1]
	v_pk_add_f32 v[24:25], v[24:25], v[16:17]
	v_pk_add_f32 v[20:21], v[20:21], v[12:13]
	global_load_dwordx4 v[10:13], v[10:11], off
	s_nop 0
	global_load_dwordx4 v[14:17], v[14:15], off offset:16
	s_load_dwordx16 s[36:51], s[78:79], 0x1e0
	s_waitcnt vmcnt(1)
	v_pk_fma_f32 v[8:9], v[24:25], v[12:13], v[8:9]
	s_waitcnt vmcnt(0)
	v_pk_fma_f32 v[12:13], v[18:19], v[14:15], v[2:3]
	v_lshlrev_b64 v[14:15], 11, v[84:85]
	s_waitcnt lgkmcnt(0)
	v_lshl_add_u64 v[14:15], s[42:43], 0, v[14:15]
	v_pk_fma_f32 v[6:7], v[22:23], v[10:11], v[6:7]
	v_cvt_pk_bf16_f32 v3, v8, v9
	v_lshl_add_u64 v[14:15], v[86:87], 1, v[14:15]
	v_cvt_pk_bf16_f32 v2, v6, v7
	v_pk_fma_f32 v[10:11], v[20:21], v[16:17], v[4:5]
	v_cvt_pk_bf16_f32 v4, v12, v13
	s_nop 0
	v_cvt_pk_bf16_f32 v5, v10, v11
	global_store_dwordx4 v[14:15], v[2:5], off
	s_nop 1
	v_mul_f32_e32 v2, v7, v7
	v_mul_f32_e32 v3, v9, v9
	v_fmac_f32_e32 v2, v6, v6
	v_fmac_f32_e32 v3, v8, v8
	v_add_f32_e32 v2, v2, v3
	v_mul_f32_e32 v3, v13, v13
	v_mul_f32_e32 v4, v11, v11
	v_fmac_f32_e32 v3, v12, v12
	v_fmac_f32_e32 v4, v10, v10
	v_add_f32_e32 v3, v3, v4
	v_and_b32_e32 v4, 64, v108
	v_add_f32_e32 v2, v2, v3
	v_xor_b32_e32 v3, 1, v108
	v_add_u32_e32 v4, 64, v4
	v_cmp_lt_i32_e64 s[0:1], v3, v4
	s_nop 1
	v_cndmask_b32_e64 v3, v108, v3, s[0:1]
	v_lshlrev_b32_e32 v3, 2, v3
	ds_bpermute_b32 v3, v3, v2
	s_waitcnt lgkmcnt(0)
	v_add_f32_e32 v2, v2, v3
	v_xor_b32_e32 v3, 2, v108
	v_cmp_lt_i32_e64 s[0:1], v3, v4
	s_nop 1
	v_cndmask_b32_e64 v3, v108, v3, s[0:1]
	v_lshlrev_b32_e32 v3, 2, v3
	ds_bpermute_b32 v3, v3, v2
	s_waitcnt lgkmcnt(0)
	v_add_f32_e32 v2, v2, v3
	v_xor_b32_e32 v3, 4, v108
	v_cmp_lt_i32_e64 s[0:1], v3, v4
	s_nop 1
	v_cndmask_b32_e64 v3, v108, v3, s[0:1]
	v_lshlrev_b32_e32 v3, 2, v3
	ds_bpermute_b32 v3, v3, v2
	s_and_saveexec_b64 s[0:1], vcc
	s_cbranch_execz .LBB0_1939
	s_load_dwordx16 s[36:51], s[78:79], 0x140
	v_ashrrev_i32_e32 v83, 31, v82
	s_waitcnt lgkmcnt(0)
	v_add_f32_e32 v4, v2, v3
	v_lshlrev_b64 v[2:3], 6, v[82:83]
	s_ashr_i32 s5, s4, 31
	v_lshl_add_u64 v[2:3], s[48:49], 0, v[2:3]
	v_lshl_add_u64 v[2:3], s[4:5], 2, v[2:3]
	global_store_dword v[2:3], v4, off sc1

.LBB0_2519:
	s_lshl_b32 s18, s26, 8
	s_load_dwordx2 s[36:37], s[78:79], 0x1f8
	s_load_dwordx2 s[38:39], s[78:79], 0x1d0
	s_load_dwordx2 s[40:41], s[78:79], 0x1f8
	v_and_b32_e32 v130, 15, v248
	v_bfe_u32 v131, v248, 8, 1
	v_bfe_u32 v132, v248, 6, 2
	v_bfe_u32 v133, v248, 4, 2
	v_lshl_add_u32 v134, v131, 6, v130
	v_lshlrev_b32_e32 v135, 5, v132
	v_lshl_or_b32 v135, v133, 2, v135
	s_lshl_b32 s0, s2, 8
	v_add_u32_e32 v135, s0, v135
	s_lshl_b32 s0, s26, 8
	v_add_u32_e32 v136, s0, v134
	v_mul_u32_u24_e32 v137, 0x800, v136
	v_lshl_add_u32 v137, v135, 1, v137
	v_lshlrev_b32_e32 v138, 11, v136
	v_lshl_add_u32 v138, v135, 1, v138
	v_lshlrev_b32_e32 v139, 2, v134
	v_add_lshl_u32 v139, v139, v132, 2
	v_xor_b32_e32 v213, 16, v227
	v_lshlrev_b32_e32 v213, 2, v213
	v_xor_b32_e32 v214, 32, v227
	v_lshlrev_b32_e32 v214, 2, v214
	v_lshlrev_b32_e32 v215, 2, v135
	s_lshr_b32 s0, s26, 3
	s_mul_i32 s0, s0, 0xe000
	s_add_u32 s0, s0, 0x5000
	v_add_u32_e32 v215, s0, v215
	s_waitcnt lgkmcnt(0)
	global_load_dwordx4 v[140:143], v215, s[38:39] offset:0
	global_load_dwordx4 v[144:147], v215, s[38:39] offset:64
	global_load_dwordx4 v[148:151], v215, s[38:39] offset:512
	global_load_dwordx4 v[152:155], v215, s[38:39] offset:576
	v_add_u32_e32 v218, 0x0, v137
	global_load_dwordx2 v[156:157], v218, s[36:37]
	v_add_u32_e32 v219, 0x20, v137
	global_load_dwordx2 v[160:161], v219, s[36:37]
	v_add_u32_e32 v220, 0x100, v137
	global_load_dwordx2 v[164:165], v220, s[36:37]
	v_add_u32_e32 v221, 0x120, v137
	global_load_dwordx2 v[168:169], v221, s[36:37]
	v_add_u32_e32 v218, 0x8000, v137
	global_load_dwordx2 v[172:173], v218, s[36:37]
	v_add_u32_e32 v219, 0x8020, v137
	global_load_dwordx2 v[182:183], v219, s[36:37]
	v_add_u32_e32 v220, 0x8100, v137
	global_load_dwordx2 v[186:187], v220, s[36:37]
	v_add_u32_e32 v221, 0x8120, v137
	global_load_dwordx2 v[190:191], v221, s[36:37]
	v_add_u32_e32 v218, 0x10000, v137
	global_load_dwordx2 v[194:195], v218, s[36:37]
	v_add_u32_e32 v219, 0x10020, v137
	global_load_dwordx2 v[198:199], v219, s[36:37]
	v_add_u32_e32 v220, 0x10100, v137
	global_load_dwordx2 v[202:203], v220, s[36:37]
	v_add_u32_e32 v221, 0x10120, v137
	global_load_dwordx2 v[206:207], v221, s[36:37]
	s_waitcnt vmcnt(12)
	s_waitcnt vmcnt(8)
	v_lshlrev_b32_e32 v158, 16, v157
	v_and_b32_e32 v159, 0xffff0000, v157
	v_and_b32_e32 v157, 0xffff0000, v156
	v_lshlrev_b32_e32 v156, 16, v156
	v_pk_fma_f32 v[126:127], v[126:127], v[140:141], v[156:157]
	v_pk_fma_f32 v[128:129], v[128:129], v[142:143], v[158:159]
	v_lshlrev_b32_e32 v162, 16, v161
	v_and_b32_e32 v163, 0xffff0000, v161
	v_and_b32_e32 v161, 0xffff0000, v160
	v_lshlrev_b32_e32 v160, 16, v160
	v_pk_fma_f32 v[122:123], v[122:123], v[144:145], v[160:161]
	v_pk_fma_f32 v[124:125], v[124:125], v[146:147], v[162:163]
	v_lshlrev_b32_e32 v166, 16, v165
	v_and_b32_e32 v167, 0xffff0000, v165
	v_and_b32_e32 v165, 0xffff0000, v164
	v_lshlrev_b32_e32 v164, 16, v164
	v_pk_fma_f32 v[118:119], v[118:119], v[148:149], v[164:165]
	v_pk_fma_f32 v[120:121], v[120:121], v[150:151], v[166:167]
	v_lshlrev_b32_e32 v170, 16, v169
	v_and_b32_e32 v171, 0xffff0000, v169
	v_and_b32_e32 v169, 0xffff0000, v168
	v_lshlrev_b32_e32 v168, 16, v168
	v_pk_fma_f32 v[114:115], v[114:115], v[152:153], v[168:169]
	v_pk_fma_f32 v[116:117], v[116:117], v[154:155], v[170:171]
	v_cvt_pk_bf16_f32 v156, v126, v127
	v_cvt_pk_bf16_f32 v157, v128, v129
	v_mul_f32_e32 v158, v127, v127
	v_mul_f32_e32 v159, v129, v129
	v_fmac_f32_e32 v158, v126, v126
	v_fmac_f32_e32 v159, v128, v128
	v_add_f32_e32 v158, v158, v159
	v_add_f32_e32 v222, 0, v158
	v_add_u32_e32 v218, 0x0, v138
	global_store_dwordx2 v218, v[156:157], s[40:41]
	v_cvt_pk_bf16_f32 v160, v122, v123
	v_cvt_pk_bf16_f32 v161, v124, v125
	v_mul_f32_e32 v162, v123, v123
	v_mul_f32_e32 v163, v125, v125
	v_fmac_f32_e32 v162, v122, v122
	v_fmac_f32_e32 v163, v124, v124
	v_add_f32_e32 v162, v162, v163
	v_add_f32_e32 v222, v222, v162
	v_add_u32_e32 v219, 0x20, v138
	global_store_dwordx2 v219, v[160:161], s[40:41]
	v_cvt_pk_bf16_f32 v164, v118, v119
	v_cvt_pk_bf16_f32 v165, v120, v121
	v_mul_f32_e32 v166, v119, v119
	v_mul_f32_e32 v167, v121, v121
	v_fmac_f32_e32 v166, v118, v118
	v_fmac_f32_e32 v167, v120, v120
	v_add_f32_e32 v166, v166, v167
	v_add_f32_e32 v222, v222, v166
	v_add_u32_e32 v220, 0x100, v138
	global_store_dwordx2 v220, v[164:165], s[40:41]
	v_cvt_pk_bf16_f32 v168, v114, v115
	v_cvt_pk_bf16_f32 v169, v116, v117
	v_mul_f32_e32 v170, v115, v115
	v_mul_f32_e32 v171, v117, v117
	v_fmac_f32_e32 v170, v114, v114
	v_fmac_f32_e32 v171, v116, v116
	v_add_f32_e32 v170, v170, v171
	v_add_f32_e32 v222, v222, v170
	v_add_u32_e32 v221, 0x120, v138
	global_store_dwordx2 v221, v[168:169], s[40:41]
	v_add_u32_e32 v218, 0x18000, v137
	global_load_dwordx2 v[156:157], v218, s[36:37]
	v_add_u32_e32 v219, 0x18020, v137
	global_load_dwordx2 v[160:161], v219, s[36:37]
	v_add_u32_e32 v220, 0x18100, v137
	global_load_dwordx2 v[164:165], v220, s[36:37]
	v_add_u32_e32 v221, 0x18120, v137
	global_load_dwordx2 v[168:169], v221, s[36:37]
	s_waitcnt vmcnt(12)
	v_lshlrev_b32_e32 v174, 16, v173
	v_and_b32_e32 v175, 0xffff0000, v173
	v_and_b32_e32 v173, 0xffff0000, v172
	v_lshlrev_b32_e32 v172, 16, v172
	v_pk_fma_f32 v[110:111], v[110:111], v[140:141], v[172:173]
	v_pk_fma_f32 v[112:113], v[112:113], v[142:143], v[174:175]
	v_lshlrev_b32_e32 v184, 16, v183
	v_and_b32_e32 v185, 0xffff0000, v183
	v_and_b32_e32 v183, 0xffff0000, v182
	v_lshlrev_b32_e32 v182, 16, v182
	v_pk_fma_f32 v[106:107], v[106:107], v[144:145], v[182:183]
	v_pk_fma_f32 v[108:109], v[108:109], v[146:147], v[184:185]
	v_lshlrev_b32_e32 v188, 16, v187
	v_and_b32_e32 v189, 0xffff0000, v187
	v_and_b32_e32 v187, 0xffff0000, v186
	v_lshlrev_b32_e32 v186, 16, v186
	v_pk_fma_f32 v[102:103], v[102:103], v[148:149], v[186:187]
	v_pk_fma_f32 v[104:105], v[104:105], v[150:151], v[188:189]
	v_lshlrev_b32_e32 v192, 16, v191
	v_and_b32_e32 v193, 0xffff0000, v191
	v_and_b32_e32 v191, 0xffff0000, v190
	v_lshlrev_b32_e32 v190, 16, v190
	v_pk_fma_f32 v[98:99], v[98:99], v[152:153], v[190:191]
	v_pk_fma_f32 v[100:101], v[100:101], v[154:155], v[192:193]
	v_cvt_pk_bf16_f32 v172, v110, v111
	v_cvt_pk_bf16_f32 v173, v112, v113
	v_mul_f32_e32 v174, v111, v111
	v_mul_f32_e32 v175, v113, v113
	v_fmac_f32_e32 v174, v110, v110
	v_fmac_f32_e32 v175, v112, v112
	v_add_f32_e32 v174, v174, v175
	v_add_f32_e32 v223, 0, v174
	v_add_u32_e32 v218, 0x8000, v138
	global_store_dwordx2 v218, v[172:173], s[40:41]
	v_cvt_pk_bf16_f32 v182, v106, v107
	v_cvt_pk_bf16_f32 v183, v108, v109
	v_mul_f32_e32 v184, v107, v107
	v_mul_f32_e32 v185, v109, v109
	v_fmac_f32_e32 v184, v106, v106
	v_fmac_f32_e32 v185, v108, v108
	v_add_f32_e32 v184, v184, v185
	v_add_f32_e32 v223, v223, v184
	v_add_u32_e32 v219, 0x8020, v138
	global_store_dwordx2 v219, v[182:183], s[40:41]
	v_cvt_pk_bf16_f32 v186, v102, v103
	v_cvt_pk_bf16_f32 v187, v104, v105
	v_mul_f32_e32 v188, v103, v103
	v_mul_f32_e32 v189, v105, v105
	v_fmac_f32_e32 v188, v102, v102
	v_fmac_f32_e32 v189, v104, v104
	v_add_f32_e32 v188, v188, v189
	v_add_f32_e32 v223, v223, v188
	v_add_u32_e32 v220, 0x8100, v138
	global_store_dwordx2 v220, v[186:187], s[40:41]
	v_cvt_pk_bf16_f32 v190, v98, v99
	v_cvt_pk_bf16_f32 v191, v100, v101
	v_mul_f32_e32 v192, v99, v99
	v_mul_f32_e32 v193, v101, v101
	v_fmac_f32_e32 v192, v98, v98
	v_fmac_f32_e32 v193, v100, v100
	v_add_f32_e32 v192, v192, v193
	v_add_f32_e32 v223, v223, v192
	v_add_u32_e32 v221, 0x8120, v138
	global_store_dwordx2 v221, v[190:191], s[40:41]
	v_add_u32_e32 v218, 0x40000, v137
	global_load_dwordx2 v[172:173], v218, s[36:37]
	v_add_u32_e32 v219, 0x40020, v137
	global_load_dwordx2 v[182:183], v219, s[36:37]
	v_add_u32_e32 v220, 0x40100, v137
	global_load_dwordx2 v[186:187], v220, s[36:37]
	v_add_u32_e32 v221, 0x40120, v137
	global_load_dwordx2 v[190:191], v221, s[36:37]
	s_waitcnt vmcnt(16)
	v_lshlrev_b32_e32 v196, 16, v195
	v_and_b32_e32 v197, 0xffff0000, v195
	v_and_b32_e32 v195, 0xffff0000, v194
	v_lshlrev_b32_e32 v194, 16, v194
	v_pk_fma_f32 v[94:95], v[94:95], v[140:141], v[194:195]
	v_pk_fma_f32 v[96:97], v[96:97], v[142:143], v[196:197]
	v_lshlrev_b32_e32 v200, 16, v199
	v_and_b32_e32 v201, 0xffff0000, v199
	v_and_b32_e32 v199, 0xffff0000, v198
	v_lshlrev_b32_e32 v198, 16, v198
	v_pk_fma_f32 v[90:91], v[90:91], v[144:145], v[198:199]
	v_pk_fma_f32 v[92:93], v[92:93], v[146:147], v[200:201]
	v_lshlrev_b32_e32 v204, 16, v203
	v_and_b32_e32 v205, 0xffff0000, v203
	v_and_b32_e32 v203, 0xffff0000, v202
	v_lshlrev_b32_e32 v202, 16, v202
	v_pk_fma_f32 v[86:87], v[86:87], v[148:149], v[202:203]
	v_pk_fma_f32 v[88:89], v[88:89], v[150:151], v[204:205]
	v_lshlrev_b32_e32 v208, 16, v207
	v_and_b32_e32 v209, 0xffff0000, v207
	v_and_b32_e32 v207, 0xffff0000, v206
	v_lshlrev_b32_e32 v206, 16, v206
	v_pk_fma_f32 v[82:83], v[82:83], v[152:153], v[206:207]
	v_pk_fma_f32 v[84:85], v[84:85], v[154:155], v[208:209]
	v_cvt_pk_bf16_f32 v194, v94, v95
	v_cvt_pk_bf16_f32 v195, v96, v97
	v_mul_f32_e32 v196, v95, v95
	v_mul_f32_e32 v197, v97, v97
	v_fmac_f32_e32 v196, v94, v94
	v_fmac_f32_e32 v197, v96, v96
	v_add_f32_e32 v196, v196, v197
	v_add_f32_e32 v224, 0, v196
	v_add_u32_e32 v218, 0x10000, v138
	global_store_dwordx2 v218, v[194:195], s[40:41]
	v_cvt_pk_bf16_f32 v198, v90, v91
	v_cvt_pk_bf16_f32 v199, v92, v93
	v_mul_f32_e32 v200, v91, v91
	v_mul_f32_e32 v201, v93, v93
	v_fmac_f32_e32 v200, v90, v90
	v_fmac_f32_e32 v201, v92, v92
	v_add_f32_e32 v200, v200, v201
	v_add_f32_e32 v224, v224, v200
	v_add_u32_e32 v219, 0x10020, v138
	global_store_dwordx2 v219, v[198:199], s[40:41]
	v_cvt_pk_bf16_f32 v202, v86, v87
	v_cvt_pk_bf16_f32 v203, v88, v89
	v_mul_f32_e32 v204, v87, v87
	v_mul_f32_e32 v205, v89, v89
	v_fmac_f32_e32 v204, v86, v86
	v_fmac_f32_e32 v205, v88, v88
	v_add_f32_e32 v204, v204, v205
	v_add_f32_e32 v224, v224, v204
	v_add_u32_e32 v220, 0x10100, v138
	global_store_dwordx2 v220, v[202:203], s[40:41]
	v_cvt_pk_bf16_f32 v206, v82, v83
	v_cvt_pk_bf16_f32 v207, v84, v85
	v_mul_f32_e32 v208, v83, v83
	v_mul_f32_e32 v209, v85, v85
	v_fmac_f32_e32 v208, v82, v82
	v_fmac_f32_e32 v209, v84, v84
	v_add_f32_e32 v208, v208, v209
	v_add_f32_e32 v224, v224, v208
	v_add_u32_e32 v221, 0x10120, v138
	global_store_dwordx2 v221, v[206:207], s[40:41]
	v_add_u32_e32 v218, 0x48000, v137
	global_load_dwordx2 v[194:195], v218, s[36:37]
	v_add_u32_e32 v219, 0x48020, v137
	global_load_dwordx2 v[198:199], v219, s[36:37]
	v_add_u32_e32 v220, 0x48100, v137
	global_load_dwordx2 v[202:203], v220, s[36:37]
	v_add_u32_e32 v221, 0x48120, v137
	global_load_dwordx2 v[206:207], v221, s[36:37]
	s_waitcnt vmcnt(16)
	v_lshlrev_b32_e32 v158, 16, v157
	v_and_b32_e32 v159, 0xffff0000, v157
	v_and_b32_e32 v157, 0xffff0000, v156
	v_lshlrev_b32_e32 v156, 16, v156
	v_pk_fma_f32 v[78:79], v[78:79], v[140:141], v[156:157]
	v_pk_fma_f32 v[80:81], v[80:81], v[142:143], v[158:159]
	v_lshlrev_b32_e32 v162, 16, v161
	v_and_b32_e32 v163, 0xffff0000, v161
	v_and_b32_e32 v161, 0xffff0000, v160
	v_lshlrev_b32_e32 v160, 16, v160
	v_pk_fma_f32 v[74:75], v[74:75], v[144:145], v[160:161]
	v_pk_fma_f32 v[76:77], v[76:77], v[146:147], v[162:163]
	v_lshlrev_b32_e32 v166, 16, v165
	v_and_b32_e32 v167, 0xffff0000, v165
	v_and_b32_e32 v165, 0xffff0000, v164
	v_lshlrev_b32_e32 v164, 16, v164
	v_pk_fma_f32 v[70:71], v[70:71], v[148:149], v[164:165]
	v_pk_fma_f32 v[72:73], v[72:73], v[150:151], v[166:167]
	v_lshlrev_b32_e32 v170, 16, v169
	v_and_b32_e32 v171, 0xffff0000, v169
	v_and_b32_e32 v169, 0xffff0000, v168
	v_lshlrev_b32_e32 v168, 16, v168
	v_pk_fma_f32 v[66:67], v[66:67], v[152:153], v[168:169]
	v_pk_fma_f32 v[68:69], v[68:69], v[154:155], v[170:171]
	v_cvt_pk_bf16_f32 v156, v78, v79
	v_cvt_pk_bf16_f32 v157, v80, v81
	v_mul_f32_e32 v158, v79, v79
	v_mul_f32_e32 v159, v81, v81
	v_fmac_f32_e32 v158, v78, v78
	v_fmac_f32_e32 v159, v80, v80
	v_add_f32_e32 v158, v158, v159
	v_add_f32_e32 v225, 0, v158
	v_add_u32_e32 v218, 0x18000, v138
	global_store_dwordx2 v218, v[156:157], s[40:41]
	v_cvt_pk_bf16_f32 v160, v74, v75
	v_cvt_pk_bf16_f32 v161, v76, v77
	v_mul_f32_e32 v162, v75, v75
	v_mul_f32_e32 v163, v77, v77
	v_fmac_f32_e32 v162, v74, v74
	v_fmac_f32_e32 v163, v76, v76
	v_add_f32_e32 v162, v162, v163
	v_add_f32_e32 v225, v225, v162
	v_add_u32_e32 v219, 0x18020, v138
	global_store_dwordx2 v219, v[160:161], s[40:41]
	v_cvt_pk_bf16_f32 v164, v70, v71
	v_cvt_pk_bf16_f32 v165, v72, v73
	v_mul_f32_e32 v166, v71, v71
	v_mul_f32_e32 v167, v73, v73
	v_fmac_f32_e32 v166, v70, v70
	v_fmac_f32_e32 v167, v72, v72
	v_add_f32_e32 v166, v166, v167
	v_add_f32_e32 v225, v225, v166
	v_add_u32_e32 v220, 0x18100, v138
	global_store_dwordx2 v220, v[164:165], s[40:41]
	v_cvt_pk_bf16_f32 v168, v66, v67
	v_cvt_pk_bf16_f32 v169, v68, v69
	v_mul_f32_e32 v170, v67, v67
	v_mul_f32_e32 v171, v69, v69
	v_fmac_f32_e32 v170, v66, v66
	v_fmac_f32_e32 v171, v68, v68
	v_add_f32_e32 v170, v170, v171
	v_add_f32_e32 v225, v225, v170
	v_add_u32_e32 v221, 0x18120, v138
	global_store_dwordx2 v221, v[168:169], s[40:41]
	v_add_u32_e32 v218, 0x50000, v137
	global_load_dwordx2 v[156:157], v218, s[36:37]
	v_add_u32_e32 v219, 0x50020, v137
	global_load_dwordx2 v[160:161], v219, s[36:37]
	v_add_u32_e32 v220, 0x50100, v137
	global_load_dwordx2 v[164:165], v220, s[36:37]
	v_add_u32_e32 v221, 0x50120, v137
	global_load_dwordx2 v[168:169], v221, s[36:37]
	s_waitcnt vmcnt(16)
	v_lshlrev_b32_e32 v174, 16, v173
	v_and_b32_e32 v175, 0xffff0000, v173
	v_and_b32_e32 v173, 0xffff0000, v172
	v_lshlrev_b32_e32 v172, 16, v172
	v_pk_fma_f32 v[62:63], v[62:63], v[140:141], v[172:173]
	v_pk_fma_f32 v[64:65], v[64:65], v[142:143], v[174:175]
	v_lshlrev_b32_e32 v184, 16, v183
	v_and_b32_e32 v185, 0xffff0000, v183
	v_and_b32_e32 v183, 0xffff0000, v182
	v_lshlrev_b32_e32 v182, 16, v182
	v_pk_fma_f32 v[58:59], v[58:59], v[144:145], v[182:183]
	v_pk_fma_f32 v[60:61], v[60:61], v[146:147], v[184:185]
	v_lshlrev_b32_e32 v188, 16, v187
	v_and_b32_e32 v189, 0xffff0000, v187
	v_and_b32_e32 v187, 0xffff0000, v186
	v_lshlrev_b32_e32 v186, 16, v186
	v_pk_fma_f32 v[54:55], v[54:55], v[148:149], v[186:187]
	v_pk_fma_f32 v[56:57], v[56:57], v[150:151], v[188:189]
	v_lshlrev_b32_e32 v192, 16, v191
	v_and_b32_e32 v193, 0xffff0000, v191
	v_and_b32_e32 v191, 0xffff0000, v190
	v_lshlrev_b32_e32 v190, 16, v190
	v_pk_fma_f32 v[50:51], v[50:51], v[152:153], v[190:191]
	v_pk_fma_f32 v[52:53], v[52:53], v[154:155], v[192:193]
	v_cvt_pk_bf16_f32 v172, v62, v63
	v_cvt_pk_bf16_f32 v173, v64, v65
	v_mul_f32_e32 v174, v63, v63
	v_mul_f32_e32 v175, v65, v65
	v_fmac_f32_e32 v174, v62, v62
	v_fmac_f32_e32 v175, v64, v64
	v_add_f32_e32 v174, v174, v175
	v_add_f32_e32 v226, 0, v174
	v_add_u32_e32 v218, 0x40000, v138
	global_store_dwordx2 v218, v[172:173], s[40:41]
	v_cvt_pk_bf16_f32 v182, v58, v59
	v_cvt_pk_bf16_f32 v183, v60, v61
	v_mul_f32_e32 v184, v59, v59
	v_mul_f32_e32 v185, v61, v61
	v_fmac_f32_e32 v184, v58, v58
	v_fmac_f32_e32 v185, v60, v60
	v_add_f32_e32 v184, v184, v185
	v_add_f32_e32 v226, v226, v184
	v_add_u32_e32 v219, 0x40020, v138
	global_store_dwordx2 v219, v[182:183], s[40:41]
	v_cvt_pk_bf16_f32 v186, v54, v55
	v_cvt_pk_bf16_f32 v187, v56, v57
	v_mul_f32_e32 v188, v55, v55
	v_mul_f32_e32 v189, v57, v57
	v_fmac_f32_e32 v188, v54, v54
	v_fmac_f32_e32 v189, v56, v56
	v_add_f32_e32 v188, v188, v189
	v_add_f32_e32 v226, v226, v188
	v_add_u32_e32 v220, 0x40100, v138
	global_store_dwordx2 v220, v[186:187], s[40:41]
	v_cvt_pk_bf16_f32 v190, v50, v51
	v_cvt_pk_bf16_f32 v191, v52, v53
	v_mul_f32_e32 v192, v51, v51
	v_mul_f32_e32 v193, v53, v53
	v_fmac_f32_e32 v192, v50, v50
	v_fmac_f32_e32 v193, v52, v52
	v_add_f32_e32 v192, v192, v193
	v_add_f32_e32 v226, v226, v192
	v_add_u32_e32 v221, 0x40120, v138
	global_store_dwordx2 v221, v[190:191], s[40:41]
	v_add_u32_e32 v218, 0x58000, v137
	global_load_dwordx2 v[172:173], v218, s[36:37]
	v_add_u32_e32 v219, 0x58020, v137
	global_load_dwordx2 v[182:183], v219, s[36:37]
	v_add_u32_e32 v220, 0x58100, v137
	global_load_dwordx2 v[186:187], v220, s[36:37]
	v_add_u32_e32 v221, 0x58120, v137
	global_load_dwordx2 v[190:191], v221, s[36:37]
	s_waitcnt vmcnt(16)
	v_lshlrev_b32_e32 v196, 16, v195
	v_and_b32_e32 v197, 0xffff0000, v195
	v_and_b32_e32 v195, 0xffff0000, v194
	v_lshlrev_b32_e32 v194, 16, v194
	v_pk_fma_f32 v[46:47], v[46:47], v[140:141], v[194:195]
	v_pk_fma_f32 v[48:49], v[48:49], v[142:143], v[196:197]
	v_lshlrev_b32_e32 v200, 16, v199
	v_and_b32_e32 v201, 0xffff0000, v199
	v_and_b32_e32 v199, 0xffff0000, v198
	v_lshlrev_b32_e32 v198, 16, v198
	v_pk_fma_f32 v[42:43], v[42:43], v[144:145], v[198:199]
	v_pk_fma_f32 v[44:45], v[44:45], v[146:147], v[200:201]
	v_lshlrev_b32_e32 v204, 16, v203
	v_and_b32_e32 v205, 0xffff0000, v203
	v_and_b32_e32 v203, 0xffff0000, v202
	v_lshlrev_b32_e32 v202, 16, v202
	v_pk_fma_f32 v[38:39], v[38:39], v[148:149], v[202:203]
	v_pk_fma_f32 v[40:41], v[40:41], v[150:151], v[204:205]
	v_lshlrev_b32_e32 v208, 16, v207
	v_and_b32_e32 v209, 0xffff0000, v207
	v_and_b32_e32 v207, 0xffff0000, v206
	v_lshlrev_b32_e32 v206, 16, v206
	v_pk_fma_f32 v[34:35], v[34:35], v[152:153], v[206:207]
	v_pk_fma_f32 v[36:37], v[36:37], v[154:155], v[208:209]
	v_cvt_pk_bf16_f32 v194, v46, v47
	v_cvt_pk_bf16_f32 v195, v48, v49
	v_mul_f32_e32 v196, v47, v47
	v_mul_f32_e32 v197, v49, v49
	v_fmac_f32_e32 v196, v46, v46
	v_fmac_f32_e32 v197, v48, v48
	v_add_f32_e32 v196, v196, v197
	v_add_f32_e32 v216, 0, v196
	v_add_u32_e32 v218, 0x48000, v138
	global_store_dwordx2 v218, v[194:195], s[40:41]
	v_cvt_pk_bf16_f32 v198, v42, v43
	v_cvt_pk_bf16_f32 v199, v44, v45
	v_mul_f32_e32 v200, v43, v43
	v_mul_f32_e32 v201, v45, v45
	v_fmac_f32_e32 v200, v42, v42
	v_fmac_f32_e32 v201, v44, v44
	v_add_f32_e32 v200, v200, v201
	v_add_f32_e32 v216, v216, v200
	v_add_u32_e32 v219, 0x48020, v138
	global_store_dwordx2 v219, v[198:199], s[40:41]
	v_cvt_pk_bf16_f32 v202, v38, v39
	v_cvt_pk_bf16_f32 v203, v40, v41
	v_mul_f32_e32 v204, v39, v39
	v_mul_f32_e32 v205, v41, v41
	v_fmac_f32_e32 v204, v38, v38
	v_fmac_f32_e32 v205, v40, v40
	v_add_f32_e32 v204, v204, v205
	v_add_f32_e32 v216, v216, v204
	v_add_u32_e32 v220, 0x48100, v138
	global_store_dwordx2 v220, v[202:203], s[40:41]
	v_cvt_pk_bf16_f32 v206, v34, v35
	v_cvt_pk_bf16_f32 v207, v36, v37
	v_mul_f32_e32 v208, v35, v35
	v_mul_f32_e32 v209, v37, v37
	v_fmac_f32_e32 v208, v34, v34
	v_fmac_f32_e32 v209, v36, v36
	v_add_f32_e32 v208, v208, v209
	v_add_f32_e32 v216, v216, v208
	v_add_u32_e32 v221, 0x48120, v138
	global_store_dwordx2 v221, v[206:207], s[40:41]
	s_waitcnt vmcnt(12)
	v_lshlrev_b32_e32 v158, 16, v157
	v_and_b32_e32 v159, 0xffff0000, v157
	v_and_b32_e32 v157, 0xffff0000, v156
	v_lshlrev_b32_e32 v156, 16, v156
	v_pk_fma_f32 v[30:31], v[30:31], v[140:141], v[156:157]
	v_pk_fma_f32 v[32:33], v[32:33], v[142:143], v[158:159]
	v_lshlrev_b32_e32 v162, 16, v161
	v_and_b32_e32 v163, 0xffff0000, v161
	v_and_b32_e32 v161, 0xffff0000, v160
	v_lshlrev_b32_e32 v160, 16, v160
	v_pk_fma_f32 v[26:27], v[26:27], v[144:145], v[160:161]
	v_pk_fma_f32 v[28:29], v[28:29], v[146:147], v[162:163]
	v_lshlrev_b32_e32 v166, 16, v165
	v_and_b32_e32 v167, 0xffff0000, v165
	v_and_b32_e32 v165, 0xffff0000, v164
	v_lshlrev_b32_e32 v164, 16, v164
	v_pk_fma_f32 v[22:23], v[22:23], v[148:149], v[164:165]
	v_pk_fma_f32 v[24:25], v[24:25], v[150:151], v[166:167]
	v_lshlrev_b32_e32 v170, 16, v169
	v_and_b32_e32 v171, 0xffff0000, v169
	v_and_b32_e32 v169, 0xffff0000, v168
	v_lshlrev_b32_e32 v168, 16, v168
	v_pk_fma_f32 v[18:19], v[18:19], v[152:153], v[168:169]
	v_pk_fma_f32 v[20:21], v[20:21], v[154:155], v[170:171]
	v_cvt_pk_bf16_f32 v156, v30, v31
	v_cvt_pk_bf16_f32 v157, v32, v33
	v_mul_f32_e32 v158, v31, v31
	v_mul_f32_e32 v159, v33, v33
	v_fmac_f32_e32 v158, v30, v30
	v_fmac_f32_e32 v159, v32, v32
	v_add_f32_e32 v158, v158, v159
	v_add_f32_e32 v217, 0, v158
	v_add_u32_e32 v218, 0x50000, v138
	global_store_dwordx2 v218, v[156:157], s[40:41]
	v_cvt_pk_bf16_f32 v160, v26, v27
	v_cvt_pk_bf16_f32 v161, v28, v29
	v_mul_f32_e32 v162, v27, v27
	v_mul_f32_e32 v163, v29, v29
	v_fmac_f32_e32 v162, v26, v26
	v_fmac_f32_e32 v163, v28, v28
	v_add_f32_e32 v162, v162, v163
	v_add_f32_e32 v217, v217, v162
	v_add_u32_e32 v219, 0x50020, v138
	global_store_dwordx2 v219, v[160:161], s[40:41]
	v_cvt_pk_bf16_f32 v164, v22, v23
	v_cvt_pk_bf16_f32 v165, v24, v25
	v_mul_f32_e32 v166, v23, v23
	v_mul_f32_e32 v167, v25, v25
	v_fmac_f32_e32 v166, v22, v22
	v_fmac_f32_e32 v167, v24, v24
	v_add_f32_e32 v166, v166, v167
	v_add_f32_e32 v217, v217, v166
	v_add_u32_e32 v220, 0x50100, v138
	global_store_dwordx2 v220, v[164:165], s[40:41]
	v_cvt_pk_bf16_f32 v168, v18, v19
	v_cvt_pk_bf16_f32 v169, v20, v21
	v_mul_f32_e32 v170, v19, v19
	v_mul_f32_e32 v171, v21, v21
	v_fmac_f32_e32 v170, v18, v18
	v_fmac_f32_e32 v171, v20, v20
	v_add_f32_e32 v170, v170, v171
	v_add_f32_e32 v217, v217, v170
	v_add_u32_e32 v221, 0x50120, v138
	global_store_dwordx2 v221, v[168:169], s[40:41]
	s_waitcnt vmcnt(8)
	v_lshlrev_b32_e32 v174, 16, v173
	v_and_b32_e32 v175, 0xffff0000, v173
	v_and_b32_e32 v173, 0xffff0000, v172
	v_lshlrev_b32_e32 v172, 16, v172
	v_pk_fma_f32 v[14:15], v[14:15], v[140:141], v[172:173]
	v_pk_fma_f32 v[16:17], v[16:17], v[142:143], v[174:175]
	v_lshlrev_b32_e32 v184, 16, v183
	v_and_b32_e32 v185, 0xffff0000, v183
	v_and_b32_e32 v183, 0xffff0000, v182
	v_lshlrev_b32_e32 v182, 16, v182
	v_pk_fma_f32 v[10:11], v[10:11], v[144:145], v[182:183]
	v_pk_fma_f32 v[12:13], v[12:13], v[146:147], v[184:185]
	v_lshlrev_b32_e32 v188, 16, v187
	v_and_b32_e32 v189, 0xffff0000, v187
	v_and_b32_e32 v187, 0xffff0000, v186
	v_lshlrev_b32_e32 v186, 16, v186
	v_pk_fma_f32 v[6:7], v[6:7], v[148:149], v[186:187]
	v_pk_fma_f32 v[8:9], v[8:9], v[150:151], v[188:189]
	v_lshlrev_b32_e32 v192, 16, v191
	v_and_b32_e32 v193, 0xffff0000, v191
	v_and_b32_e32 v191, 0xffff0000, v190
	v_lshlrev_b32_e32 v190, 16, v190
	v_pk_fma_f32 v[2:3], v[2:3], v[152:153], v[190:191]
	v_pk_fma_f32 v[4:5], v[4:5], v[154:155], v[192:193]
	v_cvt_pk_bf16_f32 v172, v14, v15
	v_cvt_pk_bf16_f32 v173, v16, v17
	v_mul_f32_e32 v174, v15, v15
	v_mul_f32_e32 v175, v17, v17
	v_fmac_f32_e32 v174, v14, v14
	v_fmac_f32_e32 v175, v16, v16
	v_add_f32_e32 v174, v174, v175
	v_add_f32_e32 v212, 0, v174
	v_add_u32_e32 v218, 0x58000, v138
	global_store_dwordx2 v218, v[172:173], s[40:41]
	v_cvt_pk_bf16_f32 v182, v10, v11
	v_cvt_pk_bf16_f32 v183, v12, v13
	v_mul_f32_e32 v184, v11, v11
	v_mul_f32_e32 v185, v13, v13
	v_fmac_f32_e32 v184, v10, v10
	v_fmac_f32_e32 v185, v12, v12
	v_add_f32_e32 v184, v184, v185
	v_add_f32_e32 v212, v212, v184
	v_add_u32_e32 v219, 0x58020, v138
	global_store_dwordx2 v219, v[182:183], s[40:41]
	v_cvt_pk_bf16_f32 v186, v6, v7
	v_cvt_pk_bf16_f32 v187, v8, v9
	v_mul_f32_e32 v188, v7, v7
	v_mul_f32_e32 v189, v9, v9
	v_fmac_f32_e32 v188, v6, v6
	v_fmac_f32_e32 v189, v8, v8
	v_add_f32_e32 v188, v188, v189
	v_add_f32_e32 v212, v212, v188
	v_add_u32_e32 v220, 0x58100, v138
	global_store_dwordx2 v220, v[186:187], s[40:41]
	v_cvt_pk_bf16_f32 v190, v2, v3
	v_cvt_pk_bf16_f32 v191, v4, v5
	v_mul_f32_e32 v192, v3, v3
	v_mul_f32_e32 v193, v5, v5
	v_fmac_f32_e32 v192, v2, v2
	v_fmac_f32_e32 v193, v4, v4
	v_add_f32_e32 v192, v192, v193
	v_add_f32_e32 v212, v212, v192
	v_add_u32_e32 v221, 0x58120, v138
	global_store_dwordx2 v221, v[190:191], s[40:41]
	ds_bpermute_b32 v156, v213, v222
	ds_bpermute_b32 v157, v213, v223
	ds_bpermute_b32 v158, v213, v224
	ds_bpermute_b32 v159, v213, v225
	ds_bpermute_b32 v160, v213, v226
	ds_bpermute_b32 v161, v213, v216
	ds_bpermute_b32 v162, v213, v217
	ds_bpermute_b32 v163, v213, v212
	s_waitcnt lgkmcnt(0)
	v_add_f32_e32 v222, v222, v156
	v_add_f32_e32 v223, v223, v157
	v_add_f32_e32 v224, v224, v158
	v_add_f32_e32 v225, v225, v159
	v_add_f32_e32 v226, v226, v160
	v_add_f32_e32 v216, v216, v161
	v_add_f32_e32 v217, v217, v162
	v_add_f32_e32 v212, v212, v163
	ds_bpermute_b32 v156, v214, v222
	ds_bpermute_b32 v157, v214, v223
	ds_bpermute_b32 v158, v214, v224
	ds_bpermute_b32 v159, v214, v225
	ds_bpermute_b32 v160, v214, v226
	ds_bpermute_b32 v161, v214, v216
	ds_bpermute_b32 v162, v214, v217
	ds_bpermute_b32 v163, v214, v212
	s_waitcnt lgkmcnt(0)
	v_add_f32_e32 v222, v222, v156
	v_add_f32_e32 v223, v223, v157
	v_add_f32_e32 v224, v224, v158
	v_add_f32_e32 v225, v225, v159
	v_add_f32_e32 v226, v226, v160
	v_add_f32_e32 v216, v216, v161
	v_add_f32_e32 v217, v217, v162
	v_add_f32_e32 v212, v212, v163
	v_cmp_gt_u32_e32 vcc, 16, v227
	s_nop 3
	s_and_saveexec_b64 s[0:1], vcc
	ds_write_b32 v139, v222 offset:0
	ds_write_b32 v139, v223 offset:256
	ds_write_b32 v139, v224 offset:512
	ds_write_b32 v139, v225 offset:768
	ds_write_b32 v139, v226 offset:2048
	ds_write_b32 v139, v216 offset:2304
	ds_write_b32 v139, v217 offset:2560
	ds_write_b32 v139, v212 offset:2816
	s_or_b64 exec, exec, s[0:1]
	s_load_dwordx2 s[36:37], s[78:79], 0x58
	s_load_dwordx2 s[38:39], s[78:79], 0x1d0
	v_lshlrev_b32_e32 v137, 2, v135
	s_lshr_b32 s0, s26, 3
	s_mul_i32 s0, s0, 0xe000
	v_add_u32_e32 v138, s0, v137
	s_waitcnt lgkmcnt(0)
	v_add_u32_e32 v216, 0x1000, v137
	global_load_dwordx4 v[156:159], v216, s[36:37] offset:0
	global_load_dwordx4 v[160:163], v216, s[36:37] offset:64
	global_load_dwordx4 v[164:167], v216, s[36:37] offset:512
	global_load_dwordx4 v[168:171], v216, s[36:37] offset:576
	v_add_u32_e32 v217, 0x6000, v138
	global_load_dwordx4 v[172:175], v217, s[38:39] offset:0
	global_load_dwordx4 v[182:185], v217, s[38:39] offset:64
	global_load_dwordx4 v[186:189], v217, s[38:39] offset:512
	global_load_dwordx4 v[190:193], v217, s[38:39] offset:576
	v_add_u32_e32 v218, 0x7000, v138
	global_load_dwordx4 v[194:197], v218, s[38:39] offset:0
	global_load_dwordx4 v[198:201], v218, s[38:39] offset:64
	global_load_dwordx4 v[202:205], v218, s[38:39] offset:512
	global_load_dwordx4 v[206:209], v218, s[38:39] offset:576
	v_mov_b32_e32 v223, v134
	v_mov_b32_e32 v224, v135
	v_mov_b32_e32 v225, v136
	s_load_dwordx16 s[36:51], s[78:79], 0x140
	v_and_b32_e32 v138, 31, v248
	s_waitcnt vmcnt(0) lgkmcnt(0)
	s_barrier
	v_lshl_or_b32 v142, s3, 5, v138
	s_waitcnt lgkmcnt(0)
	s_add_u32 s4, s46, 0x40000
	v_add_u32_e32 v138, s18, v142
	s_addc_u32 s5, s47, 0
	v_cmp_gt_u32_e64 s[0:1], 32, v227
	v_ashrrev_i32_e32 v139, 31, v138
	s_and_saveexec_b64 s[6:7], s[0:1]
	s_cbranch_execz .LBB0_2569
	v_lshl_add_u32 v140, v142, 4, 0
	ds_read_b128 v[144:147], v140
	s_ashr_i32 s3, s2, 31
	v_lshl_add_u64 v[140:141], v[138:139], 4, s[4:5]
	v_lshl_add_u64 v[140:141], s[2:3], 2, v[140:141]
	s_waitcnt lgkmcnt(0)
	v_mov_b32_e32 v148, v145
	v_mov_b32_e32 v149, v146
	v_mov_b32_e32 v145, v147
	v_pk_add_f32 v[144:145], v[148:149], v[144:145]
	s_nop 0
	v_pk_add_f32 v[144:145], v[144:145], v[144:145] op_sel:[0,1] op_sel_hi:[1,0]
	global_store_dword v[140:141], v144, off sc1

.LBB0_2586:
	s_or_b64 exec, exec, s[2:3]
	s_waitcnt vmcnt(0) lgkmcnt(0)
	s_barrier
	v_lshlrev_b32_e32 v226, 2, v223
	ds_read_b32 v210, v226 offset:4096
	ds_read_b32 v211, v226 offset:4160
	ds_read_b32 v212, v226 offset:4224
	ds_read_b32 v213, v226 offset:4288
	ds_read_b32 v214, v226 offset:4608
	ds_read_b32 v215, v226 offset:4672
	ds_read_b32 v216, v226 offset:4736
	ds_read_b32 v217, v226 offset:4800
	s_load_dwordx2 s[36:37], s[78:79], 0x210
	v_lshlrev_b32_e32 v222, 11, v225
	v_lshl_add_u32 v222, v224, 1, v222
	v_add_f32_e32 v194, 1.0, v194
	v_add_f32_e32 v195, 1.0, v195
	v_add_f32_e32 v196, 1.0, v196
	v_add_f32_e32 v197, 1.0, v197
	v_add_f32_e32 v198, 1.0, v198
	v_add_f32_e32 v199, 1.0, v199
	v_add_f32_e32 v200, 1.0, v200
	v_add_f32_e32 v201, 1.0, v201
	v_add_f32_e32 v202, 1.0, v202
	v_add_f32_e32 v203, 1.0, v203
	v_add_f32_e32 v204, 1.0, v204
	v_add_f32_e32 v205, 1.0, v205
	v_add_f32_e32 v206, 1.0, v206
	v_add_f32_e32 v207, 1.0, v207
	v_add_f32_e32 v208, 1.0, v208
	v_add_f32_e32 v209, 1.0, v209
	s_waitcnt lgkmcnt(0)
	v_mul_f32_e32 v140, v126, v210
	v_mul_f32_e32 v141, v127, v210
	v_mul_f32_e32 v142, v128, v210
	v_mul_f32_e32 v143, v129, v210
	v_mul_f32_e32 v140, v140, v156
	v_mul_f32_e32 v141, v141, v157
	v_mul_f32_e32 v142, v142, v158
	v_mul_f32_e32 v143, v143, v159
	v_fma_f32 v140, v140, v194, v172
	v_fma_f32 v141, v141, v195, v173
	v_fma_f32 v142, v142, v196, v174
	v_fma_f32 v143, v143, v197, v175
	v_cvt_pk_bf16_f32 v140, v140, v141
	v_cvt_pk_bf16_f32 v141, v142, v143
	v_add_u32_e32 v148, 0x0, v222
	global_store_dwordx2 v148, v[140:141], s[36:37]
	v_mul_f32_e32 v144, v122, v210
	v_mul_f32_e32 v145, v123, v210
	v_mul_f32_e32 v146, v124, v210
	v_mul_f32_e32 v147, v125, v210
	v_mul_f32_e32 v144, v144, v160
	v_mul_f32_e32 v145, v145, v161
	v_mul_f32_e32 v146, v146, v162
	v_mul_f32_e32 v147, v147, v163
	v_fma_f32 v144, v144, v198, v182
	v_fma_f32 v145, v145, v199, v183
	v_fma_f32 v146, v146, v200, v184
	v_fma_f32 v147, v147, v201, v185
	v_cvt_pk_bf16_f32 v144, v144, v145
	v_cvt_pk_bf16_f32 v145, v146, v147
	v_add_u32_e32 v149, 0x20, v222
	global_store_dwordx2 v149, v[144:145], s[36:37]
	v_mul_f32_e32 v140, v118, v210
	v_mul_f32_e32 v141, v119, v210
	v_mul_f32_e32 v142, v120, v210
	v_mul_f32_e32 v143, v121, v210
	v_mul_f32_e32 v140, v140, v164
	v_mul_f32_e32 v141, v141, v165
	v_mul_f32_e32 v142, v142, v166
	v_mul_f32_e32 v143, v143, v167
	v_fma_f32 v140, v140, v202, v186
	v_fma_f32 v141, v141, v203, v187
	v_fma_f32 v142, v142, v204, v188
	v_fma_f32 v143, v143, v205, v189
	v_cvt_pk_bf16_f32 v140, v140, v141
	v_cvt_pk_bf16_f32 v141, v142, v143
	v_add_u32_e32 v150, 0x100, v222
	global_store_dwordx2 v150, v[140:141], s[36:37]
	v_mul_f32_e32 v144, v114, v210
	v_mul_f32_e32 v145, v115, v210
	v_mul_f32_e32 v146, v116, v210
	v_mul_f32_e32 v147, v117, v210
	v_mul_f32_e32 v144, v144, v168
	v_mul_f32_e32 v145, v145, v169
	v_mul_f32_e32 v146, v146, v170
	v_mul_f32_e32 v147, v147, v171
	v_fma_f32 v144, v144, v206, v190
	v_fma_f32 v145, v145, v207, v191
	v_fma_f32 v146, v146, v208, v192
	v_fma_f32 v147, v147, v209, v193
	v_cvt_pk_bf16_f32 v144, v144, v145
	v_cvt_pk_bf16_f32 v145, v146, v147
	v_add_u32_e32 v151, 0x120, v222
	global_store_dwordx2 v151, v[144:145], s[36:37]
	v_mul_f32_e32 v140, v110, v211
	v_mul_f32_e32 v141, v111, v211
	v_mul_f32_e32 v142, v112, v211
	v_mul_f32_e32 v143, v113, v211
	v_mul_f32_e32 v140, v140, v156
	v_mul_f32_e32 v141, v141, v157
	v_mul_f32_e32 v142, v142, v158
	v_mul_f32_e32 v143, v143, v159
	v_fma_f32 v140, v140, v194, v172
	v_fma_f32 v141, v141, v195, v173
	v_fma_f32 v142, v142, v196, v174
	v_fma_f32 v143, v143, v197, v175
	v_cvt_pk_bf16_f32 v140, v140, v141
	v_cvt_pk_bf16_f32 v141, v142, v143
	v_add_u32_e32 v148, 0x8000, v222
	global_store_dwordx2 v148, v[140:141], s[36:37]
	v_mul_f32_e32 v144, v106, v211
	v_mul_f32_e32 v145, v107, v211
	v_mul_f32_e32 v146, v108, v211
	v_mul_f32_e32 v147, v109, v211
	v_mul_f32_e32 v144, v144, v160
	v_mul_f32_e32 v145, v145, v161
	v_mul_f32_e32 v146, v146, v162
	v_mul_f32_e32 v147, v147, v163
	v_fma_f32 v144, v144, v198, v182
	v_fma_f32 v145, v145, v199, v183
	v_fma_f32 v146, v146, v200, v184
	v_fma_f32 v147, v147, v201, v185
	v_cvt_pk_bf16_f32 v144, v144, v145
	v_cvt_pk_bf16_f32 v145, v146, v147
	v_add_u32_e32 v149, 0x8020, v222
	global_store_dwordx2 v149, v[144:145], s[36:37]
	v_mul_f32_e32 v140, v102, v211
	v_mul_f32_e32 v141, v103, v211
	v_mul_f32_e32 v142, v104, v211
	v_mul_f32_e32 v143, v105, v211
	v_mul_f32_e32 v140, v140, v164
	v_mul_f32_e32 v141, v141, v165
	v_mul_f32_e32 v142, v142, v166
	v_mul_f32_e32 v143, v143, v167
	v_fma_f32 v140, v140, v202, v186
	v_fma_f32 v141, v141, v203, v187
	v_fma_f32 v142, v142, v204, v188
	v_fma_f32 v143, v143, v205, v189
	v_cvt_pk_bf16_f32 v140, v140, v141
	v_cvt_pk_bf16_f32 v141, v142, v143
	v_add_u32_e32 v150, 0x8100, v222
	global_store_dwordx2 v150, v[140:141], s[36:37]
	v_mul_f32_e32 v144, v98, v211
	v_mul_f32_e32 v145, v99, v211
	v_mul_f32_e32 v146, v100, v211
	v_mul_f32_e32 v147, v101, v211
	v_mul_f32_e32 v144, v144, v168
	v_mul_f32_e32 v145, v145, v169
	v_mul_f32_e32 v146, v146, v170
	v_mul_f32_e32 v147, v147, v171
	v_fma_f32 v144, v144, v206, v190
	v_fma_f32 v145, v145, v207, v191
	v_fma_f32 v146, v146, v208, v192
	v_fma_f32 v147, v147, v209, v193
	v_cvt_pk_bf16_f32 v144, v144, v145
	v_cvt_pk_bf16_f32 v145, v146, v147
	v_add_u32_e32 v151, 0x8120, v222
	global_store_dwordx2 v151, v[144:145], s[36:37]
	v_mul_f32_e32 v140, v94, v212
	v_mul_f32_e32 v141, v95, v212
	v_mul_f32_e32 v142, v96, v212
	v_mul_f32_e32 v143, v97, v212
	v_mul_f32_e32 v140, v140, v156
	v_mul_f32_e32 v141, v141, v157
	v_mul_f32_e32 v142, v142, v158
	v_mul_f32_e32 v143, v143, v159
	v_fma_f32 v140, v140, v194, v172
	v_fma_f32 v141, v141, v195, v173
	v_fma_f32 v142, v142, v196, v174
	v_fma_f32 v143, v143, v197, v175
	v_cvt_pk_bf16_f32 v140, v140, v141
	v_cvt_pk_bf16_f32 v141, v142, v143
	v_add_u32_e32 v148, 0x10000, v222
	global_store_dwordx2 v148, v[140:141], s[36:37]
	v_mul_f32_e32 v144, v90, v212
	v_mul_f32_e32 v145, v91, v212
	v_mul_f32_e32 v146, v92, v212
	v_mul_f32_e32 v147, v93, v212
	v_mul_f32_e32 v144, v144, v160
	v_mul_f32_e32 v145, v145, v161
	v_mul_f32_e32 v146, v146, v162
	v_mul_f32_e32 v147, v147, v163
	v_fma_f32 v144, v144, v198, v182
	v_fma_f32 v145, v145, v199, v183
	v_fma_f32 v146, v146, v200, v184
	v_fma_f32 v147, v147, v201, v185
	v_cvt_pk_bf16_f32 v144, v144, v145
	v_cvt_pk_bf16_f32 v145, v146, v147
	v_add_u32_e32 v149, 0x10020, v222
	global_store_dwordx2 v149, v[144:145], s[36:37]
	v_mul_f32_e32 v140, v86, v212
	v_mul_f32_e32 v141, v87, v212
	v_mul_f32_e32 v142, v88, v212
	v_mul_f32_e32 v143, v89, v212
	v_mul_f32_e32 v140, v140, v164
	v_mul_f32_e32 v141, v141, v165
	v_mul_f32_e32 v142, v142, v166
	v_mul_f32_e32 v143, v143, v167
	v_fma_f32 v140, v140, v202, v186
	v_fma_f32 v141, v141, v203, v187
	v_fma_f32 v142, v142, v204, v188
	v_fma_f32 v143, v143, v205, v189
	v_cvt_pk_bf16_f32 v140, v140, v141
	v_cvt_pk_bf16_f32 v141, v142, v143
	v_add_u32_e32 v150, 0x10100, v222
	global_store_dwordx2 v150, v[140:141], s[36:37]
	v_mul_f32_e32 v144, v82, v212
	v_mul_f32_e32 v145, v83, v212
	v_mul_f32_e32 v146, v84, v212
	v_mul_f32_e32 v147, v85, v212
	v_mul_f32_e32 v144, v144, v168
	v_mul_f32_e32 v145, v145, v169
	v_mul_f32_e32 v146, v146, v170
	v_mul_f32_e32 v147, v147, v171
	v_fma_f32 v144, v144, v206, v190
	v_fma_f32 v145, v145, v207, v191
	v_fma_f32 v146, v146, v208, v192
	v_fma_f32 v147, v147, v209, v193
	v_cvt_pk_bf16_f32 v144, v144, v145
	v_cvt_pk_bf16_f32 v145, v146, v147
	v_add_u32_e32 v151, 0x10120, v222
	global_store_dwordx2 v151, v[144:145], s[36:37]
	v_mul_f32_e32 v140, v78, v213
	v_mul_f32_e32 v141, v79, v213
	v_mul_f32_e32 v142, v80, v213
	v_mul_f32_e32 v143, v81, v213
	v_mul_f32_e32 v140, v140, v156
	v_mul_f32_e32 v141, v141, v157
	v_mul_f32_e32 v142, v142, v158
	v_mul_f32_e32 v143, v143, v159
	v_fma_f32 v140, v140, v194, v172
	v_fma_f32 v141, v141, v195, v173
	v_fma_f32 v142, v142, v196, v174
	v_fma_f32 v143, v143, v197, v175
	v_cvt_pk_bf16_f32 v140, v140, v141
	v_cvt_pk_bf16_f32 v141, v142, v143
	v_add_u32_e32 v148, 0x18000, v222
	global_store_dwordx2 v148, v[140:141], s[36:37]
	v_mul_f32_e32 v144, v74, v213
	v_mul_f32_e32 v145, v75, v213
	v_mul_f32_e32 v146, v76, v213
	v_mul_f32_e32 v147, v77, v213
	v_mul_f32_e32 v144, v144, v160
	v_mul_f32_e32 v145, v145, v161
	v_mul_f32_e32 v146, v146, v162
	v_mul_f32_e32 v147, v147, v163
	v_fma_f32 v144, v144, v198, v182
	v_fma_f32 v145, v145, v199, v183
	v_fma_f32 v146, v146, v200, v184
	v_fma_f32 v147, v147, v201, v185
	v_cvt_pk_bf16_f32 v144, v144, v145
	v_cvt_pk_bf16_f32 v145, v146, v147
	v_add_u32_e32 v149, 0x18020, v222
	global_store_dwordx2 v149, v[144:145], s[36:37]
	v_mul_f32_e32 v140, v70, v213
	v_mul_f32_e32 v141, v71, v213
	v_mul_f32_e32 v142, v72, v213
	v_mul_f32_e32 v143, v73, v213
	v_mul_f32_e32 v140, v140, v164
	v_mul_f32_e32 v141, v141, v165
	v_mul_f32_e32 v142, v142, v166
	v_mul_f32_e32 v143, v143, v167
	v_fma_f32 v140, v140, v202, v186
	v_fma_f32 v141, v141, v203, v187
	v_fma_f32 v142, v142, v204, v188
	v_fma_f32 v143, v143, v205, v189
	v_cvt_pk_bf16_f32 v140, v140, v141
	v_cvt_pk_bf16_f32 v141, v142, v143
	v_add_u32_e32 v150, 0x18100, v222
	global_store_dwordx2 v150, v[140:141], s[36:37]
	v_mul_f32_e32 v144, v66, v213
	v_mul_f32_e32 v145, v67, v213
	v_mul_f32_e32 v146, v68, v213
	v_mul_f32_e32 v147, v69, v213
	v_mul_f32_e32 v144, v144, v168
	v_mul_f32_e32 v145, v145, v169
	v_mul_f32_e32 v146, v146, v170
	v_mul_f32_e32 v147, v147, v171
	v_fma_f32 v144, v144, v206, v190
	v_fma_f32 v145, v145, v207, v191
	v_fma_f32 v146, v146, v208, v192
	v_fma_f32 v147, v147, v209, v193
	v_cvt_pk_bf16_f32 v144, v144, v145
	v_cvt_pk_bf16_f32 v145, v146, v147
	v_add_u32_e32 v151, 0x18120, v222
	global_store_dwordx2 v151, v[144:145], s[36:37]
	v_mul_f32_e32 v140, v62, v214
	v_mul_f32_e32 v141, v63, v214
	v_mul_f32_e32 v142, v64, v214
	v_mul_f32_e32 v143, v65, v214
	v_mul_f32_e32 v140, v140, v156
	v_mul_f32_e32 v141, v141, v157
	v_mul_f32_e32 v142, v142, v158
	v_mul_f32_e32 v143, v143, v159
	v_fma_f32 v140, v140, v194, v172
	v_fma_f32 v141, v141, v195, v173
	v_fma_f32 v142, v142, v196, v174
	v_fma_f32 v143, v143, v197, v175
	v_cvt_pk_bf16_f32 v140, v140, v141
	v_cvt_pk_bf16_f32 v141, v142, v143
	v_add_u32_e32 v148, 0x40000, v222
	global_store_dwordx2 v148, v[140:141], s[36:37]
	v_mul_f32_e32 v144, v58, v214
	v_mul_f32_e32 v145, v59, v214
	v_mul_f32_e32 v146, v60, v214
	v_mul_f32_e32 v147, v61, v214
	v_mul_f32_e32 v144, v144, v160
	v_mul_f32_e32 v145, v145, v161
	v_mul_f32_e32 v146, v146, v162
	v_mul_f32_e32 v147, v147, v163
	v_fma_f32 v144, v144, v198, v182
	v_fma_f32 v145, v145, v199, v183
	v_fma_f32 v146, v146, v200, v184
	v_fma_f32 v147, v147, v201, v185
	v_cvt_pk_bf16_f32 v144, v144, v145
	v_cvt_pk_bf16_f32 v145, v146, v147
	v_add_u32_e32 v149, 0x40020, v222
	global_store_dwordx2 v149, v[144:145], s[36:37]
	v_mul_f32_e32 v140, v54, v214
	v_mul_f32_e32 v141, v55, v214
	v_mul_f32_e32 v142, v56, v214
	v_mul_f32_e32 v143, v57, v214
	v_mul_f32_e32 v140, v140, v164
	v_mul_f32_e32 v141, v141, v165
	v_mul_f32_e32 v142, v142, v166
	v_mul_f32_e32 v143, v143, v167
	v_fma_f32 v140, v140, v202, v186
	v_fma_f32 v141, v141, v203, v187
	v_fma_f32 v142, v142, v204, v188
	v_fma_f32 v143, v143, v205, v189
	v_cvt_pk_bf16_f32 v140, v140, v141
	v_cvt_pk_bf16_f32 v141, v142, v143
	v_add_u32_e32 v150, 0x40100, v222
	global_store_dwordx2 v150, v[140:141], s[36:37]
	v_mul_f32_e32 v144, v50, v214
	v_mul_f32_e32 v145, v51, v214
	v_mul_f32_e32 v146, v52, v214
	v_mul_f32_e32 v147, v53, v214
	v_mul_f32_e32 v144, v144, v168
	v_mul_f32_e32 v145, v145, v169
	v_mul_f32_e32 v146, v146, v170
	v_mul_f32_e32 v147, v147, v171
	v_fma_f32 v144, v144, v206, v190
	v_fma_f32 v145, v145, v207, v191
	v_fma_f32 v146, v146, v208, v192
	v_fma_f32 v147, v147, v209, v193
	v_cvt_pk_bf16_f32 v144, v144, v145
	v_cvt_pk_bf16_f32 v145, v146, v147
	v_add_u32_e32 v151, 0x40120, v222
	global_store_dwordx2 v151, v[144:145], s[36:37]
	v_mul_f32_e32 v140, v46, v215
	v_mul_f32_e32 v141, v47, v215
	v_mul_f32_e32 v142, v48, v215
	v_mul_f32_e32 v143, v49, v215
	v_mul_f32_e32 v140, v140, v156
	v_mul_f32_e32 v141, v141, v157
	v_mul_f32_e32 v142, v142, v158
	v_mul_f32_e32 v143, v143, v159
	v_fma_f32 v140, v140, v194, v172
	v_fma_f32 v141, v141, v195, v173
	v_fma_f32 v142, v142, v196, v174
	v_fma_f32 v143, v143, v197, v175
	v_cvt_pk_bf16_f32 v140, v140, v141
	v_cvt_pk_bf16_f32 v141, v142, v143
	v_add_u32_e32 v148, 0x48000, v222
	global_store_dwordx2 v148, v[140:141], s[36:37]
	v_mul_f32_e32 v144, v42, v215
	v_mul_f32_e32 v145, v43, v215
	v_mul_f32_e32 v146, v44, v215
	v_mul_f32_e32 v147, v45, v215
	v_mul_f32_e32 v144, v144, v160
	v_mul_f32_e32 v145, v145, v161
	v_mul_f32_e32 v146, v146, v162
	v_mul_f32_e32 v147, v147, v163
	v_fma_f32 v144, v144, v198, v182
	v_fma_f32 v145, v145, v199, v183
	v_fma_f32 v146, v146, v200, v184
	v_fma_f32 v147, v147, v201, v185
	v_cvt_pk_bf16_f32 v144, v144, v145
	v_cvt_pk_bf16_f32 v145, v146, v147
	v_add_u32_e32 v149, 0x48020, v222
	global_store_dwordx2 v149, v[144:145], s[36:37]
	v_mul_f32_e32 v140, v38, v215
	v_mul_f32_e32 v141, v39, v215
	v_mul_f32_e32 v142, v40, v215
	v_mul_f32_e32 v143, v41, v215
	v_mul_f32_e32 v140, v140, v164
	v_mul_f32_e32 v141, v141, v165
	v_mul_f32_e32 v142, v142, v166
	v_mul_f32_e32 v143, v143, v167
	v_fma_f32 v140, v140, v202, v186
	v_fma_f32 v141, v141, v203, v187
	v_fma_f32 v142, v142, v204, v188
	v_fma_f32 v143, v143, v205, v189
	v_cvt_pk_bf16_f32 v140, v140, v141
	v_cvt_pk_bf16_f32 v141, v142, v143
	v_add_u32_e32 v150, 0x48100, v222
	global_store_dwordx2 v150, v[140:141], s[36:37]
	v_mul_f32_e32 v144, v34, v215
	v_mul_f32_e32 v145, v35, v215
	v_mul_f32_e32 v146, v36, v215
	v_mul_f32_e32 v147, v37, v215
	v_mul_f32_e32 v144, v144, v168
	v_mul_f32_e32 v145, v145, v169
	v_mul_f32_e32 v146, v146, v170
	v_mul_f32_e32 v147, v147, v171
	v_fma_f32 v144, v144, v206, v190
	v_fma_f32 v145, v145, v207, v191
	v_fma_f32 v146, v146, v208, v192
	v_fma_f32 v147, v147, v209, v193
	v_cvt_pk_bf16_f32 v144, v144, v145
	v_cvt_pk_bf16_f32 v145, v146, v147
	v_add_u32_e32 v151, 0x48120, v222
	global_store_dwordx2 v151, v[144:145], s[36:37]
	v_mul_f32_e32 v140, v30, v216
	v_mul_f32_e32 v141, v31, v216
	v_mul_f32_e32 v142, v32, v216
	v_mul_f32_e32 v143, v33, v216
	v_mul_f32_e32 v140, v140, v156
	v_mul_f32_e32 v141, v141, v157
	v_mul_f32_e32 v142, v142, v158
	v_mul_f32_e32 v143, v143, v159
	v_fma_f32 v140, v140, v194, v172
	v_fma_f32 v141, v141, v195, v173
	v_fma_f32 v142, v142, v196, v174
	v_fma_f32 v143, v143, v197, v175
	v_cvt_pk_bf16_f32 v140, v140, v141
	v_cvt_pk_bf16_f32 v141, v142, v143
	v_add_u32_e32 v148, 0x50000, v222
	global_store_dwordx2 v148, v[140:141], s[36:37]
	v_mul_f32_e32 v144, v26, v216
	v_mul_f32_e32 v145, v27, v216
	v_mul_f32_e32 v146, v28, v216
	v_mul_f32_e32 v147, v29, v216
	v_mul_f32_e32 v144, v144, v160
	v_mul_f32_e32 v145, v145, v161
	v_mul_f32_e32 v146, v146, v162
	v_mul_f32_e32 v147, v147, v163
	v_fma_f32 v144, v144, v198, v182
	v_fma_f32 v145, v145, v199, v183
	v_fma_f32 v146, v146, v200, v184
	v_fma_f32 v147, v147, v201, v185
	v_cvt_pk_bf16_f32 v144, v144, v145
	v_cvt_pk_bf16_f32 v145, v146, v147
	v_add_u32_e32 v149, 0x50020, v222
	global_store_dwordx2 v149, v[144:145], s[36:37]
	v_mul_f32_e32 v140, v22, v216
	v_mul_f32_e32 v141, v23, v216
	v_mul_f32_e32 v142, v24, v216
	v_mul_f32_e32 v143, v25, v216
	v_mul_f32_e32 v140, v140, v164
	v_mul_f32_e32 v141, v141, v165
	v_mul_f32_e32 v142, v142, v166
	v_mul_f32_e32 v143, v143, v167
	v_fma_f32 v140, v140, v202, v186
	v_fma_f32 v141, v141, v203, v187
	v_fma_f32 v142, v142, v204, v188
	v_fma_f32 v143, v143, v205, v189
	v_cvt_pk_bf16_f32 v140, v140, v141
	v_cvt_pk_bf16_f32 v141, v142, v143
	v_add_u32_e32 v150, 0x50100, v222
	global_store_dwordx2 v150, v[140:141], s[36:37]
	v_mul_f32_e32 v144, v18, v216
	v_mul_f32_e32 v145, v19, v216
	v_mul_f32_e32 v146, v20, v216
	v_mul_f32_e32 v147, v21, v216
	v_mul_f32_e32 v144, v144, v168
	v_mul_f32_e32 v145, v145, v169
	v_mul_f32_e32 v146, v146, v170
	v_mul_f32_e32 v147, v147, v171
	v_fma_f32 v144, v144, v206, v190
	v_fma_f32 v145, v145, v207, v191
	v_fma_f32 v146, v146, v208, v192
	v_fma_f32 v147, v147, v209, v193
	v_cvt_pk_bf16_f32 v144, v144, v145
	v_cvt_pk_bf16_f32 v145, v146, v147
	v_add_u32_e32 v151, 0x50120, v222
	global_store_dwordx2 v151, v[144:145], s[36:37]
	v_mul_f32_e32 v140, v14, v217
	v_mul_f32_e32 v141, v15, v217
	v_mul_f32_e32 v142, v16, v217
	v_mul_f32_e32 v143, v17, v217
	v_mul_f32_e32 v140, v140, v156
	v_mul_f32_e32 v141, v141, v157
	v_mul_f32_e32 v142, v142, v158
	v_mul_f32_e32 v143, v143, v159
	v_fma_f32 v140, v140, v194, v172
	v_fma_f32 v141, v141, v195, v173
	v_fma_f32 v142, v142, v196, v174
	v_fma_f32 v143, v143, v197, v175
	v_cvt_pk_bf16_f32 v140, v140, v141
	v_cvt_pk_bf16_f32 v141, v142, v143
	v_add_u32_e32 v148, 0x58000, v222
	global_store_dwordx2 v148, v[140:141], s[36:37]
	v_mul_f32_e32 v144, v10, v217
	v_mul_f32_e32 v145, v11, v217
	v_mul_f32_e32 v146, v12, v217
	v_mul_f32_e32 v147, v13, v217
	v_mul_f32_e32 v144, v144, v160
	v_mul_f32_e32 v145, v145, v161
	v_mul_f32_e32 v146, v146, v162
	v_mul_f32_e32 v147, v147, v163
	v_fma_f32 v144, v144, v198, v182
	v_fma_f32 v145, v145, v199, v183
	v_fma_f32 v146, v146, v200, v184
	v_fma_f32 v147, v147, v201, v185
	v_cvt_pk_bf16_f32 v144, v144, v145
	v_cvt_pk_bf16_f32 v145, v146, v147
	v_add_u32_e32 v149, 0x58020, v222
	global_store_dwordx2 v149, v[144:145], s[36:37]
	v_mul_f32_e32 v140, v6, v217
	v_mul_f32_e32 v141, v7, v217
	v_mul_f32_e32 v142, v8, v217
	v_mul_f32_e32 v143, v9, v217
	v_mul_f32_e32 v140, v140, v164
	v_mul_f32_e32 v141, v141, v165
	v_mul_f32_e32 v142, v142, v166
	v_mul_f32_e32 v143, v143, v167
	v_fma_f32 v140, v140, v202, v186
	v_fma_f32 v141, v141, v203, v187
	v_fma_f32 v142, v142, v204, v188
	v_fma_f32 v143, v143, v205, v189
	v_cvt_pk_bf16_f32 v140, v140, v141
	v_cvt_pk_bf16_f32 v141, v142, v143
	v_add_u32_e32 v150, 0x58100, v222
	global_store_dwordx2 v150, v[140:141], s[36:37]
	v_mul_f32_e32 v144, v2, v217
	v_mul_f32_e32 v145, v3, v217
	v_mul_f32_e32 v146, v4, v217
	v_mul_f32_e32 v147, v5, v217
	v_mul_f32_e32 v144, v144, v168
	v_mul_f32_e32 v145, v145, v169
	v_mul_f32_e32 v146, v146, v170
	v_mul_f32_e32 v147, v147, v171
	v_fma_f32 v144, v144, v206, v190
	v_fma_f32 v145, v145, v207, v191
	v_fma_f32 v146, v146, v208, v192
	v_fma_f32 v147, v147, v209, v193
	v_cvt_pk_bf16_f32 v144, v144, v145
	v_cvt_pk_bf16_f32 v145, v146, v147
	v_add_u32_e32 v151, 0x58120, v222
	global_store_dwordx2 v151, v[144:145], s[36:37]
	s_load_dwordx2 s[36:37], s[78:79], 0x218
	s_load_dwordx2 s[38:39], s[78:79], 0x98
	s_load_dwordx2 s[40:41], s[78:79], 0x1d0
	v_lshlrev_b32_e32 v218, 2, v224
	s_lshr_b32 s0, s26, 3
	s_mul_i32 s0, s0, 0xe000
	v_add_u32_e32 v219, s0, v218
	s_waitcnt lgkmcnt(0)
	v_add_u32_e32 v221, 0x0, v218
	global_load_dwordx4 v[156:159], v221, s[38:39] offset:0
	global_load_dwordx4 v[160:163], v221, s[38:39] offset:64
	global_load_dwordx4 v[164:167], v221, s[38:39] offset:512
	global_load_dwordx4 v[168:171], v221, s[38:39] offset:576
	v_add_u32_e32 v220, 0xc000, v219
	global_load_dwordx4 v[172:175], v220, s[40:41] offset:0
	global_load_dwordx4 v[182:185], v220, s[40:41] offset:64
	global_load_dwordx4 v[186:189], v220, s[40:41] offset:512
	global_load_dwordx4 v[190:193], v220, s[40:41] offset:576
	v_add_u32_e32 v221, 0xd000, v219
	global_load_dwordx4 v[194:197], v221, s[40:41] offset:0
	global_load_dwordx4 v[198:201], v221, s[40:41] offset:64
	global_load_dwordx4 v[202:205], v221, s[40:41] offset:512
	global_load_dwordx4 v[206:209], v221, s[40:41] offset:576
	s_waitcnt vmcnt(0)
	v_lshlrev_b32_e32 v222, 11, v225
	v_lshl_add_u32 v222, v224, 1, v222
	v_add_f32_e32 v194, 1.0, v194
	v_add_f32_e32 v195, 1.0, v195
	v_add_f32_e32 v196, 1.0, v196
	v_add_f32_e32 v197, 1.0, v197
	v_add_f32_e32 v198, 1.0, v198
	v_add_f32_e32 v199, 1.0, v199
	v_add_f32_e32 v200, 1.0, v200
	v_add_f32_e32 v201, 1.0, v201
	v_add_f32_e32 v202, 1.0, v202
	v_add_f32_e32 v203, 1.0, v203
	v_add_f32_e32 v204, 1.0, v204
	v_add_f32_e32 v205, 1.0, v205
	v_add_f32_e32 v206, 1.0, v206
	v_add_f32_e32 v207, 1.0, v207
	v_add_f32_e32 v208, 1.0, v208
	v_add_f32_e32 v209, 1.0, v209
	s_waitcnt lgkmcnt(0)
	v_mul_f32_e32 v140, v126, v210
	v_mul_f32_e32 v141, v127, v210
	v_mul_f32_e32 v142, v128, v210
	v_mul_f32_e32 v143, v129, v210
	v_mul_f32_e32 v140, v140, v156
	v_mul_f32_e32 v141, v141, v157
	v_mul_f32_e32 v142, v142, v158
	v_mul_f32_e32 v143, v143, v159
	v_fma_f32 v140, v140, v194, v172
	v_fma_f32 v141, v141, v195, v173
	v_fma_f32 v142, v142, v196, v174
	v_fma_f32 v143, v143, v197, v175
	v_cvt_pk_bf16_f32 v140, v140, v141
	v_cvt_pk_bf16_f32 v141, v142, v143
	v_add_u32_e32 v148, 0x0, v222
	global_store_dwordx2 v148, v[140:141], s[36:37]
	v_mul_f32_e32 v144, v122, v210
	v_mul_f32_e32 v145, v123, v210
	v_mul_f32_e32 v146, v124, v210
	v_mul_f32_e32 v147, v125, v210
	v_mul_f32_e32 v144, v144, v160
	v_mul_f32_e32 v145, v145, v161
	v_mul_f32_e32 v146, v146, v162
	v_mul_f32_e32 v147, v147, v163
	v_fma_f32 v144, v144, v198, v182
	v_fma_f32 v145, v145, v199, v183
	v_fma_f32 v146, v146, v200, v184
	v_fma_f32 v147, v147, v201, v185
	v_cvt_pk_bf16_f32 v144, v144, v145
	v_cvt_pk_bf16_f32 v145, v146, v147
	v_add_u32_e32 v149, 0x20, v222
	global_store_dwordx2 v149, v[144:145], s[36:37]
	v_mul_f32_e32 v140, v118, v210
	v_mul_f32_e32 v141, v119, v210
	v_mul_f32_e32 v142, v120, v210
	v_mul_f32_e32 v143, v121, v210
	v_mul_f32_e32 v140, v140, v164
	v_mul_f32_e32 v141, v141, v165
	v_mul_f32_e32 v142, v142, v166
	v_mul_f32_e32 v143, v143, v167
	v_fma_f32 v140, v140, v202, v186
	v_fma_f32 v141, v141, v203, v187
	v_fma_f32 v142, v142, v204, v188
	v_fma_f32 v143, v143, v205, v189
	v_cvt_pk_bf16_f32 v140, v140, v141
	v_cvt_pk_bf16_f32 v141, v142, v143
	v_add_u32_e32 v150, 0x100, v222
	global_store_dwordx2 v150, v[140:141], s[36:37]
	v_mul_f32_e32 v144, v114, v210
	v_mul_f32_e32 v145, v115, v210
	v_mul_f32_e32 v146, v116, v210
	v_mul_f32_e32 v147, v117, v210
	v_mul_f32_e32 v144, v144, v168
	v_mul_f32_e32 v145, v145, v169
	v_mul_f32_e32 v146, v146, v170
	v_mul_f32_e32 v147, v147, v171
	v_fma_f32 v144, v144, v206, v190
	v_fma_f32 v145, v145, v207, v191
	v_fma_f32 v146, v146, v208, v192
	v_fma_f32 v147, v147, v209, v193
	v_cvt_pk_bf16_f32 v144, v144, v145
	v_cvt_pk_bf16_f32 v145, v146, v147
	v_add_u32_e32 v151, 0x120, v222
	global_store_dwordx2 v151, v[144:145], s[36:37]
	v_mul_f32_e32 v140, v110, v211
	v_mul_f32_e32 v141, v111, v211
	v_mul_f32_e32 v142, v112, v211
	v_mul_f32_e32 v143, v113, v211
	v_mul_f32_e32 v140, v140, v156
	v_mul_f32_e32 v141, v141, v157
	v_mul_f32_e32 v142, v142, v158
	v_mul_f32_e32 v143, v143, v159
	v_fma_f32 v140, v140, v194, v172
	v_fma_f32 v141, v141, v195, v173
	v_fma_f32 v142, v142, v196, v174
	v_fma_f32 v143, v143, v197, v175
	v_cvt_pk_bf16_f32 v140, v140, v141
	v_cvt_pk_bf16_f32 v141, v142, v143
	v_add_u32_e32 v148, 0x8000, v222
	global_store_dwordx2 v148, v[140:141], s[36:37]
	v_mul_f32_e32 v144, v106, v211
	v_mul_f32_e32 v145, v107, v211
	v_mul_f32_e32 v146, v108, v211
	v_mul_f32_e32 v147, v109, v211
	v_mul_f32_e32 v144, v144, v160
	v_mul_f32_e32 v145, v145, v161
	v_mul_f32_e32 v146, v146, v162
	v_mul_f32_e32 v147, v147, v163
	v_fma_f32 v144, v144, v198, v182
	v_fma_f32 v145, v145, v199, v183
	v_fma_f32 v146, v146, v200, v184
	v_fma_f32 v147, v147, v201, v185
	v_cvt_pk_bf16_f32 v144, v144, v145
	v_cvt_pk_bf16_f32 v145, v146, v147
	v_add_u32_e32 v149, 0x8020, v222
	global_store_dwordx2 v149, v[144:145], s[36:37]
	v_mul_f32_e32 v140, v102, v211
	v_mul_f32_e32 v141, v103, v211
	v_mul_f32_e32 v142, v104, v211
	v_mul_f32_e32 v143, v105, v211
	v_mul_f32_e32 v140, v140, v164
	v_mul_f32_e32 v141, v141, v165
	v_mul_f32_e32 v142, v142, v166
	v_mul_f32_e32 v143, v143, v167
	v_fma_f32 v140, v140, v202, v186
	v_fma_f32 v141, v141, v203, v187
	v_fma_f32 v142, v142, v204, v188
	v_fma_f32 v143, v143, v205, v189
	v_cvt_pk_bf16_f32 v140, v140, v141
	v_cvt_pk_bf16_f32 v141, v142, v143
	v_add_u32_e32 v150, 0x8100, v222
	global_store_dwordx2 v150, v[140:141], s[36:37]
	v_mul_f32_e32 v144, v98, v211
	v_mul_f32_e32 v145, v99, v211
	v_mul_f32_e32 v146, v100, v211
	v_mul_f32_e32 v147, v101, v211
	v_mul_f32_e32 v144, v144, v168
	v_mul_f32_e32 v145, v145, v169
	v_mul_f32_e32 v146, v146, v170
	v_mul_f32_e32 v147, v147, v171
	v_fma_f32 v144, v144, v206, v190
	v_fma_f32 v145, v145, v207, v191
	v_fma_f32 v146, v146, v208, v192
	v_fma_f32 v147, v147, v209, v193
	v_cvt_pk_bf16_f32 v144, v144, v145
	v_cvt_pk_bf16_f32 v145, v146, v147
	v_add_u32_e32 v151, 0x8120, v222
	global_store_dwordx2 v151, v[144:145], s[36:37]
	v_mul_f32_e32 v140, v94, v212
	v_mul_f32_e32 v141, v95, v212
	v_mul_f32_e32 v142, v96, v212
	v_mul_f32_e32 v143, v97, v212
	v_mul_f32_e32 v140, v140, v156
	v_mul_f32_e32 v141, v141, v157
	v_mul_f32_e32 v142, v142, v158
	v_mul_f32_e32 v143, v143, v159
	v_fma_f32 v140, v140, v194, v172
	v_fma_f32 v141, v141, v195, v173
	v_fma_f32 v142, v142, v196, v174
	v_fma_f32 v143, v143, v197, v175
	v_cvt_pk_bf16_f32 v140, v140, v141
	v_cvt_pk_bf16_f32 v141, v142, v143
	v_add_u32_e32 v148, 0x10000, v222
	global_store_dwordx2 v148, v[140:141], s[36:37]
	v_mul_f32_e32 v144, v90, v212
	v_mul_f32_e32 v145, v91, v212
	v_mul_f32_e32 v146, v92, v212
	v_mul_f32_e32 v147, v93, v212
	v_mul_f32_e32 v144, v144, v160
	v_mul_f32_e32 v145, v145, v161
	v_mul_f32_e32 v146, v146, v162
	v_mul_f32_e32 v147, v147, v163
	v_fma_f32 v144, v144, v198, v182
	v_fma_f32 v145, v145, v199, v183
	v_fma_f32 v146, v146, v200, v184
	v_fma_f32 v147, v147, v201, v185
	v_cvt_pk_bf16_f32 v144, v144, v145
	v_cvt_pk_bf16_f32 v145, v146, v147
	v_add_u32_e32 v149, 0x10020, v222
	global_store_dwordx2 v149, v[144:145], s[36:37]
	v_mul_f32_e32 v140, v86, v212
	v_mul_f32_e32 v141, v87, v212
	v_mul_f32_e32 v142, v88, v212
	v_mul_f32_e32 v143, v89, v212
	v_mul_f32_e32 v140, v140, v164
	v_mul_f32_e32 v141, v141, v165
	v_mul_f32_e32 v142, v142, v166
	v_mul_f32_e32 v143, v143, v167
	v_fma_f32 v140, v140, v202, v186
	v_fma_f32 v141, v141, v203, v187
	v_fma_f32 v142, v142, v204, v188
	v_fma_f32 v143, v143, v205, v189
	v_cvt_pk_bf16_f32 v140, v140, v141
	v_cvt_pk_bf16_f32 v141, v142, v143
	v_add_u32_e32 v150, 0x10100, v222
	global_store_dwordx2 v150, v[140:141], s[36:37]
	v_mul_f32_e32 v144, v82, v212
	v_mul_f32_e32 v145, v83, v212
	v_mul_f32_e32 v146, v84, v212
	v_mul_f32_e32 v147, v85, v212
	v_mul_f32_e32 v144, v144, v168
	v_mul_f32_e32 v145, v145, v169
	v_mul_f32_e32 v146, v146, v170
	v_mul_f32_e32 v147, v147, v171
	v_fma_f32 v144, v144, v206, v190
	v_fma_f32 v145, v145, v207, v191
	v_fma_f32 v146, v146, v208, v192
	v_fma_f32 v147, v147, v209, v193
	v_cvt_pk_bf16_f32 v144, v144, v145
	v_cvt_pk_bf16_f32 v145, v146, v147
	v_add_u32_e32 v151, 0x10120, v222
	global_store_dwordx2 v151, v[144:145], s[36:37]
	v_mul_f32_e32 v140, v78, v213
	v_mul_f32_e32 v141, v79, v213
	v_mul_f32_e32 v142, v80, v213
	v_mul_f32_e32 v143, v81, v213
	v_mul_f32_e32 v140, v140, v156
	v_mul_f32_e32 v141, v141, v157
	v_mul_f32_e32 v142, v142, v158
	v_mul_f32_e32 v143, v143, v159
	v_fma_f32 v140, v140, v194, v172
	v_fma_f32 v141, v141, v195, v173
	v_fma_f32 v142, v142, v196, v174
	v_fma_f32 v143, v143, v197, v175
	v_cvt_pk_bf16_f32 v140, v140, v141
	v_cvt_pk_bf16_f32 v141, v142, v143
	v_add_u32_e32 v148, 0x18000, v222
	global_store_dwordx2 v148, v[140:141], s[36:37]
	v_mul_f32_e32 v144, v74, v213
	v_mul_f32_e32 v145, v75, v213
	v_mul_f32_e32 v146, v76, v213
	v_mul_f32_e32 v147, v77, v213
	v_mul_f32_e32 v144, v144, v160
	v_mul_f32_e32 v145, v145, v161
	v_mul_f32_e32 v146, v146, v162
	v_mul_f32_e32 v147, v147, v163
	v_fma_f32 v144, v144, v198, v182
	v_fma_f32 v145, v145, v199, v183
	v_fma_f32 v146, v146, v200, v184
	v_fma_f32 v147, v147, v201, v185
	v_cvt_pk_bf16_f32 v144, v144, v145
	v_cvt_pk_bf16_f32 v145, v146, v147
	v_add_u32_e32 v149, 0x18020, v222
	global_store_dwordx2 v149, v[144:145], s[36:37]
	v_mul_f32_e32 v140, v70, v213
	v_mul_f32_e32 v141, v71, v213
	v_mul_f32_e32 v142, v72, v213
	v_mul_f32_e32 v143, v73, v213
	v_mul_f32_e32 v140, v140, v164
	v_mul_f32_e32 v141, v141, v165
	v_mul_f32_e32 v142, v142, v166
	v_mul_f32_e32 v143, v143, v167
	v_fma_f32 v140, v140, v202, v186
	v_fma_f32 v141, v141, v203, v187
	v_fma_f32 v142, v142, v204, v188
	v_fma_f32 v143, v143, v205, v189
	v_cvt_pk_bf16_f32 v140, v140, v141
	v_cvt_pk_bf16_f32 v141, v142, v143
	v_add_u32_e32 v150, 0x18100, v222
	global_store_dwordx2 v150, v[140:141], s[36:37]
	v_mul_f32_e32 v144, v66, v213
	v_mul_f32_e32 v145, v67, v213
	v_mul_f32_e32 v146, v68, v213
	v_mul_f32_e32 v147, v69, v213
	v_mul_f32_e32 v144, v144, v168
	v_mul_f32_e32 v145, v145, v169
	v_mul_f32_e32 v146, v146, v170
	v_mul_f32_e32 v147, v147, v171
	v_fma_f32 v144, v144, v206, v190
	v_fma_f32 v145, v145, v207, v191
	v_fma_f32 v146, v146, v208, v192
	v_fma_f32 v147, v147, v209, v193
	v_cvt_pk_bf16_f32 v144, v144, v145
	v_cvt_pk_bf16_f32 v145, v146, v147
	v_add_u32_e32 v151, 0x18120, v222
	global_store_dwordx2 v151, v[144:145], s[36:37]
	v_mul_f32_e32 v140, v62, v214
	v_mul_f32_e32 v141, v63, v214
	v_mul_f32_e32 v142, v64, v214
	v_mul_f32_e32 v143, v65, v214
	v_mul_f32_e32 v140, v140, v156
	v_mul_f32_e32 v141, v141, v157
	v_mul_f32_e32 v142, v142, v158
	v_mul_f32_e32 v143, v143, v159
	v_fma_f32 v140, v140, v194, v172
	v_fma_f32 v141, v141, v195, v173
	v_fma_f32 v142, v142, v196, v174
	v_fma_f32 v143, v143, v197, v175
	v_cvt_pk_bf16_f32 v140, v140, v141
	v_cvt_pk_bf16_f32 v141, v142, v143
	v_add_u32_e32 v148, 0x40000, v222
	global_store_dwordx2 v148, v[140:141], s[36:37]
	v_mul_f32_e32 v144, v58, v214
	v_mul_f32_e32 v145, v59, v214
	v_mul_f32_e32 v146, v60, v214
	v_mul_f32_e32 v147, v61, v214
	v_mul_f32_e32 v144, v144, v160
	v_mul_f32_e32 v145, v145, v161
	v_mul_f32_e32 v146, v146, v162
	v_mul_f32_e32 v147, v147, v163
	v_fma_f32 v144, v144, v198, v182
	v_fma_f32 v145, v145, v199, v183
	v_fma_f32 v146, v146, v200, v184
	v_fma_f32 v147, v147, v201, v185
	v_cvt_pk_bf16_f32 v144, v144, v145
	v_cvt_pk_bf16_f32 v145, v146, v147
	v_add_u32_e32 v149, 0x40020, v222
	global_store_dwordx2 v149, v[144:145], s[36:37]
	v_mul_f32_e32 v140, v54, v214
	v_mul_f32_e32 v141, v55, v214
	v_mul_f32_e32 v142, v56, v214
	v_mul_f32_e32 v143, v57, v214
	v_mul_f32_e32 v140, v140, v164
	v_mul_f32_e32 v141, v141, v165
	v_mul_f32_e32 v142, v142, v166
	v_mul_f32_e32 v143, v143, v167
	v_fma_f32 v140, v140, v202, v186
	v_fma_f32 v141, v141, v203, v187
	v_fma_f32 v142, v142, v204, v188
	v_fma_f32 v143, v143, v205, v189
	v_cvt_pk_bf16_f32 v140, v140, v141
	v_cvt_pk_bf16_f32 v141, v142, v143
	v_add_u32_e32 v150, 0x40100, v222
	global_store_dwordx2 v150, v[140:141], s[36:37]
	v_mul_f32_e32 v144, v50, v214
	v_mul_f32_e32 v145, v51, v214
	v_mul_f32_e32 v146, v52, v214
	v_mul_f32_e32 v147, v53, v214
	v_mul_f32_e32 v144, v144, v168
	v_mul_f32_e32 v145, v145, v169
	v_mul_f32_e32 v146, v146, v170
	v_mul_f32_e32 v147, v147, v171
	v_fma_f32 v144, v144, v206, v190
	v_fma_f32 v145, v145, v207, v191
	v_fma_f32 v146, v146, v208, v192
	v_fma_f32 v147, v147, v209, v193
	v_cvt_pk_bf16_f32 v144, v144, v145
	v_cvt_pk_bf16_f32 v145, v146, v147
	v_add_u32_e32 v151, 0x40120, v222
	global_store_dwordx2 v151, v[144:145], s[36:37]
	v_mul_f32_e32 v140, v46, v215
	v_mul_f32_e32 v141, v47, v215
	v_mul_f32_e32 v142, v48, v215
	v_mul_f32_e32 v143, v49, v215
	v_mul_f32_e32 v140, v140, v156
	v_mul_f32_e32 v141, v141, v157
	v_mul_f32_e32 v142, v142, v158
	v_mul_f32_e32 v143, v143, v159
	v_fma_f32 v140, v140, v194, v172
	v_fma_f32 v141, v141, v195, v173
	v_fma_f32 v142, v142, v196, v174
	v_fma_f32 v143, v143, v197, v175
	v_cvt_pk_bf16_f32 v140, v140, v141
	v_cvt_pk_bf16_f32 v141, v142, v143
	v_add_u32_e32 v148, 0x48000, v222
	global_store_dwordx2 v148, v[140:141], s[36:37]
	v_mul_f32_e32 v144, v42, v215
	v_mul_f32_e32 v145, v43, v215
	v_mul_f32_e32 v146, v44, v215
	v_mul_f32_e32 v147, v45, v215
	v_mul_f32_e32 v144, v144, v160
	v_mul_f32_e32 v145, v145, v161
	v_mul_f32_e32 v146, v146, v162
	v_mul_f32_e32 v147, v147, v163
	v_fma_f32 v144, v144, v198, v182
	v_fma_f32 v145, v145, v199, v183
	v_fma_f32 v146, v146, v200, v184
	v_fma_f32 v147, v147, v201, v185
	v_cvt_pk_bf16_f32 v144, v144, v145
	v_cvt_pk_bf16_f32 v145, v146, v147
	v_add_u32_e32 v149, 0x48020, v222
	global_store_dwordx2 v149, v[144:145], s[36:37]
	v_mul_f32_e32 v140, v38, v215
	v_mul_f32_e32 v141, v39, v215
	v_mul_f32_e32 v142, v40, v215
	v_mul_f32_e32 v143, v41, v215
	v_mul_f32_e32 v140, v140, v164
	v_mul_f32_e32 v141, v141, v165
	v_mul_f32_e32 v142, v142, v166
	v_mul_f32_e32 v143, v143, v167
	v_fma_f32 v140, v140, v202, v186
	v_fma_f32 v141, v141, v203, v187
	v_fma_f32 v142, v142, v204, v188
	v_fma_f32 v143, v143, v205, v189
	v_cvt_pk_bf16_f32 v140, v140, v141
	v_cvt_pk_bf16_f32 v141, v142, v143
	v_add_u32_e32 v150, 0x48100, v222
	global_store_dwordx2 v150, v[140:141], s[36:37]
	v_mul_f32_e32 v144, v34, v215
	v_mul_f32_e32 v145, v35, v215
	v_mul_f32_e32 v146, v36, v215
	v_mul_f32_e32 v147, v37, v215
	v_mul_f32_e32 v144, v144, v168
	v_mul_f32_e32 v145, v145, v169
	v_mul_f32_e32 v146, v146, v170
	v_mul_f32_e32 v147, v147, v171
	v_fma_f32 v144, v144, v206, v190
	v_fma_f32 v145, v145, v207, v191
	v_fma_f32 v146, v146, v208, v192
	v_fma_f32 v147, v147, v209, v193
	v_cvt_pk_bf16_f32 v144, v144, v145
	v_cvt_pk_bf16_f32 v145, v146, v147
	v_add_u32_e32 v151, 0x48120, v222
	global_store_dwordx2 v151, v[144:145], s[36:37]
	v_mul_f32_e32 v140, v30, v216
	v_mul_f32_e32 v141, v31, v216
	v_mul_f32_e32 v142, v32, v216
	v_mul_f32_e32 v143, v33, v216
	v_mul_f32_e32 v140, v140, v156
	v_mul_f32_e32 v141, v141, v157
	v_mul_f32_e32 v142, v142, v158
	v_mul_f32_e32 v143, v143, v159
	v_fma_f32 v140, v140, v194, v172
	v_fma_f32 v141, v141, v195, v173
	v_fma_f32 v142, v142, v196, v174
	v_fma_f32 v143, v143, v197, v175
	v_cvt_pk_bf16_f32 v140, v140, v141
	v_cvt_pk_bf16_f32 v141, v142, v143
	v_add_u32_e32 v148, 0x50000, v222
	global_store_dwordx2 v148, v[140:141], s[36:37]
	v_mul_f32_e32 v144, v26, v216
	v_mul_f32_e32 v145, v27, v216
	v_mul_f32_e32 v146, v28, v216
	v_mul_f32_e32 v147, v29, v216
	v_mul_f32_e32 v144, v144, v160
	v_mul_f32_e32 v145, v145, v161
	v_mul_f32_e32 v146, v146, v162
	v_mul_f32_e32 v147, v147, v163
	v_fma_f32 v144, v144, v198, v182
	v_fma_f32 v145, v145, v199, v183
	v_fma_f32 v146, v146, v200, v184
	v_fma_f32 v147, v147, v201, v185
	v_cvt_pk_bf16_f32 v144, v144, v145
	v_cvt_pk_bf16_f32 v145, v146, v147
	v_add_u32_e32 v149, 0x50020, v222
	global_store_dwordx2 v149, v[144:145], s[36:37]
	v_mul_f32_e32 v140, v22, v216
	v_mul_f32_e32 v141, v23, v216
	v_mul_f32_e32 v142, v24, v216
	v_mul_f32_e32 v143, v25, v216
	v_mul_f32_e32 v140, v140, v164
	v_mul_f32_e32 v141, v141, v165
	v_mul_f32_e32 v142, v142, v166
	v_mul_f32_e32 v143, v143, v167
	v_fma_f32 v140, v140, v202, v186
	v_fma_f32 v141, v141, v203, v187
	v_fma_f32 v142, v142, v204, v188
	v_fma_f32 v143, v143, v205, v189
	v_cvt_pk_bf16_f32 v140, v140, v141
	v_cvt_pk_bf16_f32 v141, v142, v143
	v_add_u32_e32 v150, 0x50100, v222
	global_store_dwordx2 v150, v[140:141], s[36:37]
	v_mul_f32_e32 v144, v18, v216
	v_mul_f32_e32 v145, v19, v216
	v_mul_f32_e32 v146, v20, v216
	v_mul_f32_e32 v147, v21, v216
	v_mul_f32_e32 v144, v144, v168
	v_mul_f32_e32 v145, v145, v169
	v_mul_f32_e32 v146, v146, v170
	v_mul_f32_e32 v147, v147, v171
	v_fma_f32 v144, v144, v206, v190
	v_fma_f32 v145, v145, v207, v191
	v_fma_f32 v146, v146, v208, v192
	v_fma_f32 v147, v147, v209, v193
	v_cvt_pk_bf16_f32 v144, v144, v145
	v_cvt_pk_bf16_f32 v145, v146, v147
	v_add_u32_e32 v151, 0x50120, v222
	global_store_dwordx2 v151, v[144:145], s[36:37]
	v_mul_f32_e32 v140, v14, v217
	v_mul_f32_e32 v141, v15, v217
	v_mul_f32_e32 v142, v16, v217
	v_mul_f32_e32 v143, v17, v217
	v_mul_f32_e32 v140, v140, v156
	v_mul_f32_e32 v141, v141, v157
	v_mul_f32_e32 v142, v142, v158
	v_mul_f32_e32 v143, v143, v159
	v_fma_f32 v140, v140, v194, v172
	v_fma_f32 v141, v141, v195, v173
	v_fma_f32 v142, v142, v196, v174
	v_fma_f32 v143, v143, v197, v175
	v_cvt_pk_bf16_f32 v140, v140, v141
	v_cvt_pk_bf16_f32 v141, v142, v143
	v_add_u32_e32 v148, 0x58000, v222
	global_store_dwordx2 v148, v[140:141], s[36:37]
	v_mul_f32_e32 v144, v10, v217
	v_mul_f32_e32 v145, v11, v217
	v_mul_f32_e32 v146, v12, v217
	v_mul_f32_e32 v147, v13, v217
	v_mul_f32_e32 v144, v144, v160
	v_mul_f32_e32 v145, v145, v161
	v_mul_f32_e32 v146, v146, v162
	v_mul_f32_e32 v147, v147, v163
	v_fma_f32 v144, v144, v198, v182
	v_fma_f32 v145, v145, v199, v183
	v_fma_f32 v146, v146, v200, v184
	v_fma_f32 v147, v147, v201, v185
	v_cvt_pk_bf16_f32 v144, v144, v145
	v_cvt_pk_bf16_f32 v145, v146, v147
	v_add_u32_e32 v149, 0x58020, v222
	global_store_dwordx2 v149, v[144:145], s[36:37]
	v_mul_f32_e32 v140, v6, v217
	v_mul_f32_e32 v141, v7, v217
	v_mul_f32_e32 v142, v8, v217
	v_mul_f32_e32 v143, v9, v217
	v_mul_f32_e32 v140, v140, v164
	v_mul_f32_e32 v141, v141, v165
	v_mul_f32_e32 v142, v142, v166
	v_mul_f32_e32 v143, v143, v167
	v_fma_f32 v140, v140, v202, v186
	v_fma_f32 v141, v141, v203, v187
	v_fma_f32 v142, v142, v204, v188
	v_fma_f32 v143, v143, v205, v189
	v_cvt_pk_bf16_f32 v140, v140, v141
	v_cvt_pk_bf16_f32 v141, v142, v143
	v_add_u32_e32 v150, 0x58100, v222
	global_store_dwordx2 v150, v[140:141], s[36:37]
	v_mul_f32_e32 v144, v2, v217
	v_mul_f32_e32 v145, v3, v217
	v_mul_f32_e32 v146, v4, v217
	v_mul_f32_e32 v147, v5, v217
	v_mul_f32_e32 v144, v144, v168
	v_mul_f32_e32 v145, v145, v169
	v_mul_f32_e32 v146, v146, v170
	v_mul_f32_e32 v147, v147, v171
	v_fma_f32 v144, v144, v206, v190
	v_fma_f32 v145, v145, v207, v191
	v_fma_f32 v146, v146, v208, v192
	v_fma_f32 v147, v147, v209, v193
	v_cvt_pk_bf16_f32 v144, v144, v145
	v_cvt_pk_bf16_f32 v145, v146, v147
	v_add_u32_e32 v151, 0x58120, v222
	global_store_dwordx2 v151, v[144:145], s[36:37]
	s_branch .LBB0_2651

.LBB0_4573:
	s_lshl_b32 s18, s12, 8
	s_load_dwordx2 s[36:37], s[78:79], 0x1f8
	s_load_dwordx2 s[38:39], s[78:79], 0x1d0
	s_load_dwordx2 s[40:41], s[78:79], 0x1f8
	v_and_b32_e32 v130, 15, v248
	v_bfe_u32 v131, v248, 8, 1
	v_bfe_u32 v132, v248, 6, 2
	v_bfe_u32 v133, v248, 4, 2
	v_lshl_add_u32 v134, v131, 6, v130
	v_lshlrev_b32_e32 v135, 5, v132
	v_lshl_or_b32 v135, v133, 2, v135
	s_lshl_b32 s0, s2, 8
	v_add_u32_e32 v135, s0, v135
	s_lshl_b32 s0, s12, 8
	v_add_u32_e32 v136, s0, v134
	v_mul_u32_u24_e32 v137, 0x800, v136
	v_lshl_add_u32 v137, v135, 1, v137
	v_lshlrev_b32_e32 v138, 11, v136
	v_lshl_add_u32 v138, v135, 1, v138
	v_lshlrev_b32_e32 v139, 2, v134
	v_add_lshl_u32 v139, v139, v132, 2
	v_xor_b32_e32 v213, 16, v227
	v_lshlrev_b32_e32 v213, 2, v213
	v_xor_b32_e32 v214, 32, v227
	v_lshlrev_b32_e32 v214, 2, v214
	v_lshlrev_b32_e32 v215, 2, v135
	s_lshr_b32 s0, s12, 3
	s_mul_i32 s0, s0, 0xe000
	s_add_u32 s0, s0, 0x8000
	v_add_u32_e32 v215, s0, v215
	s_waitcnt lgkmcnt(0)
	global_load_dwordx4 v[140:143], v215, s[38:39] offset:0
	global_load_dwordx4 v[144:147], v215, s[38:39] offset:64
	global_load_dwordx4 v[148:151], v215, s[38:39] offset:512
	global_load_dwordx4 v[152:155], v215, s[38:39] offset:576
	v_add_u32_e32 v218, 0x0, v137
	global_load_dwordx2 v[156:157], v218, s[36:37]
	v_add_u32_e32 v219, 0x20, v137
	global_load_dwordx2 v[160:161], v219, s[36:37]
	v_add_u32_e32 v220, 0x100, v137
	global_load_dwordx2 v[164:165], v220, s[36:37]
	v_add_u32_e32 v221, 0x120, v137
	global_load_dwordx2 v[168:169], v221, s[36:37]
	v_add_u32_e32 v218, 0x8000, v137
	global_load_dwordx2 v[172:173], v218, s[36:37]
	v_add_u32_e32 v219, 0x8020, v137
	global_load_dwordx2 v[182:183], v219, s[36:37]
	v_add_u32_e32 v220, 0x8100, v137
	global_load_dwordx2 v[186:187], v220, s[36:37]
	v_add_u32_e32 v221, 0x8120, v137
	global_load_dwordx2 v[190:191], v221, s[36:37]
	v_add_u32_e32 v218, 0x10000, v137
	global_load_dwordx2 v[194:195], v218, s[36:37]
	v_add_u32_e32 v219, 0x10020, v137
	global_load_dwordx2 v[198:199], v219, s[36:37]
	v_add_u32_e32 v220, 0x10100, v137
	global_load_dwordx2 v[202:203], v220, s[36:37]
	v_add_u32_e32 v221, 0x10120, v137
	global_load_dwordx2 v[206:207], v221, s[36:37]
	s_waitcnt vmcnt(12)
	s_waitcnt vmcnt(8)
	v_lshlrev_b32_e32 v158, 16, v157
	v_and_b32_e32 v159, 0xffff0000, v157
	v_and_b32_e32 v157, 0xffff0000, v156
	v_lshlrev_b32_e32 v156, 16, v156
	v_pk_fma_f32 v[126:127], v[126:127], v[140:141], v[156:157]
	v_pk_fma_f32 v[128:129], v[128:129], v[142:143], v[158:159]
	v_lshlrev_b32_e32 v162, 16, v161
	v_and_b32_e32 v163, 0xffff0000, v161
	v_and_b32_e32 v161, 0xffff0000, v160
	v_lshlrev_b32_e32 v160, 16, v160
	v_pk_fma_f32 v[122:123], v[122:123], v[144:145], v[160:161]
	v_pk_fma_f32 v[124:125], v[124:125], v[146:147], v[162:163]
	v_lshlrev_b32_e32 v166, 16, v165
	v_and_b32_e32 v167, 0xffff0000, v165
	v_and_b32_e32 v165, 0xffff0000, v164
	v_lshlrev_b32_e32 v164, 16, v164
	v_pk_fma_f32 v[118:119], v[118:119], v[148:149], v[164:165]
	v_pk_fma_f32 v[120:121], v[120:121], v[150:151], v[166:167]
	v_lshlrev_b32_e32 v170, 16, v169
	v_and_b32_e32 v171, 0xffff0000, v169
	v_and_b32_e32 v169, 0xffff0000, v168
	v_lshlrev_b32_e32 v168, 16, v168
	v_pk_fma_f32 v[114:115], v[114:115], v[152:153], v[168:169]
	v_pk_fma_f32 v[116:117], v[116:117], v[154:155], v[170:171]
	v_cvt_pk_bf16_f32 v156, v126, v127
	v_cvt_pk_bf16_f32 v157, v128, v129
	v_mul_f32_e32 v158, v127, v127
	v_mul_f32_e32 v159, v129, v129
	v_fmac_f32_e32 v158, v126, v126
	v_fmac_f32_e32 v159, v128, v128
	v_add_f32_e32 v158, v158, v159
	v_add_f32_e32 v222, 0, v158
	v_add_u32_e32 v218, 0x0, v138
	global_store_dwordx2 v218, v[156:157], s[40:41]
	v_cvt_pk_bf16_f32 v160, v122, v123
	v_cvt_pk_bf16_f32 v161, v124, v125
	v_mul_f32_e32 v162, v123, v123
	v_mul_f32_e32 v163, v125, v125
	v_fmac_f32_e32 v162, v122, v122
	v_fmac_f32_e32 v163, v124, v124
	v_add_f32_e32 v162, v162, v163
	v_add_f32_e32 v222, v222, v162
	v_add_u32_e32 v219, 0x20, v138
	global_store_dwordx2 v219, v[160:161], s[40:41]
	v_cvt_pk_bf16_f32 v164, v118, v119
	v_cvt_pk_bf16_f32 v165, v120, v121
	v_mul_f32_e32 v166, v119, v119
	v_mul_f32_e32 v167, v121, v121
	v_fmac_f32_e32 v166, v118, v118
	v_fmac_f32_e32 v167, v120, v120
	v_add_f32_e32 v166, v166, v167
	v_add_f32_e32 v222, v222, v166
	v_add_u32_e32 v220, 0x100, v138
	global_store_dwordx2 v220, v[164:165], s[40:41]
	v_cvt_pk_bf16_f32 v168, v114, v115
	v_cvt_pk_bf16_f32 v169, v116, v117
	v_mul_f32_e32 v170, v115, v115
	v_mul_f32_e32 v171, v117, v117
	v_fmac_f32_e32 v170, v114, v114
	v_fmac_f32_e32 v171, v116, v116
	v_add_f32_e32 v170, v170, v171
	v_add_f32_e32 v222, v222, v170
	v_add_u32_e32 v221, 0x120, v138
	global_store_dwordx2 v221, v[168:169], s[40:41]
	v_add_u32_e32 v218, 0x18000, v137
	global_load_dwordx2 v[156:157], v218, s[36:37]
	v_add_u32_e32 v219, 0x18020, v137
	global_load_dwordx2 v[160:161], v219, s[36:37]
	v_add_u32_e32 v220, 0x18100, v137
	global_load_dwordx2 v[164:165], v220, s[36:37]
	v_add_u32_e32 v221, 0x18120, v137
	global_load_dwordx2 v[168:169], v221, s[36:37]
	s_waitcnt vmcnt(12)
	v_lshlrev_b32_e32 v174, 16, v173
	v_and_b32_e32 v175, 0xffff0000, v173
	v_and_b32_e32 v173, 0xffff0000, v172
	v_lshlrev_b32_e32 v172, 16, v172
	v_pk_fma_f32 v[110:111], v[110:111], v[140:141], v[172:173]
	v_pk_fma_f32 v[112:113], v[112:113], v[142:143], v[174:175]
	v_lshlrev_b32_e32 v184, 16, v183
	v_and_b32_e32 v185, 0xffff0000, v183
	v_and_b32_e32 v183, 0xffff0000, v182
	v_lshlrev_b32_e32 v182, 16, v182
	v_pk_fma_f32 v[106:107], v[106:107], v[144:145], v[182:183]
	v_pk_fma_f32 v[108:109], v[108:109], v[146:147], v[184:185]
	v_lshlrev_b32_e32 v188, 16, v187
	v_and_b32_e32 v189, 0xffff0000, v187
	v_and_b32_e32 v187, 0xffff0000, v186
	v_lshlrev_b32_e32 v186, 16, v186
	v_pk_fma_f32 v[102:103], v[102:103], v[148:149], v[186:187]
	v_pk_fma_f32 v[104:105], v[104:105], v[150:151], v[188:189]
	v_lshlrev_b32_e32 v192, 16, v191
	v_and_b32_e32 v193, 0xffff0000, v191
	v_and_b32_e32 v191, 0xffff0000, v190
	v_lshlrev_b32_e32 v190, 16, v190
	v_pk_fma_f32 v[98:99], v[98:99], v[152:153], v[190:191]
	v_pk_fma_f32 v[100:101], v[100:101], v[154:155], v[192:193]
	v_cvt_pk_bf16_f32 v172, v110, v111
	v_cvt_pk_bf16_f32 v173, v112, v113
	v_mul_f32_e32 v174, v111, v111
	v_mul_f32_e32 v175, v113, v113
	v_fmac_f32_e32 v174, v110, v110
	v_fmac_f32_e32 v175, v112, v112
	v_add_f32_e32 v174, v174, v175
	v_add_f32_e32 v223, 0, v174
	v_add_u32_e32 v218, 0x8000, v138
	global_store_dwordx2 v218, v[172:173], s[40:41]
	v_cvt_pk_bf16_f32 v182, v106, v107
	v_cvt_pk_bf16_f32 v183, v108, v109
	v_mul_f32_e32 v184, v107, v107
	v_mul_f32_e32 v185, v109, v109
	v_fmac_f32_e32 v184, v106, v106
	v_fmac_f32_e32 v185, v108, v108
	v_add_f32_e32 v184, v184, v185
	v_add_f32_e32 v223, v223, v184
	v_add_u32_e32 v219, 0x8020, v138
	global_store_dwordx2 v219, v[182:183], s[40:41]
	v_cvt_pk_bf16_f32 v186, v102, v103
	v_cvt_pk_bf16_f32 v187, v104, v105
	v_mul_f32_e32 v188, v103, v103
	v_mul_f32_e32 v189, v105, v105
	v_fmac_f32_e32 v188, v102, v102
	v_fmac_f32_e32 v189, v104, v104
	v_add_f32_e32 v188, v188, v189
	v_add_f32_e32 v223, v223, v188
	v_add_u32_e32 v220, 0x8100, v138
	global_store_dwordx2 v220, v[186:187], s[40:41]
	v_cvt_pk_bf16_f32 v190, v98, v99
	v_cvt_pk_bf16_f32 v191, v100, v101
	v_mul_f32_e32 v192, v99, v99
	v_mul_f32_e32 v193, v101, v101
	v_fmac_f32_e32 v192, v98, v98
	v_fmac_f32_e32 v193, v100, v100
	v_add_f32_e32 v192, v192, v193
	v_add_f32_e32 v223, v223, v192
	v_add_u32_e32 v221, 0x8120, v138
	global_store_dwordx2 v221, v[190:191], s[40:41]
	v_add_u32_e32 v218, 0x40000, v137
	global_load_dwordx2 v[172:173], v218, s[36:37]
	v_add_u32_e32 v219, 0x40020, v137
	global_load_dwordx2 v[182:183], v219, s[36:37]
	v_add_u32_e32 v220, 0x40100, v137
	global_load_dwordx2 v[186:187], v220, s[36:37]
	v_add_u32_e32 v221, 0x40120, v137
	global_load_dwordx2 v[190:191], v221, s[36:37]
	s_waitcnt vmcnt(16)
	v_lshlrev_b32_e32 v196, 16, v195
	v_and_b32_e32 v197, 0xffff0000, v195
	v_and_b32_e32 v195, 0xffff0000, v194
	v_lshlrev_b32_e32 v194, 16, v194
	v_pk_fma_f32 v[94:95], v[94:95], v[140:141], v[194:195]
	v_pk_fma_f32 v[96:97], v[96:97], v[142:143], v[196:197]
	v_lshlrev_b32_e32 v200, 16, v199
	v_and_b32_e32 v201, 0xffff0000, v199
	v_and_b32_e32 v199, 0xffff0000, v198
	v_lshlrev_b32_e32 v198, 16, v198
	v_pk_fma_f32 v[90:91], v[90:91], v[144:145], v[198:199]
	v_pk_fma_f32 v[92:93], v[92:93], v[146:147], v[200:201]
	v_lshlrev_b32_e32 v204, 16, v203
	v_and_b32_e32 v205, 0xffff0000, v203
	v_and_b32_e32 v203, 0xffff0000, v202
	v_lshlrev_b32_e32 v202, 16, v202
	v_pk_fma_f32 v[86:87], v[86:87], v[148:149], v[202:203]
	v_pk_fma_f32 v[88:89], v[88:89], v[150:151], v[204:205]
	v_lshlrev_b32_e32 v208, 16, v207
	v_and_b32_e32 v209, 0xffff0000, v207
	v_and_b32_e32 v207, 0xffff0000, v206
	v_lshlrev_b32_e32 v206, 16, v206
	v_pk_fma_f32 v[82:83], v[82:83], v[152:153], v[206:207]
	v_pk_fma_f32 v[84:85], v[84:85], v[154:155], v[208:209]
	v_cvt_pk_bf16_f32 v194, v94, v95
	v_cvt_pk_bf16_f32 v195, v96, v97
	v_mul_f32_e32 v196, v95, v95
	v_mul_f32_e32 v197, v97, v97
	v_fmac_f32_e32 v196, v94, v94
	v_fmac_f32_e32 v197, v96, v96
	v_add_f32_e32 v196, v196, v197
	v_add_f32_e32 v224, 0, v196
	v_add_u32_e32 v218, 0x10000, v138
	global_store_dwordx2 v218, v[194:195], s[40:41]
	v_cvt_pk_bf16_f32 v198, v90, v91
	v_cvt_pk_bf16_f32 v199, v92, v93
	v_mul_f32_e32 v200, v91, v91
	v_mul_f32_e32 v201, v93, v93
	v_fmac_f32_e32 v200, v90, v90
	v_fmac_f32_e32 v201, v92, v92
	v_add_f32_e32 v200, v200, v201
	v_add_f32_e32 v224, v224, v200
	v_add_u32_e32 v219, 0x10020, v138
	global_store_dwordx2 v219, v[198:199], s[40:41]
	v_cvt_pk_bf16_f32 v202, v86, v87
	v_cvt_pk_bf16_f32 v203, v88, v89
	v_mul_f32_e32 v204, v87, v87
	v_mul_f32_e32 v205, v89, v89
	v_fmac_f32_e32 v204, v86, v86
	v_fmac_f32_e32 v205, v88, v88
	v_add_f32_e32 v204, v204, v205
	v_add_f32_e32 v224, v224, v204
	v_add_u32_e32 v220, 0x10100, v138
	global_store_dwordx2 v220, v[202:203], s[40:41]
	v_cvt_pk_bf16_f32 v206, v82, v83
	v_cvt_pk_bf16_f32 v207, v84, v85
	v_mul_f32_e32 v208, v83, v83
	v_mul_f32_e32 v209, v85, v85
	v_fmac_f32_e32 v208, v82, v82
	v_fmac_f32_e32 v209, v84, v84
	v_add_f32_e32 v208, v208, v209
	v_add_f32_e32 v224, v224, v208
	v_add_u32_e32 v221, 0x10120, v138
	global_store_dwordx2 v221, v[206:207], s[40:41]
	v_add_u32_e32 v218, 0x48000, v137
	global_load_dwordx2 v[194:195], v218, s[36:37]
	v_add_u32_e32 v219, 0x48020, v137
	global_load_dwordx2 v[198:199], v219, s[36:37]
	v_add_u32_e32 v220, 0x48100, v137
	global_load_dwordx2 v[202:203], v220, s[36:37]
	v_add_u32_e32 v221, 0x48120, v137
	global_load_dwordx2 v[206:207], v221, s[36:37]
	s_waitcnt vmcnt(16)
	v_lshlrev_b32_e32 v158, 16, v157
	v_and_b32_e32 v159, 0xffff0000, v157
	v_and_b32_e32 v157, 0xffff0000, v156
	v_lshlrev_b32_e32 v156, 16, v156
	v_pk_fma_f32 v[78:79], v[78:79], v[140:141], v[156:157]
	v_pk_fma_f32 v[80:81], v[80:81], v[142:143], v[158:159]
	v_lshlrev_b32_e32 v162, 16, v161
	v_and_b32_e32 v163, 0xffff0000, v161
	v_and_b32_e32 v161, 0xffff0000, v160
	v_lshlrev_b32_e32 v160, 16, v160
	v_pk_fma_f32 v[74:75], v[74:75], v[144:145], v[160:161]
	v_pk_fma_f32 v[76:77], v[76:77], v[146:147], v[162:163]
	v_lshlrev_b32_e32 v166, 16, v165
	v_and_b32_e32 v167, 0xffff0000, v165
	v_and_b32_e32 v165, 0xffff0000, v164
	v_lshlrev_b32_e32 v164, 16, v164
	v_pk_fma_f32 v[70:71], v[70:71], v[148:149], v[164:165]
	v_pk_fma_f32 v[72:73], v[72:73], v[150:151], v[166:167]
	v_lshlrev_b32_e32 v170, 16, v169
	v_and_b32_e32 v171, 0xffff0000, v169
	v_and_b32_e32 v169, 0xffff0000, v168
	v_lshlrev_b32_e32 v168, 16, v168
	v_pk_fma_f32 v[66:67], v[66:67], v[152:153], v[168:169]
	v_pk_fma_f32 v[68:69], v[68:69], v[154:155], v[170:171]
	v_cvt_pk_bf16_f32 v156, v78, v79
	v_cvt_pk_bf16_f32 v157, v80, v81
	v_mul_f32_e32 v158, v79, v79
	v_mul_f32_e32 v159, v81, v81
	v_fmac_f32_e32 v158, v78, v78
	v_fmac_f32_e32 v159, v80, v80
	v_add_f32_e32 v158, v158, v159
	v_add_f32_e32 v225, 0, v158
	v_add_u32_e32 v218, 0x18000, v138
	global_store_dwordx2 v218, v[156:157], s[40:41]
	v_cvt_pk_bf16_f32 v160, v74, v75
	v_cvt_pk_bf16_f32 v161, v76, v77
	v_mul_f32_e32 v162, v75, v75
	v_mul_f32_e32 v163, v77, v77
	v_fmac_f32_e32 v162, v74, v74
	v_fmac_f32_e32 v163, v76, v76
	v_add_f32_e32 v162, v162, v163
	v_add_f32_e32 v225, v225, v162
	v_add_u32_e32 v219, 0x18020, v138
	global_store_dwordx2 v219, v[160:161], s[40:41]
	v_cvt_pk_bf16_f32 v164, v70, v71
	v_cvt_pk_bf16_f32 v165, v72, v73
	v_mul_f32_e32 v166, v71, v71
	v_mul_f32_e32 v167, v73, v73
	v_fmac_f32_e32 v166, v70, v70
	v_fmac_f32_e32 v167, v72, v72
	v_add_f32_e32 v166, v166, v167
	v_add_f32_e32 v225, v225, v166
	v_add_u32_e32 v220, 0x18100, v138
	global_store_dwordx2 v220, v[164:165], s[40:41]
	v_cvt_pk_bf16_f32 v168, v66, v67
	v_cvt_pk_bf16_f32 v169, v68, v69
	v_mul_f32_e32 v170, v67, v67
	v_mul_f32_e32 v171, v69, v69
	v_fmac_f32_e32 v170, v66, v66
	v_fmac_f32_e32 v171, v68, v68
	v_add_f32_e32 v170, v170, v171
	v_add_f32_e32 v225, v225, v170
	v_add_u32_e32 v221, 0x18120, v138
	global_store_dwordx2 v221, v[168:169], s[40:41]
	v_add_u32_e32 v218, 0x50000, v137
	global_load_dwordx2 v[156:157], v218, s[36:37]
	v_add_u32_e32 v219, 0x50020, v137
	global_load_dwordx2 v[160:161], v219, s[36:37]
	v_add_u32_e32 v220, 0x50100, v137
	global_load_dwordx2 v[164:165], v220, s[36:37]
	v_add_u32_e32 v221, 0x50120, v137
	global_load_dwordx2 v[168:169], v221, s[36:37]
	s_waitcnt vmcnt(16)
	v_lshlrev_b32_e32 v174, 16, v173
	v_and_b32_e32 v175, 0xffff0000, v173
	v_and_b32_e32 v173, 0xffff0000, v172
	v_lshlrev_b32_e32 v172, 16, v172
	v_pk_fma_f32 v[62:63], v[62:63], v[140:141], v[172:173]
	v_pk_fma_f32 v[64:65], v[64:65], v[142:143], v[174:175]
	v_lshlrev_b32_e32 v184, 16, v183
	v_and_b32_e32 v185, 0xffff0000, v183
	v_and_b32_e32 v183, 0xffff0000, v182
	v_lshlrev_b32_e32 v182, 16, v182
	v_pk_fma_f32 v[58:59], v[58:59], v[144:145], v[182:183]
	v_pk_fma_f32 v[60:61], v[60:61], v[146:147], v[184:185]
	v_lshlrev_b32_e32 v188, 16, v187
	v_and_b32_e32 v189, 0xffff0000, v187
	v_and_b32_e32 v187, 0xffff0000, v186
	v_lshlrev_b32_e32 v186, 16, v186
	v_pk_fma_f32 v[54:55], v[54:55], v[148:149], v[186:187]
	v_pk_fma_f32 v[56:57], v[56:57], v[150:151], v[188:189]
	v_lshlrev_b32_e32 v192, 16, v191
	v_and_b32_e32 v193, 0xffff0000, v191
	v_and_b32_e32 v191, 0xffff0000, v190
	v_lshlrev_b32_e32 v190, 16, v190
	v_pk_fma_f32 v[50:51], v[50:51], v[152:153], v[190:191]
	v_pk_fma_f32 v[52:53], v[52:53], v[154:155], v[192:193]
	v_cvt_pk_bf16_f32 v172, v62, v63
	v_cvt_pk_bf16_f32 v173, v64, v65
	v_mul_f32_e32 v174, v63, v63
	v_mul_f32_e32 v175, v65, v65
	v_fmac_f32_e32 v174, v62, v62
	v_fmac_f32_e32 v175, v64, v64
	v_add_f32_e32 v174, v174, v175
	v_add_f32_e32 v226, 0, v174
	v_add_u32_e32 v218, 0x40000, v138
	global_store_dwordx2 v218, v[172:173], s[40:41]
	v_cvt_pk_bf16_f32 v182, v58, v59
	v_cvt_pk_bf16_f32 v183, v60, v61
	v_mul_f32_e32 v184, v59, v59
	v_mul_f32_e32 v185, v61, v61
	v_fmac_f32_e32 v184, v58, v58
	v_fmac_f32_e32 v185, v60, v60
	v_add_f32_e32 v184, v184, v185
	v_add_f32_e32 v226, v226, v184
	v_add_u32_e32 v219, 0x40020, v138
	global_store_dwordx2 v219, v[182:183], s[40:41]
	v_cvt_pk_bf16_f32 v186, v54, v55
	v_cvt_pk_bf16_f32 v187, v56, v57
	v_mul_f32_e32 v188, v55, v55
	v_mul_f32_e32 v189, v57, v57
	v_fmac_f32_e32 v188, v54, v54
	v_fmac_f32_e32 v189, v56, v56
	v_add_f32_e32 v188, v188, v189
	v_add_f32_e32 v226, v226, v188
	v_add_u32_e32 v220, 0x40100, v138
	global_store_dwordx2 v220, v[186:187], s[40:41]
	v_cvt_pk_bf16_f32 v190, v50, v51
	v_cvt_pk_bf16_f32 v191, v52, v53
	v_mul_f32_e32 v192, v51, v51
	v_mul_f32_e32 v193, v53, v53
	v_fmac_f32_e32 v192, v50, v50
	v_fmac_f32_e32 v193, v52, v52
	v_add_f32_e32 v192, v192, v193
	v_add_f32_e32 v226, v226, v192
	v_add_u32_e32 v221, 0x40120, v138
	global_store_dwordx2 v221, v[190:191], s[40:41]
	v_add_u32_e32 v218, 0x58000, v137
	global_load_dwordx2 v[172:173], v218, s[36:37]
	v_add_u32_e32 v219, 0x58020, v137
	global_load_dwordx2 v[182:183], v219, s[36:37]
	v_add_u32_e32 v220, 0x58100, v137
	global_load_dwordx2 v[186:187], v220, s[36:37]
	v_add_u32_e32 v221, 0x58120, v137
	global_load_dwordx2 v[190:191], v221, s[36:37]
	s_waitcnt vmcnt(16)
	v_lshlrev_b32_e32 v196, 16, v195
	v_and_b32_e32 v197, 0xffff0000, v195
	v_and_b32_e32 v195, 0xffff0000, v194
	v_lshlrev_b32_e32 v194, 16, v194
	v_pk_fma_f32 v[46:47], v[46:47], v[140:141], v[194:195]
	v_pk_fma_f32 v[48:49], v[48:49], v[142:143], v[196:197]
	v_lshlrev_b32_e32 v200, 16, v199
	v_and_b32_e32 v201, 0xffff0000, v199
	v_and_b32_e32 v199, 0xffff0000, v198
	v_lshlrev_b32_e32 v198, 16, v198
	v_pk_fma_f32 v[42:43], v[42:43], v[144:145], v[198:199]
	v_pk_fma_f32 v[44:45], v[44:45], v[146:147], v[200:201]
	v_lshlrev_b32_e32 v204, 16, v203
	v_and_b32_e32 v205, 0xffff0000, v203
	v_and_b32_e32 v203, 0xffff0000, v202
	v_lshlrev_b32_e32 v202, 16, v202
	v_pk_fma_f32 v[38:39], v[38:39], v[148:149], v[202:203]
	v_pk_fma_f32 v[40:41], v[40:41], v[150:151], v[204:205]
	v_lshlrev_b32_e32 v208, 16, v207
	v_and_b32_e32 v209, 0xffff0000, v207
	v_and_b32_e32 v207, 0xffff0000, v206
	v_lshlrev_b32_e32 v206, 16, v206
	v_pk_fma_f32 v[34:35], v[34:35], v[152:153], v[206:207]
	v_pk_fma_f32 v[36:37], v[36:37], v[154:155], v[208:209]
	v_cvt_pk_bf16_f32 v194, v46, v47
	v_cvt_pk_bf16_f32 v195, v48, v49
	v_mul_f32_e32 v196, v47, v47
	v_mul_f32_e32 v197, v49, v49
	v_fmac_f32_e32 v196, v46, v46
	v_fmac_f32_e32 v197, v48, v48
	v_add_f32_e32 v196, v196, v197
	v_add_f32_e32 v216, 0, v196
	v_add_u32_e32 v218, 0x48000, v138
	global_store_dwordx2 v218, v[194:195], s[40:41]
	v_cvt_pk_bf16_f32 v198, v42, v43
	v_cvt_pk_bf16_f32 v199, v44, v45
	v_mul_f32_e32 v200, v43, v43
	v_mul_f32_e32 v201, v45, v45
	v_fmac_f32_e32 v200, v42, v42
	v_fmac_f32_e32 v201, v44, v44
	v_add_f32_e32 v200, v200, v201
	v_add_f32_e32 v216, v216, v200
	v_add_u32_e32 v219, 0x48020, v138
	global_store_dwordx2 v219, v[198:199], s[40:41]
	v_cvt_pk_bf16_f32 v202, v38, v39
	v_cvt_pk_bf16_f32 v203, v40, v41
	v_mul_f32_e32 v204, v39, v39
	v_mul_f32_e32 v205, v41, v41
	v_fmac_f32_e32 v204, v38, v38
	v_fmac_f32_e32 v205, v40, v40
	v_add_f32_e32 v204, v204, v205
	v_add_f32_e32 v216, v216, v204
	v_add_u32_e32 v220, 0x48100, v138
	global_store_dwordx2 v220, v[202:203], s[40:41]
	v_cvt_pk_bf16_f32 v206, v34, v35
	v_cvt_pk_bf16_f32 v207, v36, v37
	v_mul_f32_e32 v208, v35, v35
	v_mul_f32_e32 v209, v37, v37
	v_fmac_f32_e32 v208, v34, v34
	v_fmac_f32_e32 v209, v36, v36
	v_add_f32_e32 v208, v208, v209
	v_add_f32_e32 v216, v216, v208
	v_add_u32_e32 v221, 0x48120, v138
	global_store_dwordx2 v221, v[206:207], s[40:41]
	s_waitcnt vmcnt(12)
	v_lshlrev_b32_e32 v158, 16, v157
	v_and_b32_e32 v159, 0xffff0000, v157
	v_and_b32_e32 v157, 0xffff0000, v156
	v_lshlrev_b32_e32 v156, 16, v156
	v_pk_fma_f32 v[30:31], v[30:31], v[140:141], v[156:157]
	v_pk_fma_f32 v[32:33], v[32:33], v[142:143], v[158:159]
	v_lshlrev_b32_e32 v162, 16, v161
	v_and_b32_e32 v163, 0xffff0000, v161
	v_and_b32_e32 v161, 0xffff0000, v160
	v_lshlrev_b32_e32 v160, 16, v160
	v_pk_fma_f32 v[26:27], v[26:27], v[144:145], v[160:161]
	v_pk_fma_f32 v[28:29], v[28:29], v[146:147], v[162:163]
	v_lshlrev_b32_e32 v166, 16, v165
	v_and_b32_e32 v167, 0xffff0000, v165
	v_and_b32_e32 v165, 0xffff0000, v164
	v_lshlrev_b32_e32 v164, 16, v164
	v_pk_fma_f32 v[22:23], v[22:23], v[148:149], v[164:165]
	v_pk_fma_f32 v[24:25], v[24:25], v[150:151], v[166:167]
	v_lshlrev_b32_e32 v170, 16, v169
	v_and_b32_e32 v171, 0xffff0000, v169
	v_and_b32_e32 v169, 0xffff0000, v168
	v_lshlrev_b32_e32 v168, 16, v168
	v_pk_fma_f32 v[18:19], v[18:19], v[152:153], v[168:169]
	v_pk_fma_f32 v[20:21], v[20:21], v[154:155], v[170:171]
	v_cvt_pk_bf16_f32 v156, v30, v31
	v_cvt_pk_bf16_f32 v157, v32, v33
	v_mul_f32_e32 v158, v31, v31
	v_mul_f32_e32 v159, v33, v33
	v_fmac_f32_e32 v158, v30, v30
	v_fmac_f32_e32 v159, v32, v32
	v_add_f32_e32 v158, v158, v159
	v_add_f32_e32 v217, 0, v158
	v_add_u32_e32 v218, 0x50000, v138
	global_store_dwordx2 v218, v[156:157], s[40:41]
	v_cvt_pk_bf16_f32 v160, v26, v27
	v_cvt_pk_bf16_f32 v161, v28, v29
	v_mul_f32_e32 v162, v27, v27
	v_mul_f32_e32 v163, v29, v29
	v_fmac_f32_e32 v162, v26, v26
	v_fmac_f32_e32 v163, v28, v28
	v_add_f32_e32 v162, v162, v163
	v_add_f32_e32 v217, v217, v162
	v_add_u32_e32 v219, 0x50020, v138
	global_store_dwordx2 v219, v[160:161], s[40:41]
	v_cvt_pk_bf16_f32 v164, v22, v23
	v_cvt_pk_bf16_f32 v165, v24, v25
	v_mul_f32_e32 v166, v23, v23
	v_mul_f32_e32 v167, v25, v25
	v_fmac_f32_e32 v166, v22, v22
	v_fmac_f32_e32 v167, v24, v24
	v_add_f32_e32 v166, v166, v167
	v_add_f32_e32 v217, v217, v166
	v_add_u32_e32 v220, 0x50100, v138
	global_store_dwordx2 v220, v[164:165], s[40:41]
	v_cvt_pk_bf16_f32 v168, v18, v19
	v_cvt_pk_bf16_f32 v169, v20, v21
	v_mul_f32_e32 v170, v19, v19
	v_mul_f32_e32 v171, v21, v21
	v_fmac_f32_e32 v170, v18, v18
	v_fmac_f32_e32 v171, v20, v20
	v_add_f32_e32 v170, v170, v171
	v_add_f32_e32 v217, v217, v170
	v_add_u32_e32 v221, 0x50120, v138
	global_store_dwordx2 v221, v[168:169], s[40:41]
	s_waitcnt vmcnt(8)
	v_lshlrev_b32_e32 v174, 16, v173
	v_and_b32_e32 v175, 0xffff0000, v173
	v_and_b32_e32 v173, 0xffff0000, v172
	v_lshlrev_b32_e32 v172, 16, v172
	v_pk_fma_f32 v[14:15], v[14:15], v[140:141], v[172:173]
	v_pk_fma_f32 v[16:17], v[16:17], v[142:143], v[174:175]
	v_lshlrev_b32_e32 v184, 16, v183
	v_and_b32_e32 v185, 0xffff0000, v183
	v_and_b32_e32 v183, 0xffff0000, v182
	v_lshlrev_b32_e32 v182, 16, v182
	v_pk_fma_f32 v[10:11], v[10:11], v[144:145], v[182:183]
	v_pk_fma_f32 v[12:13], v[12:13], v[146:147], v[184:185]
	v_lshlrev_b32_e32 v188, 16, v187
	v_and_b32_e32 v189, 0xffff0000, v187
	v_and_b32_e32 v187, 0xffff0000, v186
	v_lshlrev_b32_e32 v186, 16, v186
	v_pk_fma_f32 v[6:7], v[6:7], v[148:149], v[186:187]
	v_pk_fma_f32 v[8:9], v[8:9], v[150:151], v[188:189]
	v_lshlrev_b32_e32 v192, 16, v191
	v_and_b32_e32 v193, 0xffff0000, v191
	v_and_b32_e32 v191, 0xffff0000, v190
	v_lshlrev_b32_e32 v190, 16, v190
	v_pk_fma_f32 v[2:3], v[2:3], v[152:153], v[190:191]
	v_pk_fma_f32 v[4:5], v[4:5], v[154:155], v[192:193]
	v_cvt_pk_bf16_f32 v172, v14, v15
	v_cvt_pk_bf16_f32 v173, v16, v17
	v_mul_f32_e32 v174, v15, v15
	v_mul_f32_e32 v175, v17, v17
	v_fmac_f32_e32 v174, v14, v14
	v_fmac_f32_e32 v175, v16, v16
	v_add_f32_e32 v174, v174, v175
	v_add_f32_e32 v212, 0, v174
	v_add_u32_e32 v218, 0x58000, v138
	global_store_dwordx2 v218, v[172:173], s[40:41]
	v_cvt_pk_bf16_f32 v182, v10, v11
	v_cvt_pk_bf16_f32 v183, v12, v13
	v_mul_f32_e32 v184, v11, v11
	v_mul_f32_e32 v185, v13, v13
	v_fmac_f32_e32 v184, v10, v10
	v_fmac_f32_e32 v185, v12, v12
	v_add_f32_e32 v184, v184, v185
	v_add_f32_e32 v212, v212, v184
	v_add_u32_e32 v219, 0x58020, v138
	global_store_dwordx2 v219, v[182:183], s[40:41]
	v_cvt_pk_bf16_f32 v186, v6, v7
	v_cvt_pk_bf16_f32 v187, v8, v9
	v_mul_f32_e32 v188, v7, v7
	v_mul_f32_e32 v189, v9, v9
	v_fmac_f32_e32 v188, v6, v6
	v_fmac_f32_e32 v189, v8, v8
	v_add_f32_e32 v188, v188, v189
	v_add_f32_e32 v212, v212, v188
	v_add_u32_e32 v220, 0x58100, v138
	global_store_dwordx2 v220, v[186:187], s[40:41]
	v_cvt_pk_bf16_f32 v190, v2, v3
	v_cvt_pk_bf16_f32 v191, v4, v5
	v_mul_f32_e32 v192, v3, v3
	v_mul_f32_e32 v193, v5, v5
	v_fmac_f32_e32 v192, v2, v2
	v_fmac_f32_e32 v193, v4, v4
	v_add_f32_e32 v192, v192, v193
	v_add_f32_e32 v212, v212, v192
	v_add_u32_e32 v221, 0x58120, v138
	global_store_dwordx2 v221, v[190:191], s[40:41]
	ds_bpermute_b32 v156, v213, v222
	ds_bpermute_b32 v157, v213, v223
	ds_bpermute_b32 v158, v213, v224
	ds_bpermute_b32 v159, v213, v225
	ds_bpermute_b32 v160, v213, v226
	ds_bpermute_b32 v161, v213, v216
	ds_bpermute_b32 v162, v213, v217
	ds_bpermute_b32 v163, v213, v212
	s_waitcnt lgkmcnt(0)
	v_add_f32_e32 v222, v222, v156
	v_add_f32_e32 v223, v223, v157
	v_add_f32_e32 v224, v224, v158
	v_add_f32_e32 v225, v225, v159
	v_add_f32_e32 v226, v226, v160
	v_add_f32_e32 v216, v216, v161
	v_add_f32_e32 v217, v217, v162
	v_add_f32_e32 v212, v212, v163
	ds_bpermute_b32 v156, v214, v222
	ds_bpermute_b32 v157, v214, v223
	ds_bpermute_b32 v158, v214, v224
	ds_bpermute_b32 v159, v214, v225
	ds_bpermute_b32 v160, v214, v226
	ds_bpermute_b32 v161, v214, v216
	ds_bpermute_b32 v162, v214, v217
	ds_bpermute_b32 v163, v214, v212
	s_waitcnt lgkmcnt(0)
	v_add_f32_e32 v222, v222, v156
	v_add_f32_e32 v223, v223, v157
	v_add_f32_e32 v224, v224, v158
	v_add_f32_e32 v225, v225, v159
	v_add_f32_e32 v226, v226, v160
	v_add_f32_e32 v216, v216, v161
	v_add_f32_e32 v217, v217, v162
	v_add_f32_e32 v212, v212, v163
	v_cmp_gt_u32_e32 vcc, 16, v227
	s_nop 3
	s_and_saveexec_b64 s[0:1], vcc
	ds_write_b32 v139, v222 offset:0
	ds_write_b32 v139, v223 offset:256
	ds_write_b32 v139, v224 offset:512
	ds_write_b32 v139, v225 offset:768
	ds_write_b32 v139, v226 offset:2048
	ds_write_b32 v139, v216 offset:2304
	ds_write_b32 v139, v217 offset:2560
	ds_write_b32 v139, v212 offset:2816
	s_or_b64 exec, exec, s[0:1]
	s_load_dwordx2 s[36:37], s[78:79], 0x60
	s_load_dwordx2 s[38:39], s[78:79], 0x1d0
	v_lshlrev_b32_e32 v137, 2, v135
	s_lshr_b32 s0, s12, 3
	s_mul_i32 s0, s0, 0xe000
	v_add_u32_e32 v138, s0, v137
	s_waitcnt lgkmcnt(0)
	v_add_u32_e32 v216, 0x1000, v137
	global_load_dwordx4 v[156:159], v216, s[36:37] offset:0
	global_load_dwordx4 v[160:163], v216, s[36:37] offset:64
	global_load_dwordx4 v[164:167], v216, s[36:37] offset:512
	global_load_dwordx4 v[168:171], v216, s[36:37] offset:576
	v_add_u32_e32 v217, 0x9000, v138
	global_load_dwordx4 v[172:175], v217, s[38:39] offset:0
	global_load_dwordx4 v[182:185], v217, s[38:39] offset:64
	global_load_dwordx4 v[186:189], v217, s[38:39] offset:512
	global_load_dwordx4 v[190:193], v217, s[38:39] offset:576
	v_add_u32_e32 v218, 0xa000, v138
	global_load_dwordx4 v[194:197], v218, s[38:39] offset:0
	global_load_dwordx4 v[198:201], v218, s[38:39] offset:64
	global_load_dwordx4 v[202:205], v218, s[38:39] offset:512
	global_load_dwordx4 v[206:209], v218, s[38:39] offset:576
	v_mov_b32_e32 v223, v134
	v_mov_b32_e32 v224, v135
	v_mov_b32_e32 v225, v136
	s_load_dwordx16 s[36:51], s[78:79], 0x140
	v_and_b32_e32 v138, 31, v248
	s_waitcnt vmcnt(0) lgkmcnt(0)
	s_barrier
	s_waitcnt lgkmcnt(0)
	s_mov_b64 s[26:27], s[46:47]
	v_lshl_or_b32 v142, s3, 5, v138
	s_add_u32 s4, s26, 0x80000
	v_add_u32_e32 v138, s18, v142
	s_addc_u32 s5, s27, 0
	v_cmp_gt_u32_e64 s[0:1], 32, v227
	v_ashrrev_i32_e32 v139, 31, v138
	s_and_saveexec_b64 s[6:7], s[0:1]
	s_cbranch_execz .LBB0_4623
	v_lshl_add_u32 v140, v142, 4, 0
	ds_read_b128 v[144:147], v140
	s_ashr_i32 s3, s2, 31
	v_lshl_add_u64 v[140:141], v[138:139], 4, s[4:5]
	v_lshl_add_u64 v[140:141], s[2:3], 2, v[140:141]
	s_waitcnt lgkmcnt(0)
	v_mov_b32_e32 v150, v145
	v_mov_b32_e32 v151, v146
	v_mov_b32_e32 v145, v147
	v_pk_add_f32 v[144:145], v[150:151], v[144:145]
	s_nop 0
	v_pk_add_f32 v[144:145], v[144:145], v[144:145] op_sel:[0,1] op_sel_hi:[1,0]
	global_store_dword v[140:141], v144, off sc1

.LBB0_5232:
	s_lshl_b32 s14, s24, 8
	s_load_dwordx2 s[36:37], s[78:79], 0x1f8
	s_load_dwordx2 s[38:39], s[78:79], 0x1d0
	s_load_dwordx2 s[40:41], s[78:79], 0x1f8
	v_and_b32_e32 v130, 15, v248
	v_bfe_u32 v131, v248, 8, 1
	v_bfe_u32 v132, v248, 6, 2
	v_bfe_u32 v133, v248, 4, 2
	v_lshl_add_u32 v134, v131, 6, v130
	v_lshlrev_b32_e32 v135, 5, v132
	v_lshl_or_b32 v135, v133, 2, v135
	s_lshl_b32 s0, s6, 8
	v_add_u32_e32 v135, s0, v135
	s_lshl_b32 s0, s24, 8
	v_add_u32_e32 v136, s0, v134
	v_mul_u32_u24_e32 v137, 0x800, v136
	v_lshl_add_u32 v137, v135, 1, v137
	v_lshlrev_b32_e32 v138, 11, v136
	v_lshl_add_u32 v138, v135, 1, v138
	v_lshlrev_b32_e32 v139, 2, v134
	v_add_lshl_u32 v139, v139, v132, 2
	v_xor_b32_e32 v213, 16, v227
	v_lshlrev_b32_e32 v213, 2, v213
	v_xor_b32_e32 v214, 32, v227
	v_lshlrev_b32_e32 v214, 2, v214
	v_lshlrev_b32_e32 v215, 2, v135
	s_lshr_b32 s0, s24, 3
	s_mul_i32 s0, s0, 0xe000
	s_add_u32 s0, s0, 0xb000
	v_add_u32_e32 v215, s0, v215
	s_waitcnt lgkmcnt(0)
	global_load_dwordx4 v[140:143], v215, s[38:39] offset:0
	global_load_dwordx4 v[144:147], v215, s[38:39] offset:64
	global_load_dwordx4 v[148:151], v215, s[38:39] offset:512
	global_load_dwordx4 v[152:155], v215, s[38:39] offset:576
	v_add_u32_e32 v218, 0x0, v137
	global_load_dwordx2 v[156:157], v218, s[36:37]
	v_add_u32_e32 v219, 0x20, v137
	global_load_dwordx2 v[160:161], v219, s[36:37]
	v_add_u32_e32 v220, 0x100, v137
	global_load_dwordx2 v[164:165], v220, s[36:37]
	v_add_u32_e32 v221, 0x120, v137
	global_load_dwordx2 v[168:169], v221, s[36:37]
	v_add_u32_e32 v218, 0x8000, v137
	global_load_dwordx2 v[172:173], v218, s[36:37]
	v_add_u32_e32 v219, 0x8020, v137
	global_load_dwordx2 v[182:183], v219, s[36:37]
	v_add_u32_e32 v220, 0x8100, v137
	global_load_dwordx2 v[186:187], v220, s[36:37]
	v_add_u32_e32 v221, 0x8120, v137
	global_load_dwordx2 v[190:191], v221, s[36:37]
	v_add_u32_e32 v218, 0x10000, v137
	global_load_dwordx2 v[194:195], v218, s[36:37]
	v_add_u32_e32 v219, 0x10020, v137
	global_load_dwordx2 v[198:199], v219, s[36:37]
	v_add_u32_e32 v220, 0x10100, v137
	global_load_dwordx2 v[202:203], v220, s[36:37]
	v_add_u32_e32 v221, 0x10120, v137
	global_load_dwordx2 v[206:207], v221, s[36:37]
	s_waitcnt vmcnt(12)
	s_waitcnt vmcnt(8)
	v_lshlrev_b32_e32 v158, 16, v157
	v_and_b32_e32 v159, 0xffff0000, v157
	v_and_b32_e32 v157, 0xffff0000, v156
	v_lshlrev_b32_e32 v156, 16, v156
	v_pk_fma_f32 v[126:127], v[126:127], v[140:141], v[156:157]
	v_pk_fma_f32 v[128:129], v[128:129], v[142:143], v[158:159]
	v_lshlrev_b32_e32 v162, 16, v161
	v_and_b32_e32 v163, 0xffff0000, v161
	v_and_b32_e32 v161, 0xffff0000, v160
	v_lshlrev_b32_e32 v160, 16, v160
	v_pk_fma_f32 v[122:123], v[122:123], v[144:145], v[160:161]
	v_pk_fma_f32 v[124:125], v[124:125], v[146:147], v[162:163]
	v_lshlrev_b32_e32 v166, 16, v165
	v_and_b32_e32 v167, 0xffff0000, v165
	v_and_b32_e32 v165, 0xffff0000, v164
	v_lshlrev_b32_e32 v164, 16, v164
	v_pk_fma_f32 v[118:119], v[118:119], v[148:149], v[164:165]
	v_pk_fma_f32 v[120:121], v[120:121], v[150:151], v[166:167]
	v_lshlrev_b32_e32 v170, 16, v169
	v_and_b32_e32 v171, 0xffff0000, v169
	v_and_b32_e32 v169, 0xffff0000, v168
	v_lshlrev_b32_e32 v168, 16, v168
	v_pk_fma_f32 v[114:115], v[114:115], v[152:153], v[168:169]
	v_pk_fma_f32 v[116:117], v[116:117], v[154:155], v[170:171]
	v_cvt_pk_bf16_f32 v156, v126, v127
	v_cvt_pk_bf16_f32 v157, v128, v129
	v_mul_f32_e32 v158, v127, v127
	v_mul_f32_e32 v159, v129, v129
	v_fmac_f32_e32 v158, v126, v126
	v_fmac_f32_e32 v159, v128, v128
	v_add_f32_e32 v158, v158, v159
	v_add_f32_e32 v222, 0, v158
	v_add_u32_e32 v218, 0x0, v138
	global_store_dwordx2 v218, v[156:157], s[40:41]
	v_cvt_pk_bf16_f32 v160, v122, v123
	v_cvt_pk_bf16_f32 v161, v124, v125
	v_mul_f32_e32 v162, v123, v123
	v_mul_f32_e32 v163, v125, v125
	v_fmac_f32_e32 v162, v122, v122
	v_fmac_f32_e32 v163, v124, v124
	v_add_f32_e32 v162, v162, v163
	v_add_f32_e32 v222, v222, v162
	v_add_u32_e32 v219, 0x20, v138
	global_store_dwordx2 v219, v[160:161], s[40:41]
	v_cvt_pk_bf16_f32 v164, v118, v119
	v_cvt_pk_bf16_f32 v165, v120, v121
	v_mul_f32_e32 v166, v119, v119
	v_mul_f32_e32 v167, v121, v121
	v_fmac_f32_e32 v166, v118, v118
	v_fmac_f32_e32 v167, v120, v120
	v_add_f32_e32 v166, v166, v167
	v_add_f32_e32 v222, v222, v166
	v_add_u32_e32 v220, 0x100, v138
	global_store_dwordx2 v220, v[164:165], s[40:41]
	v_cvt_pk_bf16_f32 v168, v114, v115
	v_cvt_pk_bf16_f32 v169, v116, v117
	v_mul_f32_e32 v170, v115, v115
	v_mul_f32_e32 v171, v117, v117
	v_fmac_f32_e32 v170, v114, v114
	v_fmac_f32_e32 v171, v116, v116
	v_add_f32_e32 v170, v170, v171
	v_add_f32_e32 v222, v222, v170
	v_add_u32_e32 v221, 0x120, v138
	global_store_dwordx2 v221, v[168:169], s[40:41]
	v_add_u32_e32 v218, 0x18000, v137
	global_load_dwordx2 v[156:157], v218, s[36:37]
	v_add_u32_e32 v219, 0x18020, v137
	global_load_dwordx2 v[160:161], v219, s[36:37]
	v_add_u32_e32 v220, 0x18100, v137
	global_load_dwordx2 v[164:165], v220, s[36:37]
	v_add_u32_e32 v221, 0x18120, v137
	global_load_dwordx2 v[168:169], v221, s[36:37]
	s_waitcnt vmcnt(12)
	v_lshlrev_b32_e32 v174, 16, v173
	v_and_b32_e32 v175, 0xffff0000, v173
	v_and_b32_e32 v173, 0xffff0000, v172
	v_lshlrev_b32_e32 v172, 16, v172
	v_pk_fma_f32 v[110:111], v[110:111], v[140:141], v[172:173]
	v_pk_fma_f32 v[112:113], v[112:113], v[142:143], v[174:175]
	v_lshlrev_b32_e32 v184, 16, v183
	v_and_b32_e32 v185, 0xffff0000, v183
	v_and_b32_e32 v183, 0xffff0000, v182
	v_lshlrev_b32_e32 v182, 16, v182
	v_pk_fma_f32 v[106:107], v[106:107], v[144:145], v[182:183]
	v_pk_fma_f32 v[108:109], v[108:109], v[146:147], v[184:185]
	v_lshlrev_b32_e32 v188, 16, v187
	v_and_b32_e32 v189, 0xffff0000, v187
	v_and_b32_e32 v187, 0xffff0000, v186
	v_lshlrev_b32_e32 v186, 16, v186
	v_pk_fma_f32 v[102:103], v[102:103], v[148:149], v[186:187]
	v_pk_fma_f32 v[104:105], v[104:105], v[150:151], v[188:189]
	v_lshlrev_b32_e32 v192, 16, v191
	v_and_b32_e32 v193, 0xffff0000, v191
	v_and_b32_e32 v191, 0xffff0000, v190
	v_lshlrev_b32_e32 v190, 16, v190
	v_pk_fma_f32 v[98:99], v[98:99], v[152:153], v[190:191]
	v_pk_fma_f32 v[100:101], v[100:101], v[154:155], v[192:193]
	v_cvt_pk_bf16_f32 v172, v110, v111
	v_cvt_pk_bf16_f32 v173, v112, v113
	v_mul_f32_e32 v174, v111, v111
	v_mul_f32_e32 v175, v113, v113
	v_fmac_f32_e32 v174, v110, v110
	v_fmac_f32_e32 v175, v112, v112
	v_add_f32_e32 v174, v174, v175
	v_add_f32_e32 v223, 0, v174
	v_add_u32_e32 v218, 0x8000, v138
	global_store_dwordx2 v218, v[172:173], s[40:41]
	v_cvt_pk_bf16_f32 v182, v106, v107
	v_cvt_pk_bf16_f32 v183, v108, v109
	v_mul_f32_e32 v184, v107, v107
	v_mul_f32_e32 v185, v109, v109
	v_fmac_f32_e32 v184, v106, v106
	v_fmac_f32_e32 v185, v108, v108
	v_add_f32_e32 v184, v184, v185
	v_add_f32_e32 v223, v223, v184
	v_add_u32_e32 v219, 0x8020, v138
	global_store_dwordx2 v219, v[182:183], s[40:41]
	v_cvt_pk_bf16_f32 v186, v102, v103
	v_cvt_pk_bf16_f32 v187, v104, v105
	v_mul_f32_e32 v188, v103, v103
	v_mul_f32_e32 v189, v105, v105
	v_fmac_f32_e32 v188, v102, v102
	v_fmac_f32_e32 v189, v104, v104
	v_add_f32_e32 v188, v188, v189
	v_add_f32_e32 v223, v223, v188
	v_add_u32_e32 v220, 0x8100, v138
	global_store_dwordx2 v220, v[186:187], s[40:41]
	v_cvt_pk_bf16_f32 v190, v98, v99
	v_cvt_pk_bf16_f32 v191, v100, v101
	v_mul_f32_e32 v192, v99, v99
	v_mul_f32_e32 v193, v101, v101
	v_fmac_f32_e32 v192, v98, v98
	v_fmac_f32_e32 v193, v100, v100
	v_add_f32_e32 v192, v192, v193
	v_add_f32_e32 v223, v223, v192
	v_add_u32_e32 v221, 0x8120, v138
	global_store_dwordx2 v221, v[190:191], s[40:41]
	v_add_u32_e32 v218, 0x40000, v137
	global_load_dwordx2 v[172:173], v218, s[36:37]
	v_add_u32_e32 v219, 0x40020, v137
	global_load_dwordx2 v[182:183], v219, s[36:37]
	v_add_u32_e32 v220, 0x40100, v137
	global_load_dwordx2 v[186:187], v220, s[36:37]
	v_add_u32_e32 v221, 0x40120, v137
	global_load_dwordx2 v[190:191], v221, s[36:37]
	s_waitcnt vmcnt(16)
	v_lshlrev_b32_e32 v196, 16, v195
	v_and_b32_e32 v197, 0xffff0000, v195
	v_and_b32_e32 v195, 0xffff0000, v194
	v_lshlrev_b32_e32 v194, 16, v194
	v_pk_fma_f32 v[94:95], v[94:95], v[140:141], v[194:195]
	v_pk_fma_f32 v[96:97], v[96:97], v[142:143], v[196:197]
	v_lshlrev_b32_e32 v200, 16, v199
	v_and_b32_e32 v201, 0xffff0000, v199
	v_and_b32_e32 v199, 0xffff0000, v198
	v_lshlrev_b32_e32 v198, 16, v198
	v_pk_fma_f32 v[90:91], v[90:91], v[144:145], v[198:199]
	v_pk_fma_f32 v[92:93], v[92:93], v[146:147], v[200:201]
	v_lshlrev_b32_e32 v204, 16, v203
	v_and_b32_e32 v205, 0xffff0000, v203
	v_and_b32_e32 v203, 0xffff0000, v202
	v_lshlrev_b32_e32 v202, 16, v202
	v_pk_fma_f32 v[86:87], v[86:87], v[148:149], v[202:203]
	v_pk_fma_f32 v[88:89], v[88:89], v[150:151], v[204:205]
	v_lshlrev_b32_e32 v208, 16, v207
	v_and_b32_e32 v209, 0xffff0000, v207
	v_and_b32_e32 v207, 0xffff0000, v206
	v_lshlrev_b32_e32 v206, 16, v206
	v_pk_fma_f32 v[82:83], v[82:83], v[152:153], v[206:207]
	v_pk_fma_f32 v[84:85], v[84:85], v[154:155], v[208:209]
	v_cvt_pk_bf16_f32 v194, v94, v95
	v_cvt_pk_bf16_f32 v195, v96, v97
	v_mul_f32_e32 v196, v95, v95
	v_mul_f32_e32 v197, v97, v97
	v_fmac_f32_e32 v196, v94, v94
	v_fmac_f32_e32 v197, v96, v96
	v_add_f32_e32 v196, v196, v197
	v_add_f32_e32 v224, 0, v196
	v_add_u32_e32 v218, 0x10000, v138
	global_store_dwordx2 v218, v[194:195], s[40:41]
	v_cvt_pk_bf16_f32 v198, v90, v91
	v_cvt_pk_bf16_f32 v199, v92, v93
	v_mul_f32_e32 v200, v91, v91
	v_mul_f32_e32 v201, v93, v93
	v_fmac_f32_e32 v200, v90, v90
	v_fmac_f32_e32 v201, v92, v92
	v_add_f32_e32 v200, v200, v201
	v_add_f32_e32 v224, v224, v200
	v_add_u32_e32 v219, 0x10020, v138
	global_store_dwordx2 v219, v[198:199], s[40:41]
	v_cvt_pk_bf16_f32 v202, v86, v87
	v_cvt_pk_bf16_f32 v203, v88, v89
	v_mul_f32_e32 v204, v87, v87
	v_mul_f32_e32 v205, v89, v89
	v_fmac_f32_e32 v204, v86, v86
	v_fmac_f32_e32 v205, v88, v88
	v_add_f32_e32 v204, v204, v205
	v_add_f32_e32 v224, v224, v204
	v_add_u32_e32 v220, 0x10100, v138
	global_store_dwordx2 v220, v[202:203], s[40:41]
	v_cvt_pk_bf16_f32 v206, v82, v83
	v_cvt_pk_bf16_f32 v207, v84, v85
	v_mul_f32_e32 v208, v83, v83
	v_mul_f32_e32 v209, v85, v85
	v_fmac_f32_e32 v208, v82, v82
	v_fmac_f32_e32 v209, v84, v84
	v_add_f32_e32 v208, v208, v209
	v_add_f32_e32 v224, v224, v208
	v_add_u32_e32 v221, 0x10120, v138
	global_store_dwordx2 v221, v[206:207], s[40:41]
	v_add_u32_e32 v218, 0x48000, v137
	global_load_dwordx2 v[194:195], v218, s[36:37]
	v_add_u32_e32 v219, 0x48020, v137
	global_load_dwordx2 v[198:199], v219, s[36:37]
	v_add_u32_e32 v220, 0x48100, v137
	global_load_dwordx2 v[202:203], v220, s[36:37]
	v_add_u32_e32 v221, 0x48120, v137
	global_load_dwordx2 v[206:207], v221, s[36:37]
	s_waitcnt vmcnt(16)
	v_lshlrev_b32_e32 v158, 16, v157
	v_and_b32_e32 v159, 0xffff0000, v157
	v_and_b32_e32 v157, 0xffff0000, v156
	v_lshlrev_b32_e32 v156, 16, v156
	v_pk_fma_f32 v[78:79], v[78:79], v[140:141], v[156:157]
	v_pk_fma_f32 v[80:81], v[80:81], v[142:143], v[158:159]
	v_lshlrev_b32_e32 v162, 16, v161
	v_and_b32_e32 v163, 0xffff0000, v161
	v_and_b32_e32 v161, 0xffff0000, v160
	v_lshlrev_b32_e32 v160, 16, v160
	v_pk_fma_f32 v[74:75], v[74:75], v[144:145], v[160:161]
	v_pk_fma_f32 v[76:77], v[76:77], v[146:147], v[162:163]
	v_lshlrev_b32_e32 v166, 16, v165
	v_and_b32_e32 v167, 0xffff0000, v165
	v_and_b32_e32 v165, 0xffff0000, v164
	v_lshlrev_b32_e32 v164, 16, v164
	v_pk_fma_f32 v[70:71], v[70:71], v[148:149], v[164:165]
	v_pk_fma_f32 v[72:73], v[72:73], v[150:151], v[166:167]
	v_lshlrev_b32_e32 v170, 16, v169
	v_and_b32_e32 v171, 0xffff0000, v169
	v_and_b32_e32 v169, 0xffff0000, v168
	v_lshlrev_b32_e32 v168, 16, v168
	v_pk_fma_f32 v[66:67], v[66:67], v[152:153], v[168:169]
	v_pk_fma_f32 v[68:69], v[68:69], v[154:155], v[170:171]
	v_cvt_pk_bf16_f32 v156, v78, v79
	v_cvt_pk_bf16_f32 v157, v80, v81
	v_mul_f32_e32 v158, v79, v79
	v_mul_f32_e32 v159, v81, v81
	v_fmac_f32_e32 v158, v78, v78
	v_fmac_f32_e32 v159, v80, v80
	v_add_f32_e32 v158, v158, v159
	v_add_f32_e32 v225, 0, v158
	v_add_u32_e32 v218, 0x18000, v138
	global_store_dwordx2 v218, v[156:157], s[40:41]
	v_cvt_pk_bf16_f32 v160, v74, v75
	v_cvt_pk_bf16_f32 v161, v76, v77
	v_mul_f32_e32 v162, v75, v75
	v_mul_f32_e32 v163, v77, v77
	v_fmac_f32_e32 v162, v74, v74
	v_fmac_f32_e32 v163, v76, v76
	v_add_f32_e32 v162, v162, v163
	v_add_f32_e32 v225, v225, v162
	v_add_u32_e32 v219, 0x18020, v138
	global_store_dwordx2 v219, v[160:161], s[40:41]
	v_cvt_pk_bf16_f32 v164, v70, v71
	v_cvt_pk_bf16_f32 v165, v72, v73
	v_mul_f32_e32 v166, v71, v71
	v_mul_f32_e32 v167, v73, v73
	v_fmac_f32_e32 v166, v70, v70
	v_fmac_f32_e32 v167, v72, v72
	v_add_f32_e32 v166, v166, v167
	v_add_f32_e32 v225, v225, v166
	v_add_u32_e32 v220, 0x18100, v138
	global_store_dwordx2 v220, v[164:165], s[40:41]
	v_cvt_pk_bf16_f32 v168, v66, v67
	v_cvt_pk_bf16_f32 v169, v68, v69
	v_mul_f32_e32 v170, v67, v67
	v_mul_f32_e32 v171, v69, v69
	v_fmac_f32_e32 v170, v66, v66
	v_fmac_f32_e32 v171, v68, v68
	v_add_f32_e32 v170, v170, v171
	v_add_f32_e32 v225, v225, v170
	v_add_u32_e32 v221, 0x18120, v138
	global_store_dwordx2 v221, v[168:169], s[40:41]
	v_add_u32_e32 v218, 0x50000, v137
	global_load_dwordx2 v[156:157], v218, s[36:37]
	v_add_u32_e32 v219, 0x50020, v137
	global_load_dwordx2 v[160:161], v219, s[36:37]
	v_add_u32_e32 v220, 0x50100, v137
	global_load_dwordx2 v[164:165], v220, s[36:37]
	v_add_u32_e32 v221, 0x50120, v137
	global_load_dwordx2 v[168:169], v221, s[36:37]
	s_waitcnt vmcnt(16)
	v_lshlrev_b32_e32 v174, 16, v173
	v_and_b32_e32 v175, 0xffff0000, v173
	v_and_b32_e32 v173, 0xffff0000, v172
	v_lshlrev_b32_e32 v172, 16, v172
	v_pk_fma_f32 v[62:63], v[62:63], v[140:141], v[172:173]
	v_pk_fma_f32 v[64:65], v[64:65], v[142:143], v[174:175]
	v_lshlrev_b32_e32 v184, 16, v183
	v_and_b32_e32 v185, 0xffff0000, v183
	v_and_b32_e32 v183, 0xffff0000, v182
	v_lshlrev_b32_e32 v182, 16, v182
	v_pk_fma_f32 v[58:59], v[58:59], v[144:145], v[182:183]
	v_pk_fma_f32 v[60:61], v[60:61], v[146:147], v[184:185]
	v_lshlrev_b32_e32 v188, 16, v187
	v_and_b32_e32 v189, 0xffff0000, v187
	v_and_b32_e32 v187, 0xffff0000, v186
	v_lshlrev_b32_e32 v186, 16, v186
	v_pk_fma_f32 v[54:55], v[54:55], v[148:149], v[186:187]
	v_pk_fma_f32 v[56:57], v[56:57], v[150:151], v[188:189]
	v_lshlrev_b32_e32 v192, 16, v191
	v_and_b32_e32 v193, 0xffff0000, v191
	v_and_b32_e32 v191, 0xffff0000, v190
	v_lshlrev_b32_e32 v190, 16, v190
	v_pk_fma_f32 v[50:51], v[50:51], v[152:153], v[190:191]
	v_pk_fma_f32 v[52:53], v[52:53], v[154:155], v[192:193]
	v_cvt_pk_bf16_f32 v172, v62, v63
	v_cvt_pk_bf16_f32 v173, v64, v65
	v_mul_f32_e32 v174, v63, v63
	v_mul_f32_e32 v175, v65, v65
	v_fmac_f32_e32 v174, v62, v62
	v_fmac_f32_e32 v175, v64, v64
	v_add_f32_e32 v174, v174, v175
	v_add_f32_e32 v226, 0, v174
	v_add_u32_e32 v218, 0x40000, v138
	global_store_dwordx2 v218, v[172:173], s[40:41]
	v_cvt_pk_bf16_f32 v182, v58, v59
	v_cvt_pk_bf16_f32 v183, v60, v61
	v_mul_f32_e32 v184, v59, v59
	v_mul_f32_e32 v185, v61, v61
	v_fmac_f32_e32 v184, v58, v58
	v_fmac_f32_e32 v185, v60, v60
	v_add_f32_e32 v184, v184, v185
	v_add_f32_e32 v226, v226, v184
	v_add_u32_e32 v219, 0x40020, v138
	global_store_dwordx2 v219, v[182:183], s[40:41]
	v_cvt_pk_bf16_f32 v186, v54, v55
	v_cvt_pk_bf16_f32 v187, v56, v57
	v_mul_f32_e32 v188, v55, v55
	v_mul_f32_e32 v189, v57, v57
	v_fmac_f32_e32 v188, v54, v54
	v_fmac_f32_e32 v189, v56, v56
	v_add_f32_e32 v188, v188, v189
	v_add_f32_e32 v226, v226, v188
	v_add_u32_e32 v220, 0x40100, v138
	global_store_dwordx2 v220, v[186:187], s[40:41]
	v_cvt_pk_bf16_f32 v190, v50, v51
	v_cvt_pk_bf16_f32 v191, v52, v53
	v_mul_f32_e32 v192, v51, v51
	v_mul_f32_e32 v193, v53, v53
	v_fmac_f32_e32 v192, v50, v50
	v_fmac_f32_e32 v193, v52, v52
	v_add_f32_e32 v192, v192, v193
	v_add_f32_e32 v226, v226, v192
	v_add_u32_e32 v221, 0x40120, v138
	global_store_dwordx2 v221, v[190:191], s[40:41]
	v_add_u32_e32 v218, 0x58000, v137
	global_load_dwordx2 v[172:173], v218, s[36:37]
	v_add_u32_e32 v219, 0x58020, v137
	global_load_dwordx2 v[182:183], v219, s[36:37]
	v_add_u32_e32 v220, 0x58100, v137
	global_load_dwordx2 v[186:187], v220, s[36:37]
	v_add_u32_e32 v221, 0x58120, v137
	global_load_dwordx2 v[190:191], v221, s[36:37]
	s_waitcnt vmcnt(16)
	v_lshlrev_b32_e32 v196, 16, v195
	v_and_b32_e32 v197, 0xffff0000, v195
	v_and_b32_e32 v195, 0xffff0000, v194
	v_lshlrev_b32_e32 v194, 16, v194
	v_pk_fma_f32 v[46:47], v[46:47], v[140:141], v[194:195]
	v_pk_fma_f32 v[48:49], v[48:49], v[142:143], v[196:197]
	v_lshlrev_b32_e32 v200, 16, v199
	v_and_b32_e32 v201, 0xffff0000, v199
	v_and_b32_e32 v199, 0xffff0000, v198
	v_lshlrev_b32_e32 v198, 16, v198
	v_pk_fma_f32 v[42:43], v[42:43], v[144:145], v[198:199]
	v_pk_fma_f32 v[44:45], v[44:45], v[146:147], v[200:201]
	v_lshlrev_b32_e32 v204, 16, v203
	v_and_b32_e32 v205, 0xffff0000, v203
	v_and_b32_e32 v203, 0xffff0000, v202
	v_lshlrev_b32_e32 v202, 16, v202
	v_pk_fma_f32 v[38:39], v[38:39], v[148:149], v[202:203]
	v_pk_fma_f32 v[40:41], v[40:41], v[150:151], v[204:205]
	v_lshlrev_b32_e32 v208, 16, v207
	v_and_b32_e32 v209, 0xffff0000, v207
	v_and_b32_e32 v207, 0xffff0000, v206
	v_lshlrev_b32_e32 v206, 16, v206
	v_pk_fma_f32 v[34:35], v[34:35], v[152:153], v[206:207]
	v_pk_fma_f32 v[36:37], v[36:37], v[154:155], v[208:209]
	v_cvt_pk_bf16_f32 v194, v46, v47
	v_cvt_pk_bf16_f32 v195, v48, v49
	v_mul_f32_e32 v196, v47, v47
	v_mul_f32_e32 v197, v49, v49
	v_fmac_f32_e32 v196, v46, v46
	v_fmac_f32_e32 v197, v48, v48
	v_add_f32_e32 v196, v196, v197
	v_add_f32_e32 v216, 0, v196
	v_add_u32_e32 v218, 0x48000, v138
	global_store_dwordx2 v218, v[194:195], s[40:41]
	v_cvt_pk_bf16_f32 v198, v42, v43
	v_cvt_pk_bf16_f32 v199, v44, v45
	v_mul_f32_e32 v200, v43, v43
	v_mul_f32_e32 v201, v45, v45
	v_fmac_f32_e32 v200, v42, v42
	v_fmac_f32_e32 v201, v44, v44
	v_add_f32_e32 v200, v200, v201
	v_add_f32_e32 v216, v216, v200
	v_add_u32_e32 v219, 0x48020, v138
	global_store_dwordx2 v219, v[198:199], s[40:41]
	v_cvt_pk_bf16_f32 v202, v38, v39
	v_cvt_pk_bf16_f32 v203, v40, v41
	v_mul_f32_e32 v204, v39, v39
	v_mul_f32_e32 v205, v41, v41
	v_fmac_f32_e32 v204, v38, v38
	v_fmac_f32_e32 v205, v40, v40
	v_add_f32_e32 v204, v204, v205
	v_add_f32_e32 v216, v216, v204
	v_add_u32_e32 v220, 0x48100, v138
	global_store_dwordx2 v220, v[202:203], s[40:41]
	v_cvt_pk_bf16_f32 v206, v34, v35
	v_cvt_pk_bf16_f32 v207, v36, v37
	v_mul_f32_e32 v208, v35, v35
	v_mul_f32_e32 v209, v37, v37
	v_fmac_f32_e32 v208, v34, v34
	v_fmac_f32_e32 v209, v36, v36
	v_add_f32_e32 v208, v208, v209
	v_add_f32_e32 v216, v216, v208
	v_add_u32_e32 v221, 0x48120, v138
	global_store_dwordx2 v221, v[206:207], s[40:41]
	s_waitcnt vmcnt(12)
	v_lshlrev_b32_e32 v158, 16, v157
	v_and_b32_e32 v159, 0xffff0000, v157
	v_and_b32_e32 v157, 0xffff0000, v156
	v_lshlrev_b32_e32 v156, 16, v156
	v_pk_fma_f32 v[30:31], v[30:31], v[140:141], v[156:157]
	v_pk_fma_f32 v[32:33], v[32:33], v[142:143], v[158:159]
	v_lshlrev_b32_e32 v162, 16, v161
	v_and_b32_e32 v163, 0xffff0000, v161
	v_and_b32_e32 v161, 0xffff0000, v160
	v_lshlrev_b32_e32 v160, 16, v160
	v_pk_fma_f32 v[26:27], v[26:27], v[144:145], v[160:161]
	v_pk_fma_f32 v[28:29], v[28:29], v[146:147], v[162:163]
	v_lshlrev_b32_e32 v166, 16, v165
	v_and_b32_e32 v167, 0xffff0000, v165
	v_and_b32_e32 v165, 0xffff0000, v164
	v_lshlrev_b32_e32 v164, 16, v164
	v_pk_fma_f32 v[22:23], v[22:23], v[148:149], v[164:165]
	v_pk_fma_f32 v[24:25], v[24:25], v[150:151], v[166:167]
	v_lshlrev_b32_e32 v170, 16, v169
	v_and_b32_e32 v171, 0xffff0000, v169
	v_and_b32_e32 v169, 0xffff0000, v168
	v_lshlrev_b32_e32 v168, 16, v168
	v_pk_fma_f32 v[18:19], v[18:19], v[152:153], v[168:169]
	v_pk_fma_f32 v[20:21], v[20:21], v[154:155], v[170:171]
	v_cvt_pk_bf16_f32 v156, v30, v31
	v_cvt_pk_bf16_f32 v157, v32, v33
	v_mul_f32_e32 v158, v31, v31
	v_mul_f32_e32 v159, v33, v33
	v_fmac_f32_e32 v158, v30, v30
	v_fmac_f32_e32 v159, v32, v32
	v_add_f32_e32 v158, v158, v159
	v_add_f32_e32 v217, 0, v158
	v_add_u32_e32 v218, 0x50000, v138
	global_store_dwordx2 v218, v[156:157], s[40:41]
	v_cvt_pk_bf16_f32 v160, v26, v27
	v_cvt_pk_bf16_f32 v161, v28, v29
	v_mul_f32_e32 v162, v27, v27
	v_mul_f32_e32 v163, v29, v29
	v_fmac_f32_e32 v162, v26, v26
	v_fmac_f32_e32 v163, v28, v28
	v_add_f32_e32 v162, v162, v163
	v_add_f32_e32 v217, v217, v162
	v_add_u32_e32 v219, 0x50020, v138
	global_store_dwordx2 v219, v[160:161], s[40:41]
	v_cvt_pk_bf16_f32 v164, v22, v23
	v_cvt_pk_bf16_f32 v165, v24, v25
	v_mul_f32_e32 v166, v23, v23
	v_mul_f32_e32 v167, v25, v25
	v_fmac_f32_e32 v166, v22, v22
	v_fmac_f32_e32 v167, v24, v24
	v_add_f32_e32 v166, v166, v167
	v_add_f32_e32 v217, v217, v166
	v_add_u32_e32 v220, 0x50100, v138
	global_store_dwordx2 v220, v[164:165], s[40:41]
	v_cvt_pk_bf16_f32 v168, v18, v19
	v_cvt_pk_bf16_f32 v169, v20, v21
	v_mul_f32_e32 v170, v19, v19
	v_mul_f32_e32 v171, v21, v21
	v_fmac_f32_e32 v170, v18, v18
	v_fmac_f32_e32 v171, v20, v20
	v_add_f32_e32 v170, v170, v171
	v_add_f32_e32 v217, v217, v170
	v_add_u32_e32 v221, 0x50120, v138
	global_store_dwordx2 v221, v[168:169], s[40:41]
	s_waitcnt vmcnt(8)
	v_lshlrev_b32_e32 v174, 16, v173
	v_and_b32_e32 v175, 0xffff0000, v173
	v_and_b32_e32 v173, 0xffff0000, v172
	v_lshlrev_b32_e32 v172, 16, v172
	v_pk_fma_f32 v[14:15], v[14:15], v[140:141], v[172:173]
	v_pk_fma_f32 v[16:17], v[16:17], v[142:143], v[174:175]
	v_lshlrev_b32_e32 v184, 16, v183
	v_and_b32_e32 v185, 0xffff0000, v183
	v_and_b32_e32 v183, 0xffff0000, v182
	v_lshlrev_b32_e32 v182, 16, v182
	v_pk_fma_f32 v[10:11], v[10:11], v[144:145], v[182:183]
	v_pk_fma_f32 v[12:13], v[12:13], v[146:147], v[184:185]
	v_lshlrev_b32_e32 v188, 16, v187
	v_and_b32_e32 v189, 0xffff0000, v187
	v_and_b32_e32 v187, 0xffff0000, v186
	v_lshlrev_b32_e32 v186, 16, v186
	v_pk_fma_f32 v[6:7], v[6:7], v[148:149], v[186:187]
	v_pk_fma_f32 v[8:9], v[8:9], v[150:151], v[188:189]
	v_lshlrev_b32_e32 v192, 16, v191
	v_and_b32_e32 v193, 0xffff0000, v191
	v_and_b32_e32 v191, 0xffff0000, v190
	v_lshlrev_b32_e32 v190, 16, v190
	v_pk_fma_f32 v[2:3], v[2:3], v[152:153], v[190:191]
	v_pk_fma_f32 v[4:5], v[4:5], v[154:155], v[192:193]
	v_cvt_pk_bf16_f32 v172, v14, v15
	v_cvt_pk_bf16_f32 v173, v16, v17
	v_mul_f32_e32 v174, v15, v15
	v_mul_f32_e32 v175, v17, v17
	v_fmac_f32_e32 v174, v14, v14
	v_fmac_f32_e32 v175, v16, v16
	v_add_f32_e32 v174, v174, v175
	v_add_f32_e32 v212, 0, v174
	v_add_u32_e32 v218, 0x58000, v138
	global_store_dwordx2 v218, v[172:173], s[40:41]
	v_cvt_pk_bf16_f32 v182, v10, v11
	v_cvt_pk_bf16_f32 v183, v12, v13
	v_mul_f32_e32 v184, v11, v11
	v_mul_f32_e32 v185, v13, v13
	v_fmac_f32_e32 v184, v10, v10
	v_fmac_f32_e32 v185, v12, v12
	v_add_f32_e32 v184, v184, v185
	v_add_f32_e32 v212, v212, v184
	v_add_u32_e32 v219, 0x58020, v138
	global_store_dwordx2 v219, v[182:183], s[40:41]
	v_cvt_pk_bf16_f32 v186, v6, v7
	v_cvt_pk_bf16_f32 v187, v8, v9
	v_mul_f32_e32 v188, v7, v7
	v_mul_f32_e32 v189, v9, v9
	v_fmac_f32_e32 v188, v6, v6
	v_fmac_f32_e32 v189, v8, v8
	v_add_f32_e32 v188, v188, v189
	v_add_f32_e32 v212, v212, v188
	v_add_u32_e32 v220, 0x58100, v138
	global_store_dwordx2 v220, v[186:187], s[40:41]
	v_cvt_pk_bf16_f32 v190, v2, v3
	v_cvt_pk_bf16_f32 v191, v4, v5
	v_mul_f32_e32 v192, v3, v3
	v_mul_f32_e32 v193, v5, v5
	v_fmac_f32_e32 v192, v2, v2
	v_fmac_f32_e32 v193, v4, v4
	v_add_f32_e32 v192, v192, v193
	v_add_f32_e32 v212, v212, v192
	v_add_u32_e32 v221, 0x58120, v138
	global_store_dwordx2 v221, v[190:191], s[40:41]
	ds_bpermute_b32 v156, v213, v222
	ds_bpermute_b32 v157, v213, v223
	ds_bpermute_b32 v158, v213, v224
	ds_bpermute_b32 v159, v213, v225
	ds_bpermute_b32 v160, v213, v226
	ds_bpermute_b32 v161, v213, v216
	ds_bpermute_b32 v162, v213, v217
	ds_bpermute_b32 v163, v213, v212
	s_waitcnt lgkmcnt(0)
	v_add_f32_e32 v222, v222, v156
	v_add_f32_e32 v223, v223, v157
	v_add_f32_e32 v224, v224, v158
	v_add_f32_e32 v225, v225, v159
	v_add_f32_e32 v226, v226, v160
	v_add_f32_e32 v216, v216, v161
	v_add_f32_e32 v217, v217, v162
	v_add_f32_e32 v212, v212, v163
	ds_bpermute_b32 v156, v214, v222
	ds_bpermute_b32 v157, v214, v223
	ds_bpermute_b32 v158, v214, v224
	ds_bpermute_b32 v159, v214, v225
	ds_bpermute_b32 v160, v214, v226
	ds_bpermute_b32 v161, v214, v216
	ds_bpermute_b32 v162, v214, v217
	ds_bpermute_b32 v163, v214, v212
	s_waitcnt lgkmcnt(0)
	v_add_f32_e32 v222, v222, v156
	v_add_f32_e32 v223, v223, v157
	v_add_f32_e32 v224, v224, v158
	v_add_f32_e32 v225, v225, v159
	v_add_f32_e32 v226, v226, v160
	v_add_f32_e32 v216, v216, v161
	v_add_f32_e32 v217, v217, v162
	v_add_f32_e32 v212, v212, v163
	v_cmp_gt_u32_e32 vcc, 16, v227
	s_nop 3
	s_and_saveexec_b64 s[0:1], vcc
	ds_write_b32 v139, v222 offset:0
	ds_write_b32 v139, v223 offset:256
	ds_write_b32 v139, v224 offset:512
	ds_write_b32 v139, v225 offset:768
	ds_write_b32 v139, v226 offset:2048
	ds_write_b32 v139, v216 offset:2304
	ds_write_b32 v139, v217 offset:2560
	ds_write_b32 v139, v212 offset:2816
	s_or_b64 exec, exec, s[0:1]
	s_load_dwordx2 s[36:37], s[78:79], 0xf8
	s_load_dwordx2 s[38:39], s[78:79], 0x1d0
	v_lshlrev_b32_e32 v137, 2, v135
	s_lshr_b32 s0, s24, 3
	s_mul_i32 s0, s0, 0xe000
	v_add_u32_e32 v138, s0, v137
	s_waitcnt lgkmcnt(0)
	v_add_u32_e32 v216, 0x0, v137
	global_load_dwordx4 v[156:159], v216, s[36:37] offset:0
	global_load_dwordx4 v[160:163], v216, s[36:37] offset:64
	global_load_dwordx4 v[164:167], v216, s[36:37] offset:512
	global_load_dwordx4 v[168:171], v216, s[36:37] offset:576
	v_mov_b32_e32 v223, v134
	v_mov_b32_e32 v224, v135
	v_mov_b32_e32 v225, v136
	v_readlane_b32 s36, v252, 0
	v_and_b32_e32 v0, 31, v248
	v_readlane_b32 s46, v252, 10
	s_waitcnt vmcnt(0) lgkmcnt(0)
	s_barrier
	v_lshl_or_b32 v136, s7, 5, v0
	v_readlane_b32 s47, v252, 11
	s_add_u32 s4, s46, 0xc0000
	v_add_u32_e32 v132, s14, v136
	s_addc_u32 s5, s47, 0
	v_cmp_gt_u32_e64 s[0:1], 32, v227
	s_waitcnt lgkmcnt(0)
	v_ashrrev_i32_e32 v133, 31, v132
	v_readlane_b32 s37, v252, 1
	v_readlane_b32 s38, v252, 2
	v_readlane_b32 s39, v252, 3
	v_readlane_b32 s40, v252, 4
	v_readlane_b32 s41, v252, 5
	v_readlane_b32 s42, v252, 6
	v_readlane_b32 s43, v252, 7
	v_readlane_b32 s44, v252, 8
	v_readlane_b32 s45, v252, 9
	v_readlane_b32 s48, v252, 12
	v_readlane_b32 s49, v252, 13
	v_readlane_b32 s50, v252, 14
	v_readlane_b32 s51, v252, 15
	s_and_saveexec_b64 s[2:3], s[0:1]
	s_cbranch_execz .LBB0_5282
	v_lshl_add_u32 v0, v136, 4, 0
	ds_read_b128 v[138:141], v0
	s_ashr_i32 s7, s6, 31
	v_lshl_add_u64 v[134:135], v[132:133], 4, s[4:5]
	v_lshl_add_u64 v[134:135], s[6:7], 2, v[134:135]
	s_waitcnt lgkmcnt(0)
	v_mov_b32_e32 v142, v139
	v_mov_b32_e32 v143, v140
	v_mov_b32_e32 v139, v141
	v_pk_add_f32 v[138:139], v[142:143], v[138:139]
	s_nop 0
	v_pk_add_f32 v[138:139], v[138:139], v[138:139] op_sel:[0,1] op_sel_hi:[1,0]
	global_store_dword v[134:135], v138, off sc1

.LBB0_5299:
	s_or_b64 exec, exec, s[2:3]
	s_waitcnt vmcnt(0) lgkmcnt(0)
	s_barrier
	v_lshlrev_b32_e32 v226, 2, v223
	ds_read_b32 v210, v226 offset:4096
	ds_read_b32 v211, v226 offset:4160
	ds_read_b32 v212, v226 offset:4224
	ds_read_b32 v213, v226 offset:4288
	ds_read_b32 v214, v226 offset:4608
	ds_read_b32 v215, v226 offset:4672
	ds_read_b32 v216, v226 offset:4736
	ds_read_b32 v217, v226 offset:4800
	s_load_dwordx2 s[36:37], s[78:79], 0x100
	v_lshlrev_b32_e32 v222, 12, v225
	v_lshl_add_u32 v222, v224, 2, v222
	s_waitcnt lgkmcnt(0)
	v_mul_f32_e32 v140, v126, v210
	v_mul_f32_e32 v141, v127, v210
	v_mul_f32_e32 v142, v128, v210
	v_mul_f32_e32 v143, v129, v210
	v_mul_f32_e32 v140, v140, v156
	v_mul_f32_e32 v141, v141, v157
	v_mul_f32_e32 v142, v142, v158
	v_mul_f32_e32 v143, v143, v159
	v_add_u32_e32 v148, 0x0, v222
	global_store_dwordx4 v148, v[140:143], s[36:37]
	v_mul_f32_e32 v144, v122, v210
	v_mul_f32_e32 v145, v123, v210
	v_mul_f32_e32 v146, v124, v210
	v_mul_f32_e32 v147, v125, v210
	v_mul_f32_e32 v144, v144, v160
	v_mul_f32_e32 v145, v145, v161
	v_mul_f32_e32 v146, v146, v162
	v_mul_f32_e32 v147, v147, v163
	v_add_u32_e32 v149, 0x40, v222
	global_store_dwordx4 v149, v[144:147], s[36:37]
	v_mul_f32_e32 v140, v118, v210
	v_mul_f32_e32 v141, v119, v210
	v_mul_f32_e32 v142, v120, v210
	v_mul_f32_e32 v143, v121, v210
	v_mul_f32_e32 v140, v140, v164
	v_mul_f32_e32 v141, v141, v165
	v_mul_f32_e32 v142, v142, v166
	v_mul_f32_e32 v143, v143, v167
	v_add_u32_e32 v150, 0x200, v222
	global_store_dwordx4 v150, v[140:143], s[36:37]
	v_mul_f32_e32 v144, v114, v210
	v_mul_f32_e32 v145, v115, v210
	v_mul_f32_e32 v146, v116, v210
	v_mul_f32_e32 v147, v117, v210
	v_mul_f32_e32 v144, v144, v168
	v_mul_f32_e32 v145, v145, v169
	v_mul_f32_e32 v146, v146, v170
	v_mul_f32_e32 v147, v147, v171
	v_add_u32_e32 v151, 0x240, v222
	global_store_dwordx4 v151, v[144:147], s[36:37]
	v_mul_f32_e32 v140, v110, v211
	v_mul_f32_e32 v141, v111, v211
	v_mul_f32_e32 v142, v112, v211
	v_mul_f32_e32 v143, v113, v211
	v_mul_f32_e32 v140, v140, v156
	v_mul_f32_e32 v141, v141, v157
	v_mul_f32_e32 v142, v142, v158
	v_mul_f32_e32 v143, v143, v159
	v_add_u32_e32 v148, 0x10000, v222
	global_store_dwordx4 v148, v[140:143], s[36:37]
	v_mul_f32_e32 v144, v106, v211
	v_mul_f32_e32 v145, v107, v211
	v_mul_f32_e32 v146, v108, v211
	v_mul_f32_e32 v147, v109, v211
	v_mul_f32_e32 v144, v144, v160
	v_mul_f32_e32 v145, v145, v161
	v_mul_f32_e32 v146, v146, v162
	v_mul_f32_e32 v147, v147, v163
	v_add_u32_e32 v149, 0x10040, v222
	global_store_dwordx4 v149, v[144:147], s[36:37]
	v_mul_f32_e32 v140, v102, v211
	v_mul_f32_e32 v141, v103, v211
	v_mul_f32_e32 v142, v104, v211
	v_mul_f32_e32 v143, v105, v211
	v_mul_f32_e32 v140, v140, v164
	v_mul_f32_e32 v141, v141, v165
	v_mul_f32_e32 v142, v142, v166
	v_mul_f32_e32 v143, v143, v167
	v_add_u32_e32 v150, 0x10200, v222
	global_store_dwordx4 v150, v[140:143], s[36:37]
	v_mul_f32_e32 v144, v98, v211
	v_mul_f32_e32 v145, v99, v211
	v_mul_f32_e32 v146, v100, v211
	v_mul_f32_e32 v147, v101, v211
	v_mul_f32_e32 v144, v144, v168
	v_mul_f32_e32 v145, v145, v169
	v_mul_f32_e32 v146, v146, v170
	v_mul_f32_e32 v147, v147, v171
	v_add_u32_e32 v151, 0x10240, v222
	global_store_dwordx4 v151, v[144:147], s[36:37]
	v_mul_f32_e32 v140, v94, v212
	v_mul_f32_e32 v141, v95, v212
	v_mul_f32_e32 v142, v96, v212
	v_mul_f32_e32 v143, v97, v212
	v_mul_f32_e32 v140, v140, v156
	v_mul_f32_e32 v141, v141, v157
	v_mul_f32_e32 v142, v142, v158
	v_mul_f32_e32 v143, v143, v159
	v_add_u32_e32 v148, 0x20000, v222
	global_store_dwordx4 v148, v[140:143], s[36:37]
	v_mul_f32_e32 v144, v90, v212
	v_mul_f32_e32 v145, v91, v212
	v_mul_f32_e32 v146, v92, v212
	v_mul_f32_e32 v147, v93, v212
	v_mul_f32_e32 v144, v144, v160
	v_mul_f32_e32 v145, v145, v161
	v_mul_f32_e32 v146, v146, v162
	v_mul_f32_e32 v147, v147, v163
	v_add_u32_e32 v149, 0x20040, v222
	global_store_dwordx4 v149, v[144:147], s[36:37]
	v_mul_f32_e32 v140, v86, v212
	v_mul_f32_e32 v141, v87, v212
	v_mul_f32_e32 v142, v88, v212
	v_mul_f32_e32 v143, v89, v212
	v_mul_f32_e32 v140, v140, v164
	v_mul_f32_e32 v141, v141, v165
	v_mul_f32_e32 v142, v142, v166
	v_mul_f32_e32 v143, v143, v167
	v_add_u32_e32 v150, 0x20200, v222
	global_store_dwordx4 v150, v[140:143], s[36:37]
	v_mul_f32_e32 v144, v82, v212
	v_mul_f32_e32 v145, v83, v212
	v_mul_f32_e32 v146, v84, v212
	v_mul_f32_e32 v147, v85, v212
	v_mul_f32_e32 v144, v144, v168
	v_mul_f32_e32 v145, v145, v169
	v_mul_f32_e32 v146, v146, v170
	v_mul_f32_e32 v147, v147, v171
	v_add_u32_e32 v151, 0x20240, v222
	global_store_dwordx4 v151, v[144:147], s[36:37]
	v_mul_f32_e32 v140, v78, v213
	v_mul_f32_e32 v141, v79, v213
	v_mul_f32_e32 v142, v80, v213
	v_mul_f32_e32 v143, v81, v213
	v_mul_f32_e32 v140, v140, v156
	v_mul_f32_e32 v141, v141, v157
	v_mul_f32_e32 v142, v142, v158
	v_mul_f32_e32 v143, v143, v159
	v_add_u32_e32 v148, 0x30000, v222
	global_store_dwordx4 v148, v[140:143], s[36:37]
	v_mul_f32_e32 v144, v74, v213
	v_mul_f32_e32 v145, v75, v213
	v_mul_f32_e32 v146, v76, v213
	v_mul_f32_e32 v147, v77, v213
	v_mul_f32_e32 v144, v144, v160
	v_mul_f32_e32 v145, v145, v161
	v_mul_f32_e32 v146, v146, v162
	v_mul_f32_e32 v147, v147, v163
	v_add_u32_e32 v149, 0x30040, v222
	global_store_dwordx4 v149, v[144:147], s[36:37]
	v_mul_f32_e32 v140, v70, v213
	v_mul_f32_e32 v141, v71, v213
	v_mul_f32_e32 v142, v72, v213
	v_mul_f32_e32 v143, v73, v213
	v_mul_f32_e32 v140, v140, v164
	v_mul_f32_e32 v141, v141, v165
	v_mul_f32_e32 v142, v142, v166
	v_mul_f32_e32 v143, v143, v167
	v_add_u32_e32 v150, 0x30200, v222
	global_store_dwordx4 v150, v[140:143], s[36:37]
	v_mul_f32_e32 v144, v66, v213
	v_mul_f32_e32 v145, v67, v213
	v_mul_f32_e32 v146, v68, v213
	v_mul_f32_e32 v147, v69, v213
	v_mul_f32_e32 v144, v144, v168
	v_mul_f32_e32 v145, v145, v169
	v_mul_f32_e32 v146, v146, v170
	v_mul_f32_e32 v147, v147, v171
	v_add_u32_e32 v151, 0x30240, v222
	global_store_dwordx4 v151, v[144:147], s[36:37]
	v_mul_f32_e32 v140, v62, v214
	v_mul_f32_e32 v141, v63, v214
	v_mul_f32_e32 v142, v64, v214
	v_mul_f32_e32 v143, v65, v214
	v_mul_f32_e32 v140, v140, v156
	v_mul_f32_e32 v141, v141, v157
	v_mul_f32_e32 v142, v142, v158
	v_mul_f32_e32 v143, v143, v159
	v_add_u32_e32 v148, 0x80000, v222
	global_store_dwordx4 v148, v[140:143], s[36:37]
	v_mul_f32_e32 v144, v58, v214
	v_mul_f32_e32 v145, v59, v214
	v_mul_f32_e32 v146, v60, v214
	v_mul_f32_e32 v147, v61, v214
	v_mul_f32_e32 v144, v144, v160
	v_mul_f32_e32 v145, v145, v161
	v_mul_f32_e32 v146, v146, v162
	v_mul_f32_e32 v147, v147, v163
	v_add_u32_e32 v149, 0x80040, v222
	global_store_dwordx4 v149, v[144:147], s[36:37]
	v_mul_f32_e32 v140, v54, v214
	v_mul_f32_e32 v141, v55, v214
	v_mul_f32_e32 v142, v56, v214
	v_mul_f32_e32 v143, v57, v214
	v_mul_f32_e32 v140, v140, v164
	v_mul_f32_e32 v141, v141, v165
	v_mul_f32_e32 v142, v142, v166
	v_mul_f32_e32 v143, v143, v167
	v_add_u32_e32 v150, 0x80200, v222
	global_store_dwordx4 v150, v[140:143], s[36:37]
	v_mul_f32_e32 v144, v50, v214
	v_mul_f32_e32 v145, v51, v214
	v_mul_f32_e32 v146, v52, v214
	v_mul_f32_e32 v147, v53, v214
	v_mul_f32_e32 v144, v144, v168
	v_mul_f32_e32 v145, v145, v169
	v_mul_f32_e32 v146, v146, v170
	v_mul_f32_e32 v147, v147, v171
	v_add_u32_e32 v151, 0x80240, v222
	global_store_dwordx4 v151, v[144:147], s[36:37]
	v_mul_f32_e32 v140, v46, v215
	v_mul_f32_e32 v141, v47, v215
	v_mul_f32_e32 v142, v48, v215
	v_mul_f32_e32 v143, v49, v215
	v_mul_f32_e32 v140, v140, v156
	v_mul_f32_e32 v141, v141, v157
	v_mul_f32_e32 v142, v142, v158
	v_mul_f32_e32 v143, v143, v159
	v_add_u32_e32 v148, 0x90000, v222
	global_store_dwordx4 v148, v[140:143], s[36:37]
	v_mul_f32_e32 v144, v42, v215
	v_mul_f32_e32 v145, v43, v215
	v_mul_f32_e32 v146, v44, v215
	v_mul_f32_e32 v147, v45, v215
	v_mul_f32_e32 v144, v144, v160
	v_mul_f32_e32 v145, v145, v161
	v_mul_f32_e32 v146, v146, v162
	v_mul_f32_e32 v147, v147, v163
	v_add_u32_e32 v149, 0x90040, v222
	global_store_dwordx4 v149, v[144:147], s[36:37]
	v_mul_f32_e32 v140, v38, v215
	v_mul_f32_e32 v141, v39, v215
	v_mul_f32_e32 v142, v40, v215
	v_mul_f32_e32 v143, v41, v215
	v_mul_f32_e32 v140, v140, v164
	v_mul_f32_e32 v141, v141, v165
	v_mul_f32_e32 v142, v142, v166
	v_mul_f32_e32 v143, v143, v167
	v_add_u32_e32 v150, 0x90200, v222
	global_store_dwordx4 v150, v[140:143], s[36:37]
	v_mul_f32_e32 v144, v34, v215
	v_mul_f32_e32 v145, v35, v215
	v_mul_f32_e32 v146, v36, v215
	v_mul_f32_e32 v147, v37, v215
	v_mul_f32_e32 v144, v144, v168
	v_mul_f32_e32 v145, v145, v169
	v_mul_f32_e32 v146, v146, v170
	v_mul_f32_e32 v147, v147, v171
	v_add_u32_e32 v151, 0x90240, v222
	global_store_dwordx4 v151, v[144:147], s[36:37]
	v_mul_f32_e32 v140, v30, v216
	v_mul_f32_e32 v141, v31, v216
	v_mul_f32_e32 v142, v32, v216
	v_mul_f32_e32 v143, v33, v216
	v_mul_f32_e32 v140, v140, v156
	v_mul_f32_e32 v141, v141, v157
	v_mul_f32_e32 v142, v142, v158
	v_mul_f32_e32 v143, v143, v159
	v_add_u32_e32 v148, 0xa0000, v222
	global_store_dwordx4 v148, v[140:143], s[36:37]
	v_mul_f32_e32 v144, v26, v216
	v_mul_f32_e32 v145, v27, v216
	v_mul_f32_e32 v146, v28, v216
	v_mul_f32_e32 v147, v29, v216
	v_mul_f32_e32 v144, v144, v160
	v_mul_f32_e32 v145, v145, v161
	v_mul_f32_e32 v146, v146, v162
	v_mul_f32_e32 v147, v147, v163
	v_add_u32_e32 v149, 0xa0040, v222
	global_store_dwordx4 v149, v[144:147], s[36:37]
	v_mul_f32_e32 v140, v22, v216
	v_mul_f32_e32 v141, v23, v216
	v_mul_f32_e32 v142, v24, v216
	v_mul_f32_e32 v143, v25, v216
	v_mul_f32_e32 v140, v140, v164
	v_mul_f32_e32 v141, v141, v165
	v_mul_f32_e32 v142, v142, v166
	v_mul_f32_e32 v143, v143, v167
	v_add_u32_e32 v150, 0xa0200, v222
	global_store_dwordx4 v150, v[140:143], s[36:37]
	v_mul_f32_e32 v144, v18, v216
	v_mul_f32_e32 v145, v19, v216
	v_mul_f32_e32 v146, v20, v216
	v_mul_f32_e32 v147, v21, v216
	v_mul_f32_e32 v144, v144, v168
	v_mul_f32_e32 v145, v145, v169
	v_mul_f32_e32 v146, v146, v170
	v_mul_f32_e32 v147, v147, v171
	v_add_u32_e32 v151, 0xa0240, v222
	global_store_dwordx4 v151, v[144:147], s[36:37]
	v_mul_f32_e32 v140, v14, v217
	v_mul_f32_e32 v141, v15, v217
	v_mul_f32_e32 v142, v16, v217
	v_mul_f32_e32 v143, v17, v217
	v_mul_f32_e32 v140, v140, v156
	v_mul_f32_e32 v141, v141, v157
	v_mul_f32_e32 v142, v142, v158
	v_mul_f32_e32 v143, v143, v159
	v_add_u32_e32 v148, 0xb0000, v222
	global_store_dwordx4 v148, v[140:143], s[36:37]
	v_mul_f32_e32 v144, v10, v217
	v_mul_f32_e32 v145, v11, v217
	v_mul_f32_e32 v146, v12, v217
	v_mul_f32_e32 v147, v13, v217
	v_mul_f32_e32 v144, v144, v160
	v_mul_f32_e32 v145, v145, v161
	v_mul_f32_e32 v146, v146, v162
	v_mul_f32_e32 v147, v147, v163
	v_add_u32_e32 v149, 0xb0040, v222
	global_store_dwordx4 v149, v[144:147], s[36:37]
	v_mul_f32_e32 v140, v6, v217
	v_mul_f32_e32 v141, v7, v217
	v_mul_f32_e32 v142, v8, v217
	v_mul_f32_e32 v143, v9, v217
	v_mul_f32_e32 v140, v140, v164
	v_mul_f32_e32 v141, v141, v165
	v_mul_f32_e32 v142, v142, v166
	v_mul_f32_e32 v143, v143, v167
	v_add_u32_e32 v150, 0xb0200, v222
	global_store_dwordx4 v150, v[140:143], s[36:37]
	v_mul_f32_e32 v144, v2, v217
	v_mul_f32_e32 v145, v3, v217
	v_mul_f32_e32 v146, v4, v217
	v_mul_f32_e32 v147, v5, v217
	v_mul_f32_e32 v144, v144, v168
	v_mul_f32_e32 v145, v145, v169
	v_mul_f32_e32 v146, v146, v170
	v_mul_f32_e32 v147, v147, v171
	v_add_u32_e32 v151, 0xb0240, v222
	global_store_dwordx4 v151, v[144:147], s[36:37]
	s_branch .LBB0_5300
